# v41 + the peeled first iteration's fragment reads issued at the unit-loop header (before the next-tile decode)
# baseline (speedup 1.0000x reference)
; #define PG8_STAGE(bufoff, gbase, voff) do { _Pragma("unroll") for (int _i = 0; _i < 2; ++_i) \
;         __builtin_amdgcn_global_load_lds((const unsigned*)((const char*)(gbase) + (voff)[_i]), (PG8_LAS unsigned*)(lds + (bufoff) + ldsw + _i * 8192), 16, 0, 0); } while (0)
; #define PG8_LDA(dst, b, h) do { _Pragma("unroll") for (int m = 0; m < 4; ++m) _Pragma("unroll") for (int k = 0; k < 2; ++k) dst[m][k] = *(const PG8_LAS bf16x8*)(lds + PG8_SA(b, h) + aoff + m * 2048 + k * 1024); } while (0)
; #define PG8_LDB(dst, b, h) do { _Pragma("unroll") for (int n = 0; n < 2; ++n) _Pragma("unroll") for (int k = 0; k < 2; ++k) dst[n][k] = *(const PG8_LAS bf16x8*)(lds + PG8_SB(b, h) + boff + n * 2048 + k * 1024); } while (0)
; #define PG8_WAIT_V(n) asm volatile("s_waitcnt vmcnt(" #n ")" ::: "memory")
; #define PG8_WAIT_L(n) asm volatile("s_waitcnt lgkmcnt(" #n ")" ::: "memory")
; #define PG8_BAR __builtin_amdgcn_s_barrier()
; #define PG8_SCHED __builtin_amdgcn_sched_barrier(0)
; template <class Epi, class Sched, bool ALIGN_EPI = false, bool SP2 = false>
; __device__ __forceinline__ void gemm_phase(PG8_LAS unsigned char* lds, const Gemm g, const Sched& S, const Epi& E) {
;     ...
;     for (;;) {
;         const bool has_next = S.next(ui + 1, nxt);
;         const char* nA = has_next ? (const char*)g.A + (size_t)nxt.pm * tstepA : cA; const char* nB = has_next ? (const char*)g.Bt + (size_t)nxt.pn * tstepB : cB;
;         for (int t = 0; t < nt; t += 2) {
;             const bool last = (t == nt - 2);
;             const char* a1 = cA + (size_t)(t + 1) * kstepA;
;             const char* a2 = last ? nA : cA + (size_t)(t + 2) * kstepA; const char* b2 = last ? nB : cB + (size_t)(t + 2) * kstep;
;             const char* a3 = a2 + kstepA; const char* b3 = b2 + kstep;
;             if (last && has_next) S.a_ready(nxt);
;             if constexpr (SP2) {
;             PG8_LDB(B0, 0, 0); PG8_LDB(B1, 0, 1); PG8_SCHED; PG8_LDA(At, 0, 0); PG8_STAGE(PG8_SA(1, 1), a1 + hstepA, voffA);
;             PG8_WAIT_V(8); PG8_WAIT_L(0); PG8_BAR; PG8_MMA(0, 0, At, B0); PG8_MMA(0, 1, At, B1); PG8_BAR; PG8_SCHED;
;             PG8_LDA(At, 0, 1); PG8_STAGE(PG8_SB(0, 0), b2, voffB); PG8_STAGE(PG8_SB(0, 1), b2 + hstepB, voffB); PG8_STAGE(PG8_SA(0, 0), a2, voffA);
;             PG8_WAIT_V(8); PG8_WAIT_L(0); PG8_BAR; PG8_MMA(1, 0, At, B0); PG8_MMA(1, 1, At, B1); PG8_BAR; PG8_SCHED;
.LBB0_138:
	ds_read_b128 v[150:153], v143
	ds_read_b128 v[154:157], v143 offset:1024
	ds_read_b128 v[158:161], v143 offset:2048
	ds_read_b128 v[162:165], v143 offset:3072
	ds_read_b128 v[166:169], v144
	ds_read_b128 v[170:173], v144 offset:1024
	ds_read_b128 v[174:177], v144 offset:2048
	ds_read_b128 v[178:181], v144 offset:3072
	ds_read_b128 v[182:185], v145
	ds_read_b128 v[190:193], v145 offset:1024
	ds_read_b128 v[194:197], v145 offset:2048
	ds_read_b128 v[198:201], v145 offset:3072
	ds_read_b128 v[202:205], v145 offset:4096
	ds_read_b128 v[206:209], v145 offset:5120
	ds_read_b128 v[210:213], v145 offset:6144
	ds_read_b128 v[214:217], v145 offset:7168
	s_add_i32 s78, s78, 1
	s_mul_i32 s2, s78, s82
	s_mul_hi_u32 s3, s78, s85
	s_add_i32 s3, s3, s2
	s_mul_i32 s2, s78, s85
	s_add_u32 s60, s2, s16
	s_addc_u32 s61, s3, s15
	v_cmp_gt_i64_e32 vcc, s[60:61], v[140:141]
	v_cmp_lt_i64_e64 s[2:3], s[60:61], v[138:139]
	s_cbranch_vccnz .LBB0_140
	s_ashr_i32 s8, s60, 31
	s_lshr_b32 s8, s8, 29
	s_add_i32 s8, s60, s8
	s_ashr_i32 s9, s8, 3
	s_and_b32 s8, s8, -8
	s_sub_i32 s8, s60, s8
	s_cmp_lt_i32 s8, 0
	s_cselect_b32 s33, s17, 0x160
	s_mul_i32 s8, s8, s33
	s_add_i32 s8, s8, s9
	s_mul_hi_i32 s9, s8, 0x2e8ba2e9
	s_lshr_b32 s33, s9, 31
	s_ashr_i32 s9, s9, 4
	s_add_i32 s9, s9, s33
	s_lshl_b32 s33, s9, 2
	s_mulk_i32 s9, 0x58
	s_sub_i32 s8, s8, s9
	s_abs_i32 s9, s8
	s_ashr_i32 s56, s8, 2
	s_and_b32 s8, s8, 3
	s_add_i32 s58, s33, s8
.LBB0_140:
	s_ashr_i32 s59, s58, 31
	s_lshl_b64 s[60:61], s[58:59], 19
	s_add_u32 s60, s12, s60
	s_addc_u32 s61, s13, s61
	s_and_b64 s[62:63], s[2:3], exec
	s_cselect_b32 s59, s61, s71
	s_cselect_b32 s92, s60, s70
	s_ashr_i32 s57, s56, 31
	s_lshl_b64 s[62:63], s[56:57], 19
	s_add_u32 s62, s80, s62
	s_addc_u32 s63, s81, s63
	s_and_b64 s[94:95], s[2:3], exec
	s_cselect_b32 s57, s63, s73
	s_cselect_b32 s93, s62, s72
	s_add_u32 s70, s70, 0x10000
	s_addc_u32 s71, s71, 0
	s_add_u32 s72, s72, 0x10000
	s_addc_u32 s73, s73, 0
	s_mov_b32 s94, -2
	s_cmp_eq_u32 s94, 12
	s_cselect_b32 s97, s59, s71
	s_cselect_b32 s96, s92, s70
	s_cselect_b32 vcc_hi, s57, s73
	s_cselect_b32 vcc_lo, s93, s72
	s_movk_i32 s8, 0xc000
	v_lshl_add_u64 v[186:187], s[70:71], 0, v[128:129]
	s_mov_b32 s9, -1
	v_lshl_add_u64 v[220:221], v[186:187], 0, s[8:9]
	s_movk_i32 s8, 0xe000
	s_add_i32 m0, s18, 0xc000
	s_mov_b32 s9, -1
	global_load_lds_dwordx4 v[220:221], off
	v_lshl_add_u64 v[186:187], v[186:187], 0, s[8:9]
	s_add_i32 m0, s18, 0xe000
	s_nop 0
	global_load_lds_dwordx4 v[186:187], off
	s_waitcnt vmcnt(8)
	s_waitcnt lgkmcnt(0)
	s_barrier
	s_waitcnt lgkmcnt(0)
	v_mfma_f32_16x16x32_bf16 v[116:119], v[150:153], v[182:185], 0
	v_mfma_f32_16x16x32_bf16 v[112:115], v[158:161], v[182:185], 0
	v_mfma_f32_16x16x32_bf16 v[108:111], v[150:153], v[194:197], 0
	v_mfma_f32_16x16x32_bf16 v[100:103], v[158:161], v[194:197], 0
	v_mfma_f32_16x16x32_bf16 v[92:95], v[150:153], v[202:205], 0
	v_mfma_f32_16x16x32_bf16 v[84:87], v[158:161], v[202:205], 0
	v_mfma_f32_16x16x32_bf16 v[76:79], v[150:153], v[210:213], 0
	v_mfma_f32_16x16x32_bf16 v[68:71], v[158:161], v[210:213], 0
	v_mfma_f32_16x16x32_bf16 v[116:119], v[154:157], v[190:193], v[116:119]
	v_mfma_f32_16x16x32_bf16 v[112:115], v[162:165], v[190:193], v[112:115]
	v_mfma_f32_16x16x32_bf16 v[108:111], v[154:157], v[198:201], v[108:111]
	v_mfma_f32_16x16x32_bf16 v[100:103], v[162:165], v[198:201], v[100:103]
	v_mfma_f32_16x16x32_bf16 v[92:95], v[154:157], v[206:209], v[92:95]
	v_mfma_f32_16x16x32_bf16 v[84:87], v[162:165], v[206:209], v[84:87]
	v_mfma_f32_16x16x32_bf16 v[76:79], v[154:157], v[214:217], v[76:79]
	v_mfma_f32_16x16x32_bf16 v[68:71], v[162:165], v[214:217], v[68:71]
	v_mfma_f32_16x16x32_bf16 v[124:127], v[166:169], v[182:185], 0
	v_mfma_f32_16x16x32_bf16 v[120:123], v[174:177], v[182:185], 0
	v_mfma_f32_16x16x32_bf16 v[104:107], v[166:169], v[194:197], 0
	v_mfma_f32_16x16x32_bf16 v[96:99], v[174:177], v[194:197], 0
	v_mfma_f32_16x16x32_bf16 v[88:91], v[166:169], v[202:205], 0
	v_mfma_f32_16x16x32_bf16 v[80:83], v[174:177], v[202:205], 0
	v_mfma_f32_16x16x32_bf16 v[72:75], v[166:169], v[210:213], 0
	v_mfma_f32_16x16x32_bf16 v[64:67], v[174:177], v[210:213], 0
	v_mfma_f32_16x16x32_bf16 v[124:127], v[170:173], v[190:193], v[124:127]
	v_mfma_f32_16x16x32_bf16 v[120:123], v[178:181], v[190:193], v[120:123]
	v_mfma_f32_16x16x32_bf16 v[104:107], v[170:173], v[198:201], v[104:107]
	v_mfma_f32_16x16x32_bf16 v[96:99], v[178:181], v[198:201], v[96:99]
	v_mfma_f32_16x16x32_bf16 v[88:91], v[170:173], v[206:209], v[88:91]
	v_mfma_f32_16x16x32_bf16 v[80:83], v[178:181], v[206:209], v[80:83]
	v_mfma_f32_16x16x32_bf16 v[72:75], v[170:173], v[214:217], v[72:75]
	v_mfma_f32_16x16x32_bf16 v[64:67], v[178:181], v[214:217], v[64:67]
	s_barrier
	s_add_i32 s8, s86, s14
	v_lshl_add_u64 v[186:187], vcc, 0, v[128:129]
	s_mov_b32 m0, s8
	ds_read_b128 v[182:185], v145 offset:16384
	ds_read_b128 v[190:193], v145 offset:17408
	ds_read_b128 v[194:197], v145 offset:18432
	ds_read_b128 v[198:201], v145 offset:19456
	ds_read_b128 v[202:205], v145 offset:20480
	ds_read_b128 v[206:209], v145 offset:21504
	ds_read_b128 v[210:213], v145 offset:22528
	ds_read_b128 v[214:217], v145 offset:23552
	global_load_lds_dwordx4 v[186:187], off
	v_lshl_add_u64 v[220:221], v[186:187], 0, s[4:5]
	s_add_i32 m0, s8, 0x2000
	s_add_i32 s8, s89, s14
	global_load_lds_dwordx4 v[220:221], off
	v_lshl_add_u64 v[220:221], v[186:187], 0, s[6:7]
	s_mov_b32 m0, s8
	s_nop 0
	global_load_lds_dwordx4 v[220:221], off
	v_lshl_add_u64 v[220:221], v[186:187], 0, s[30:31]
	s_add_i32 m0, s8, 0x2000
	s_nop 0
	global_load_lds_dwordx4 v[220:221], off
	v_lshl_add_u64 v[220:221], s[96:97], 0, v[128:129]
	s_mov_b32 m0, s18
	v_lshl_add_u64 v[222:223], v[220:221], 0, s[4:5]
	global_load_lds_dwordx4 v[220:221], off
	s_mov_b32 m0, s19
	s_nop 0
	global_load_lds_dwordx4 v[222:223], off
	s_waitcnt vmcnt(8)
	s_waitcnt lgkmcnt(0)
	s_barrier
; #define PG8_STAGE(bufoff, gbase, voff) do { _Pragma("unroll") for (int _i = 0; _i < 2; ++_i) \
;         __builtin_amdgcn_global_load_lds((const unsigned*)((const char*)(gbase) + (voff)[_i]), (PG8_LAS unsigned*)(lds + (bufoff) + ldsw + _i * 8192), 16, 0, 0); } while (0)
; #define PG8_LDA(dst, b, h) do { _Pragma("unroll") for (int m = 0; m < 4; ++m) _Pragma("unroll") for (int k = 0; k < 2; ++k) dst[m][k] = *(const PG8_LAS bf16x8*)(lds + PG8_SA(b, h) + aoff + m * 2048 + k * 1024); } while (0)
; #define PG8_LDB(dst, b, h) do { _Pragma("unroll") for (int n = 0; n < 2; ++n) _Pragma("unroll") for (int k = 0; k < 2; ++k) dst[n][k] = *(const PG8_LAS bf16x8*)(lds + PG8_SB(b, h) + boff + n * 2048 + k * 1024); } while (0)
; #define PG8_MMA(ai, bj, At, Bt) do { __builtin_amdgcn_s_setprio(1); _Pragma("unroll") for (int m = 0; m < 4; ++m) _Pragma("unroll") for (int n = 0; n < 2; ++n) _Pragma("unroll") for (int k = 0; k < 2; ++k) \
;         acc[ai][bj][m][n] = __builtin_amdgcn_mfma_f32_16x16x32_bf16(Bt[n][k], At[m][k], acc[ai][bj][m][n], 0, 0, 0); __builtin_amdgcn_s_setprio(0); } while (0)
; #define PG8_WAIT_V(n) asm volatile("s_waitcnt vmcnt(" #n ")" ::: "memory")
; #define PG8_WAIT_L(n) asm volatile("s_waitcnt lgkmcnt(" #n ")" ::: "memory")
; #define PG8_BAR __builtin_amdgcn_s_barrier()
; #define PG8_SCHED __builtin_amdgcn_sched_barrier(0)
; template <class Epi, class Sched, bool ALIGN_EPI = false, bool SP2 = false>
; __device__ __forceinline__ void gemm_phase(PG8_LAS unsigned char* lds, const Gemm g, const Sched& S, const Epi& E) {
;     ...
;             PG8_WAIT_V(8); PG8_WAIT_L(0); PG8_BAR; PG8_MMA(1, 0, At, B0); PG8_MMA(1, 1, At, B1); PG8_BAR; PG8_SCHED;
;             PG8_LDB(B0, 1, 0); PG8_LDB(B1, 1, 1); PG8_SCHED; PG8_LDA(At, 1, 0); PG8_STAGE(PG8_SA(0, 1), a2 + hstepA, voffA);
;             PG8_WAIT_V(8); PG8_WAIT_L(0); PG8_BAR; PG8_MMA(0, 0, At, B0); PG8_MMA(0, 1, At, B1); PG8_BAR; PG8_SCHED;
	s_waitcnt lgkmcnt(0)
	v_mfma_f32_16x16x32_bf16 v[60:63], v[150:153], v[182:185], 0
	v_mfma_f32_16x16x32_bf16 v[52:55], v[158:161], v[182:185], 0
	v_mfma_f32_16x16x32_bf16 v[44:47], v[150:153], v[194:197], 0
	v_mfma_f32_16x16x32_bf16 v[36:39], v[158:161], v[194:197], 0
	v_mfma_f32_16x16x32_bf16 v[28:31], v[150:153], v[202:205], 0
	v_mfma_f32_16x16x32_bf16 v[20:23], v[158:161], v[202:205], 0
	v_mfma_f32_16x16x32_bf16 v[12:15], v[150:153], v[210:213], 0
	v_mfma_f32_16x16x32_bf16 v[4:7], v[158:161], v[210:213], 0
	v_mfma_f32_16x16x32_bf16 v[60:63], v[154:157], v[190:193], v[60:63]
	v_mfma_f32_16x16x32_bf16 v[52:55], v[162:165], v[190:193], v[52:55]
	v_mfma_f32_16x16x32_bf16 v[44:47], v[154:157], v[198:201], v[44:47]
	v_mfma_f32_16x16x32_bf16 v[36:39], v[162:165], v[198:201], v[36:39]
	v_mfma_f32_16x16x32_bf16 v[28:31], v[154:157], v[206:209], v[28:31]
	v_mfma_f32_16x16x32_bf16 v[20:23], v[162:165], v[206:209], v[20:23]
	v_mfma_f32_16x16x32_bf16 v[12:15], v[154:157], v[214:217], v[12:15]
	v_mfma_f32_16x16x32_bf16 v[4:7], v[162:165], v[214:217], v[4:7]
	v_mfma_f32_16x16x32_bf16 v[56:59], v[166:169], v[182:185], 0
	v_mfma_f32_16x16x32_bf16 v[48:51], v[174:177], v[182:185], 0
	v_mfma_f32_16x16x32_bf16 v[40:43], v[166:169], v[194:197], 0
	v_mfma_f32_16x16x32_bf16 v[32:35], v[174:177], v[194:197], 0
	v_mfma_f32_16x16x32_bf16 v[24:27], v[166:169], v[202:205], 0
	v_mfma_f32_16x16x32_bf16 v[16:19], v[174:177], v[202:205], 0
	v_mfma_f32_16x16x32_bf16 v[8:11], v[166:169], v[210:213], 0
	v_mfma_f32_16x16x32_bf16 v[0:3], v[174:177], v[210:213], 0
	v_mfma_f32_16x16x32_bf16 v[56:59], v[170:173], v[190:193], v[56:59]
	v_mfma_f32_16x16x32_bf16 v[48:51], v[178:181], v[190:193], v[48:51]
	v_mfma_f32_16x16x32_bf16 v[40:43], v[170:173], v[198:201], v[40:43]
	v_mfma_f32_16x16x32_bf16 v[32:35], v[178:181], v[198:201], v[32:35]
	v_mfma_f32_16x16x32_bf16 v[24:27], v[170:173], v[206:209], v[24:27]
	v_mfma_f32_16x16x32_bf16 v[16:19], v[178:181], v[206:209], v[16:19]
	v_mfma_f32_16x16x32_bf16 v[8:11], v[170:173], v[214:217], v[8:11]
	v_mfma_f32_16x16x32_bf16 v[0:3], v[178:181], v[214:217], v[0:3]
	s_barrier
	ds_read_b128 v[150:153], v146
	ds_read_b128 v[154:157], v146 offset:1024
	ds_read_b128 v[158:161], v146 offset:2048
	ds_read_b128 v[162:165], v146 offset:3072
	ds_read_b128 v[166:169], v147
	ds_read_b128 v[170:173], v147 offset:1024
	ds_read_b128 v[174:177], v147 offset:2048
	ds_read_b128 v[178:181], v147 offset:3072
	s_mov_b32 m0, s74
	v_lshl_add_u64 v[222:223], v[220:221], 0, s[6:7]
	ds_read_b128 v[182:185], v145 offset:32768
	ds_read_b128 v[190:193], v145 offset:33792
	ds_read_b128 v[194:197], v145 offset:34816
	ds_read_b128 v[198:201], v145 offset:35840
	ds_read_b128 v[202:205], v145 offset:36864
	ds_read_b128 v[206:209], v145 offset:37888
	ds_read_b128 v[210:213], v145 offset:38912
	ds_read_b128 v[214:217], v145 offset:39936
	global_load_lds_dwordx4 v[222:223], off
	v_lshl_add_u64 v[222:223], v[220:221], 0, s[30:31]
	s_mov_b32 m0, s75
	s_nop 0
	global_load_lds_dwordx4 v[222:223], off
	s_waitcnt vmcnt(8)
	s_waitcnt lgkmcnt(0)
	s_barrier
	s_waitcnt lgkmcnt(0)
	v_mfma_f32_16x16x32_bf16 v[116:119], v[150:153], v[182:185], v[116:119]
	v_mfma_f32_16x16x32_bf16 v[112:115], v[158:161], v[182:185], v[112:115]
	v_mfma_f32_16x16x32_bf16 v[108:111], v[150:153], v[194:197], v[108:111]
	v_mfma_f32_16x16x32_bf16 v[100:103], v[158:161], v[194:197], v[100:103]
	v_mfma_f32_16x16x32_bf16 v[92:95], v[150:153], v[202:205], v[92:95]
	v_mfma_f32_16x16x32_bf16 v[84:87], v[158:161], v[202:205], v[84:87]
	v_mfma_f32_16x16x32_bf16 v[76:79], v[150:153], v[210:213], v[76:79]
	v_mfma_f32_16x16x32_bf16 v[68:71], v[158:161], v[210:213], v[68:71]
	v_mfma_f32_16x16x32_bf16 v[116:119], v[154:157], v[190:193], v[116:119]
	v_mfma_f32_16x16x32_bf16 v[112:115], v[162:165], v[190:193], v[112:115]
	v_mfma_f32_16x16x32_bf16 v[108:111], v[154:157], v[198:201], v[108:111]
	v_mfma_f32_16x16x32_bf16 v[100:103], v[162:165], v[198:201], v[100:103]
	v_mfma_f32_16x16x32_bf16 v[92:95], v[154:157], v[206:209], v[92:95]
	v_mfma_f32_16x16x32_bf16 v[84:87], v[162:165], v[206:209], v[84:87]
	v_mfma_f32_16x16x32_bf16 v[76:79], v[154:157], v[214:217], v[76:79]
	v_mfma_f32_16x16x32_bf16 v[68:71], v[162:165], v[214:217], v[68:71]
	v_mfma_f32_16x16x32_bf16 v[124:127], v[166:169], v[182:185], v[124:127]
	v_mfma_f32_16x16x32_bf16 v[120:123], v[174:177], v[182:185], v[120:123]
	v_mfma_f32_16x16x32_bf16 v[104:107], v[166:169], v[194:197], v[104:107]
	v_mfma_f32_16x16x32_bf16 v[96:99], v[174:177], v[194:197], v[96:99]
	v_mfma_f32_16x16x32_bf16 v[88:91], v[166:169], v[202:205], v[88:91]
	v_mfma_f32_16x16x32_bf16 v[80:83], v[174:177], v[202:205], v[80:83]
	v_mfma_f32_16x16x32_bf16 v[72:75], v[166:169], v[210:213], v[72:75]
	v_mfma_f32_16x16x32_bf16 v[64:67], v[174:177], v[210:213], v[64:67]
	v_mfma_f32_16x16x32_bf16 v[124:127], v[170:173], v[190:193], v[124:127]
	v_mfma_f32_16x16x32_bf16 v[120:123], v[178:181], v[190:193], v[120:123]
	v_mfma_f32_16x16x32_bf16 v[104:107], v[170:173], v[198:201], v[104:107]
	v_mfma_f32_16x16x32_bf16 v[96:99], v[178:181], v[198:201], v[96:99]
	v_mfma_f32_16x16x32_bf16 v[88:91], v[170:173], v[206:209], v[88:91]
	v_mfma_f32_16x16x32_bf16 v[80:83], v[178:181], v[206:209], v[80:83]
	v_mfma_f32_16x16x32_bf16 v[72:75], v[170:173], v[214:217], v[72:75]
	v_mfma_f32_16x16x32_bf16 v[64:67], v[178:181], v[214:217], v[64:67]
	s_barrier
; #define PG8_STAGE(bufoff, gbase, voff) do { _Pragma("unroll") for (int _i = 0; _i < 2; ++_i) \
;         __builtin_amdgcn_global_load_lds((const unsigned*)((const char*)(gbase) + (voff)[_i]), (PG8_LAS unsigned*)(lds + (bufoff) + ldsw + _i * 8192), 16, 0, 0); } while (0)
; #define PG8_LDA(dst, b, h) do { _Pragma("unroll") for (int m = 0; m < 4; ++m) _Pragma("unroll") for (int k = 0; k < 2; ++k) dst[m][k] = *(const PG8_LAS bf16x8*)(lds + PG8_SA(b, h) + aoff + m * 2048 + k * 1024); } while (0)
; #define PG8_MMA(ai, bj, At, Bt) do { __builtin_amdgcn_s_setprio(1); _Pragma("unroll") for (int m = 0; m < 4; ++m) _Pragma("unroll") for (int n = 0; n < 2; ++n) _Pragma("unroll") for (int k = 0; k < 2; ++k) \
;         acc[ai][bj][m][n] = __builtin_amdgcn_mfma_f32_16x16x32_bf16(Bt[n][k], At[m][k], acc[ai][bj][m][n], 0, 0, 0); __builtin_amdgcn_s_setprio(0); } while (0)
; #define PG8_WAIT_V(n) asm volatile("s_waitcnt vmcnt(" #n ")" ::: "memory")
; #define PG8_WAIT_L(n) asm volatile("s_waitcnt lgkmcnt(" #n ")" ::: "memory")
; #define PG8_BAR __builtin_amdgcn_s_barrier()
; #define PG8_SCHED __builtin_amdgcn_sched_barrier(0)
; template <class Epi, class Sched, bool ALIGN_EPI = false, bool SP2 = false>
; __device__ __forceinline__ void gemm_phase(PG8_LAS unsigned char* lds, const Gemm g, const Sched& S, const Epi& E) {
;     ...
;         for (int t = 0; t < nt; t += 2) {
;     ...
;             PG8_WAIT_V(8); PG8_WAIT_L(0); PG8_BAR; PG8_MMA(0, 0, At, B0); PG8_MMA(0, 1, At, B1); PG8_BAR; PG8_SCHED;
;             PG8_LDA(At, 1, 1); PG8_STAGE(PG8_SB(1, 0), b3, voffB); PG8_STAGE(PG8_SB(1, 1), b3 + hstepB, voffB); PG8_STAGE(PG8_SA(1, 0), a3, voffA);
;             PG8_WAIT_V(8); PG8_WAIT_L(0); PG8_BAR; PG8_MMA(1, 0, At, B0); PG8_MMA(1, 1, At, B1); PG8_BAR; PG8_SCHED;
	s_add_i32 s8, s90, s14
	v_lshl_add_u64 v[222:223], v[186:187], 0, s[34:35]
	s_mov_b32 m0, s8
	ds_read_b128 v[182:185], v145 offset:49152
	ds_read_b128 v[190:193], v145 offset:50176
	ds_read_b128 v[194:197], v145 offset:51200
	ds_read_b128 v[198:201], v145 offset:52224
	ds_read_b128 v[202:205], v145 offset:53248
	ds_read_b128 v[206:209], v145 offset:54272
	ds_read_b128 v[210:213], v145 offset:55296
	ds_read_b128 v[214:217], v145 offset:56320
	global_load_lds_dwordx4 v[222:223], off
	v_lshl_add_u64 v[222:223], v[186:187], 0, s[36:37]
	s_add_i32 m0, s8, 0x2000
	s_add_i32 s8, s91, s14
	global_load_lds_dwordx4 v[222:223], off
	v_lshl_add_u64 v[222:223], v[186:187], 0, s[38:39]
	s_mov_b32 m0, s8
	v_lshl_add_u64 v[186:187], v[186:187], 0, s[40:41]
	global_load_lds_dwordx4 v[222:223], off
	s_add_i32 m0, s8, 0x2000
	s_nop 0
	global_load_lds_dwordx4 v[186:187], off
	v_lshl_add_u64 v[186:187], v[220:221], 0, s[34:35]
	s_mov_b32 m0, s76
	s_nop 0
	global_load_lds_dwordx4 v[186:187], off
	v_lshl_add_u64 v[186:187], v[220:221], 0, s[36:37]
	s_mov_b32 m0, s77
	s_nop 0
	global_load_lds_dwordx4 v[186:187], off
	s_waitcnt vmcnt(8)
	s_waitcnt lgkmcnt(0)
	s_barrier
	s_waitcnt lgkmcnt(0)
	v_mfma_f32_16x16x32_bf16 v[60:63], v[150:153], v[182:185], v[60:63]
	v_mfma_f32_16x16x32_bf16 v[52:55], v[158:161], v[182:185], v[52:55]
	v_mfma_f32_16x16x32_bf16 v[44:47], v[150:153], v[194:197], v[44:47]
	v_mfma_f32_16x16x32_bf16 v[36:39], v[158:161], v[194:197], v[36:39]
	v_mfma_f32_16x16x32_bf16 v[28:31], v[150:153], v[202:205], v[28:31]
	v_mfma_f32_16x16x32_bf16 v[20:23], v[158:161], v[202:205], v[20:23]
	v_mfma_f32_16x16x32_bf16 v[12:15], v[150:153], v[210:213], v[12:15]
	v_mfma_f32_16x16x32_bf16 v[4:7], v[158:161], v[210:213], v[4:7]
	v_mfma_f32_16x16x32_bf16 v[60:63], v[154:157], v[190:193], v[60:63]
	v_mfma_f32_16x16x32_bf16 v[52:55], v[162:165], v[190:193], v[52:55]
	v_mfma_f32_16x16x32_bf16 v[44:47], v[154:157], v[198:201], v[44:47]
	v_mfma_f32_16x16x32_bf16 v[36:39], v[162:165], v[198:201], v[36:39]
	v_mfma_f32_16x16x32_bf16 v[28:31], v[154:157], v[206:209], v[28:31]
	v_mfma_f32_16x16x32_bf16 v[20:23], v[162:165], v[206:209], v[20:23]
	v_mfma_f32_16x16x32_bf16 v[12:15], v[154:157], v[214:217], v[12:15]
	v_mfma_f32_16x16x32_bf16 v[4:7], v[162:165], v[214:217], v[4:7]
	v_mfma_f32_16x16x32_bf16 v[56:59], v[166:169], v[182:185], v[56:59]
	v_mfma_f32_16x16x32_bf16 v[48:51], v[174:177], v[182:185], v[48:51]
	v_mfma_f32_16x16x32_bf16 v[40:43], v[166:169], v[194:197], v[40:43]
	v_mfma_f32_16x16x32_bf16 v[32:35], v[174:177], v[194:197], v[32:35]
	v_mfma_f32_16x16x32_bf16 v[24:27], v[166:169], v[202:205], v[24:27]
	v_mfma_f32_16x16x32_bf16 v[16:19], v[174:177], v[202:205], v[16:19]
	v_mfma_f32_16x16x32_bf16 v[8:11], v[166:169], v[210:213], v[8:11]
	v_mfma_f32_16x16x32_bf16 v[0:3], v[174:177], v[210:213], v[0:3]
	v_mfma_f32_16x16x32_bf16 v[56:59], v[170:173], v[190:193], v[56:59]
	v_mfma_f32_16x16x32_bf16 v[48:51], v[178:181], v[190:193], v[48:51]
	v_mfma_f32_16x16x32_bf16 v[40:43], v[170:173], v[198:201], v[40:43]
	v_mfma_f32_16x16x32_bf16 v[32:35], v[178:181], v[198:201], v[32:35]
	v_mfma_f32_16x16x32_bf16 v[24:27], v[170:173], v[206:209], v[24:27]
	v_mfma_f32_16x16x32_bf16 v[16:19], v[178:181], v[206:209], v[16:19]
	v_mfma_f32_16x16x32_bf16 v[8:11], v[170:173], v[214:217], v[8:11]
	v_mfma_f32_16x16x32_bf16 v[0:3], v[178:181], v[214:217], v[0:3]
	s_barrier
	s_add_i32 s94, s94, 2
	s_add_u32 s70, s70, 0x10000
	s_addc_u32 s71, s71, 0
	s_add_u32 s72, s72, 0x10000
	s_addc_u32 s73, s73, 0
	s_cmp_gt_u32 s94, 13

; #define PG8_STAGE(bufoff, gbase, voff) do { _Pragma("unroll") for (int _i = 0; _i < 2; ++_i) \
;         __builtin_amdgcn_global_load_lds((const unsigned*)((const char*)(gbase) + (voff)[_i]), (PG8_LAS unsigned*)(lds + (bufoff) + ldsw + _i * 8192), 16, 0, 0); } while (0)
; #define PG8_LDA(dst, b, h) do { _Pragma("unroll") for (int m = 0; m < 4; ++m) _Pragma("unroll") for (int k = 0; k < 2; ++k) dst[m][k] = *(const PG8_LAS bf16x8*)(lds + PG8_SA(b, h) + aoff + m * 2048 + k * 1024); } while (0)
; #define PG8_LDB(dst, b, h) do { _Pragma("unroll") for (int n = 0; n < 2; ++n) _Pragma("unroll") for (int k = 0; k < 2; ++k) dst[n][k] = *(const PG8_LAS bf16x8*)(lds + PG8_SB(b, h) + boff + n * 2048 + k * 1024); } while (0)
; #define PG8_SCHED __builtin_amdgcn_sched_barrier(0)
; template <class Epi, class Sched, bool ALIGN_EPI = false, bool SP2 = false>
; __device__ __forceinline__ void gemm_phase(PG8_LAS unsigned char* lds, const Gemm g, const Sched& S, const Epi& E) {
;     ...
;     for (;;) {
;         const bool has_next = S.next(ui + 1, nxt);
;         const char* nA = has_next ? (const char*)g.A + (size_t)nxt.pm * tstepA : cA; const char* nB = has_next ? (const char*)g.Bt + (size_t)nxt.pn * tstepB : cB;
;         for (int t = 0; t < nt; t += 2) {
;             const bool last = (t == nt - 2);
;             const char* a1 = cA + (size_t)(t + 1) * kstepA;
;             const char* a2 = last ? nA : cA + (size_t)(t + 2) * kstepA; const char* b2 = last ? nB : cB + (size_t)(t + 2) * kstep;
;             const char* a3 = a2 + kstepA; const char* b3 = b2 + kstep;
;             if (last && has_next) S.a_ready(nxt);
;             if constexpr (SP2) {
;             PG8_LDB(B0, 0, 0); PG8_LDB(B1, 0, 1); PG8_SCHED; PG8_LDA(At, 0, 0); PG8_STAGE(PG8_SA(1, 1), a1 + hstepA, voffA);
.LBB0_215:
	ds_read_b128 v[112:115], v210
	ds_read_b128 v[124:127], v210 offset:1024
	ds_read_b128 v[136:139], v210 offset:2048
	ds_read_b128 v[140:143], v210 offset:3072
	ds_read_b128 v[144:147], v211
	ds_read_b128 v[148:151], v211 offset:1024
	ds_read_b128 v[152:155], v211 offset:2048
	ds_read_b128 v[156:159], v211 offset:3072
	ds_read_b128 v[160:163], v212
	ds_read_b128 v[164:167], v212 offset:1024
	ds_read_b128 v[168:171], v212 offset:2048
	ds_read_b128 v[172:175], v212 offset:3072
	ds_read_b128 v[176:179], v212 offset:4096
	ds_read_b128 v[180:183], v212 offset:5120
	ds_read_b128 v[220:223], v212 offset:6144
	ds_read_b128 v[224:227], v212 offset:7168
	s_add_i32 s80, s80, 1
	s_mul_i32 s0, s80, s82
	s_mul_hi_u32 s1, s80, s85
	s_add_i32 s1, s1, s0
	s_mul_i32 s0, s80, s85
	s_add_u32 s4, s0, s16
	s_addc_u32 s5, s1, s86
	v_cmp_gt_i64_e32 vcc, s[4:5], v[206:207]
	v_cmp_lt_i64_e64 s[0:1], s[4:5], v[204:205]
	s_cbranch_vccnz .LBB0_221
	s_ashr_i32 s5, s4, 31
	s_lshr_b32 s5, s5, 29
	s_add_i32 s62, s4, s5
	s_and_b32 s5, s62, -8
	s_sub_i32 s63, s4, s5
	s_cmp_gt_i32 s63, -1
	s_mov_b64 s[4:5], -1
	s_cbranch_scc0 .LBB0_218
	s_lshl_b32 s73, s63, 6
	s_mov_b64 s[4:5], 0

; #define PG8_STAGE(bufoff, gbase, voff) do { _Pragma("unroll") for (int _i = 0; _i < 2; ++_i) \
;         __builtin_amdgcn_global_load_lds((const unsigned*)((const char*)(gbase) + (voff)[_i]), (PG8_LAS unsigned*)(lds + (bufoff) + ldsw + _i * 8192), 16, 0, 0); } while (0)
; #define PG8_LDA(dst, b, h) do { _Pragma("unroll") for (int m = 0; m < 4; ++m) _Pragma("unroll") for (int k = 0; k < 2; ++k) dst[m][k] = *(const PG8_LAS bf16x8*)(lds + PG8_SA(b, h) + aoff + m * 2048 + k * 1024); } while (0)
; #define PG8_LDB(dst, b, h) do { _Pragma("unroll") for (int n = 0; n < 2; ++n) _Pragma("unroll") for (int k = 0; k < 2; ++k) dst[n][k] = *(const PG8_LAS bf16x8*)(lds + PG8_SB(b, h) + boff + n * 2048 + k * 1024); } while (0)
; #define PG8_MMA(ai, bj, At, Bt) do { __builtin_amdgcn_s_setprio(1); _Pragma("unroll") for (int m = 0; m < 4; ++m) _Pragma("unroll") for (int n = 0; n < 2; ++n) _Pragma("unroll") for (int k = 0; k < 2; ++k) \
;         acc[ai][bj][m][n] = __builtin_amdgcn_mfma_f32_16x16x32_bf16(Bt[n][k], At[m][k], acc[ai][bj][m][n], 0, 0, 0); __builtin_amdgcn_s_setprio(0); } while (0)
; #define PG8_WAIT_V(n) asm volatile("s_waitcnt vmcnt(" #n ")" ::: "memory")
; #define PG8_WAIT_L(n) asm volatile("s_waitcnt lgkmcnt(" #n ")" ::: "memory")
; template <class Epi, class Sched, bool ALIGN_EPI = false, bool SP2 = false>
; __device__ __forceinline__ void gemm_phase(PG8_LAS unsigned char* lds, const Gemm g, const Sched& S, const Epi& E) {
;     ...
;             const bool last = (t == nt - 2);
;             const char* a1 = cA + (size_t)(t + 1) * kstepA;
;             const char* a2 = last ? nA : cA + (size_t)(t + 2) * kstepA; const char* b2 = last ? nB : cB + (size_t)(t + 2) * kstep;
;             const char* a3 = a2 + kstepA; const char* b3 = b2 + kstep;
;             if (last && has_next) S.a_ready(nxt);
;             if constexpr (SP2) {
;             PG8_LDB(B0, 0, 0); PG8_LDB(B1, 0, 1); PG8_SCHED; PG8_LDA(At, 0, 0); PG8_STAGE(PG8_SA(1, 1), a1 + hstepA, voffA);
;             PG8_WAIT_V(8); PG8_WAIT_L(0); PG8_BAR; PG8_MMA(0, 0, At, B0); PG8_MMA(0, 1, At, B1); PG8_BAR; PG8_SCHED;
;             PG8_LDA(At, 0, 1); PG8_STAGE(PG8_SB(0, 0), b2, voffB); PG8_STAGE(PG8_SB(0, 1), b2 + hstepB, voffB); PG8_STAGE(PG8_SA(0, 0), a2, voffA);
;             PG8_WAIT_V(8); PG8_WAIT_L(0); PG8_BAR; PG8_MMA(1, 0, At, B0); PG8_MMA(1, 1, At, B1); PG8_BAR; PG8_SCHED;
.LBB0_225:
	s_add_u32 s68, s68, 0x10000
	s_addc_u32 s69, s69, 0
	s_add_u32 s70, s70, 0x10000
	s_addc_u32 s71, s71, 0
	s_mov_b32 s73, -2
	s_waitcnt lgkmcnt(0)
	s_cmp_eq_u32 s73, 40
	s_cselect_b32 s9, s1, s69
	s_cselect_b32 s8, s0, s68
	s_cselect_b32 s75, s63, s71
	s_cselect_b32 s74, s62, s70
	v_lshl_add_u64 v[208:209], s[68:69], 0, v[184:185]
	v_lshl_add_u64 v[216:217], v[208:209], 0, s[96:97]
	s_add_i32 m0, s15, 0xc000
	global_load_lds_dwordx4 v[216:217], off
	v_lshl_add_u64 v[208:209], v[208:209], 0, s[60:61]
	s_add_i32 m0, s15, 0xe000
	s_nop 0
	global_load_lds_dwordx4 v[208:209], off
	s_waitcnt vmcnt(8)
	s_waitcnt lgkmcnt(0)
	s_barrier
	s_waitcnt lgkmcnt(0)
	v_mfma_f32_16x16x32_bf16 v[132:135], v[112:115], v[160:163], 0
	v_mfma_f32_16x16x32_bf16 v[128:131], v[136:139], v[160:163], 0
	v_mfma_f32_16x16x32_bf16 v[108:111], v[112:115], v[168:171], 0
	v_mfma_f32_16x16x32_bf16 v[104:107], v[136:139], v[168:171], 0
	v_mfma_f32_16x16x32_bf16 v[92:95], v[112:115], v[176:179], 0
	v_mfma_f32_16x16x32_bf16 v[88:91], v[136:139], v[176:179], 0
	v_mfma_f32_16x16x32_bf16 v[76:79], v[112:115], v[220:223], 0
	v_mfma_f32_16x16x32_bf16 v[72:75], v[136:139], v[220:223], 0
	v_mfma_f32_16x16x32_bf16 v[132:135], v[124:127], v[164:167], v[132:135]
	v_mfma_f32_16x16x32_bf16 v[128:131], v[140:143], v[164:167], v[128:131]
	v_mfma_f32_16x16x32_bf16 v[108:111], v[124:127], v[172:175], v[108:111]
	v_mfma_f32_16x16x32_bf16 v[104:107], v[140:143], v[172:175], v[104:107]
	v_mfma_f32_16x16x32_bf16 v[92:95], v[124:127], v[180:183], v[92:95]
	v_mfma_f32_16x16x32_bf16 v[88:91], v[140:143], v[180:183], v[88:91]
	v_mfma_f32_16x16x32_bf16 v[76:79], v[124:127], v[224:227], v[76:79]
	v_mfma_f32_16x16x32_bf16 v[72:75], v[140:143], v[224:227], v[72:75]
	v_mfma_f32_16x16x32_bf16 v[120:123], v[144:147], v[160:163], 0
	v_mfma_f32_16x16x32_bf16 v[116:119], v[152:155], v[160:163], 0
	v_mfma_f32_16x16x32_bf16 v[100:103], v[144:147], v[168:171], 0
	v_mfma_f32_16x16x32_bf16 v[96:99], v[152:155], v[168:171], 0
	v_mfma_f32_16x16x32_bf16 v[84:87], v[144:147], v[176:179], 0
	v_mfma_f32_16x16x32_bf16 v[80:83], v[152:155], v[176:179], 0
	v_mfma_f32_16x16x32_bf16 v[68:71], v[144:147], v[220:223], 0
	v_mfma_f32_16x16x32_bf16 v[64:67], v[152:155], v[220:223], 0
	v_mfma_f32_16x16x32_bf16 v[120:123], v[148:151], v[164:167], v[120:123]
	v_mfma_f32_16x16x32_bf16 v[116:119], v[156:159], v[164:167], v[116:119]
	v_mfma_f32_16x16x32_bf16 v[100:103], v[148:151], v[172:175], v[100:103]
	v_mfma_f32_16x16x32_bf16 v[96:99], v[156:159], v[172:175], v[96:99]
	v_mfma_f32_16x16x32_bf16 v[84:87], v[148:151], v[180:183], v[84:87]
	v_mfma_f32_16x16x32_bf16 v[80:83], v[156:159], v[180:183], v[80:83]
	v_mfma_f32_16x16x32_bf16 v[68:71], v[148:151], v[224:227], v[68:71]
	v_mfma_f32_16x16x32_bf16 v[64:67], v[156:159], v[224:227], v[64:67]
	s_barrier
	s_add_i32 s33, s89, s14
	v_lshl_add_u64 v[208:209], s[74:75], 0, v[184:185]
	s_mov_b32 m0, s33
	ds_read_b128 v[160:163], v212 offset:16384
	ds_read_b128 v[164:167], v212 offset:17408
	ds_read_b128 v[168:171], v212 offset:18432
	ds_read_b128 v[172:175], v212 offset:19456
	ds_read_b128 v[176:179], v212 offset:20480
	ds_read_b128 v[180:183], v212 offset:21504
	ds_read_b128 v[220:223], v212 offset:22528
	ds_read_b128 v[224:227], v212 offset:23552
	global_load_lds_dwordx4 v[208:209], off
	v_lshl_add_u64 v[216:217], v[208:209], 0, s[30:31]
	s_add_i32 m0, s33, 0x2000
	s_add_i32 s33, s90, s14
	global_load_lds_dwordx4 v[216:217], off
	v_lshl_add_u64 v[216:217], v[208:209], 0, s[34:35]
	s_mov_b32 m0, s33
	s_nop 0
	global_load_lds_dwordx4 v[216:217], off
	v_lshl_add_u64 v[216:217], v[208:209], 0, s[36:37]
	s_add_i32 m0, s33, 0x2000
	s_nop 0
	global_load_lds_dwordx4 v[216:217], off
	v_lshl_add_u64 v[216:217], s[8:9], 0, v[184:185]
	s_mov_b32 m0, s15
	v_lshl_add_u64 v[228:229], v[216:217], 0, s[30:31]
	global_load_lds_dwordx4 v[216:217], off
	s_mov_b32 m0, s17
	s_nop 0
	global_load_lds_dwordx4 v[228:229], off
	s_waitcnt vmcnt(8)
	s_waitcnt lgkmcnt(0)
	s_barrier
	s_waitcnt lgkmcnt(0)
	v_mfma_f32_16x16x32_bf16 v[60:63], v[112:115], v[160:163], 0
	v_mfma_f32_16x16x32_bf16 v[56:59], v[136:139], v[160:163], 0
	v_mfma_f32_16x16x32_bf16 v[44:47], v[112:115], v[168:171], 0
	v_mfma_f32_16x16x32_bf16 v[40:43], v[136:139], v[168:171], 0
	v_mfma_f32_16x16x32_bf16 v[28:31], v[112:115], v[176:179], 0
	v_mfma_f32_16x16x32_bf16 v[24:27], v[136:139], v[176:179], 0
	v_mfma_f32_16x16x32_bf16 v[12:15], v[112:115], v[220:223], 0
	v_mfma_f32_16x16x32_bf16 v[8:11], v[136:139], v[220:223], 0
	v_mfma_f32_16x16x32_bf16 v[60:63], v[124:127], v[164:167], v[60:63]
	v_mfma_f32_16x16x32_bf16 v[56:59], v[140:143], v[164:167], v[56:59]
	v_mfma_f32_16x16x32_bf16 v[44:47], v[124:127], v[172:175], v[44:47]
	v_mfma_f32_16x16x32_bf16 v[40:43], v[140:143], v[172:175], v[40:43]
	v_mfma_f32_16x16x32_bf16 v[28:31], v[124:127], v[180:183], v[28:31]
	v_mfma_f32_16x16x32_bf16 v[24:27], v[140:143], v[180:183], v[24:27]
	v_mfma_f32_16x16x32_bf16 v[12:15], v[124:127], v[224:227], v[12:15]
	v_mfma_f32_16x16x32_bf16 v[8:11], v[140:143], v[224:227], v[8:11]
	v_mfma_f32_16x16x32_bf16 v[52:55], v[144:147], v[160:163], 0
	v_mfma_f32_16x16x32_bf16 v[48:51], v[152:155], v[160:163], 0
	v_mfma_f32_16x16x32_bf16 v[36:39], v[144:147], v[168:171], 0
	v_mfma_f32_16x16x32_bf16 v[32:35], v[152:155], v[168:171], 0
	v_mfma_f32_16x16x32_bf16 v[20:23], v[144:147], v[176:179], 0
	v_mfma_f32_16x16x32_bf16 v[16:19], v[152:155], v[176:179], 0
	v_mfma_f32_16x16x32_bf16 v[4:7], v[144:147], v[220:223], 0
	v_mfma_f32_16x16x32_bf16 v[0:3], v[152:155], v[220:223], 0
	v_mfma_f32_16x16x32_bf16 v[52:55], v[148:151], v[164:167], v[52:55]
	v_mfma_f32_16x16x32_bf16 v[48:51], v[156:159], v[164:167], v[48:51]
	v_mfma_f32_16x16x32_bf16 v[36:39], v[148:151], v[172:175], v[36:39]
	v_mfma_f32_16x16x32_bf16 v[32:35], v[156:159], v[172:175], v[32:35]
	v_mfma_f32_16x16x32_bf16 v[20:23], v[148:151], v[180:183], v[20:23]
	v_mfma_f32_16x16x32_bf16 v[16:19], v[156:159], v[180:183], v[16:19]
	v_mfma_f32_16x16x32_bf16 v[4:7], v[148:151], v[224:227], v[4:7]
	v_mfma_f32_16x16x32_bf16 v[0:3], v[156:159], v[224:227], v[0:3]
	s_barrier
; #define PG8_STAGE(bufoff, gbase, voff) do { _Pragma("unroll") for (int _i = 0; _i < 2; ++_i) \
;         __builtin_amdgcn_global_load_lds((const unsigned*)((const char*)(gbase) + (voff)[_i]), (PG8_LAS unsigned*)(lds + (bufoff) + ldsw + _i * 8192), 16, 0, 0); } while (0)
; #define PG8_LDA(dst, b, h) do { _Pragma("unroll") for (int m = 0; m < 4; ++m) _Pragma("unroll") for (int k = 0; k < 2; ++k) dst[m][k] = *(const PG8_LAS bf16x8*)(lds + PG8_SA(b, h) + aoff + m * 2048 + k * 1024); } while (0)
; #define PG8_LDB(dst, b, h) do { _Pragma("unroll") for (int n = 0; n < 2; ++n) _Pragma("unroll") for (int k = 0; k < 2; ++k) dst[n][k] = *(const PG8_LAS bf16x8*)(lds + PG8_SB(b, h) + boff + n * 2048 + k * 1024); } while (0)
; #define PG8_MMA(ai, bj, At, Bt) do { __builtin_amdgcn_s_setprio(1); _Pragma("unroll") for (int m = 0; m < 4; ++m) _Pragma("unroll") for (int n = 0; n < 2; ++n) _Pragma("unroll") for (int k = 0; k < 2; ++k) \
;         acc[ai][bj][m][n] = __builtin_amdgcn_mfma_f32_16x16x32_bf16(Bt[n][k], At[m][k], acc[ai][bj][m][n], 0, 0, 0); __builtin_amdgcn_s_setprio(0); } while (0)
; #define PG8_WAIT_V(n) asm volatile("s_waitcnt vmcnt(" #n ")" ::: "memory")
; #define PG8_WAIT_L(n) asm volatile("s_waitcnt lgkmcnt(" #n ")" ::: "memory")
; #define PG8_BAR __builtin_amdgcn_s_barrier()
; #define PG8_SCHED __builtin_amdgcn_sched_barrier(0)
; template <class Epi, class Sched, bool ALIGN_EPI = false, bool SP2 = false>
; __device__ __forceinline__ void gemm_phase(PG8_LAS unsigned char* lds, const Gemm g, const Sched& S, const Epi& E) {
;     ...
;             PG8_LDB(B0, 1, 0); PG8_LDB(B1, 1, 1); PG8_SCHED; PG8_LDA(At, 1, 0); PG8_STAGE(PG8_SA(0, 1), a2 + hstepA, voffA);
;             PG8_WAIT_V(8); PG8_WAIT_L(0); PG8_BAR; PG8_MMA(0, 0, At, B0); PG8_MMA(0, 1, At, B1); PG8_BAR; PG8_SCHED;
;             PG8_LDA(At, 1, 1); PG8_STAGE(PG8_SB(1, 0), b3, voffB); PG8_STAGE(PG8_SB(1, 1), b3 + hstepB, voffB); PG8_STAGE(PG8_SA(1, 0), a3, voffA);
;             PG8_WAIT_V(8); PG8_WAIT_L(0); PG8_BAR; PG8_MMA(1, 0, At, B0); PG8_MMA(1, 1, At, B1); PG8_BAR; PG8_SCHED;
	ds_read_b128 v[112:115], v213
	ds_read_b128 v[124:127], v213 offset:1024
	ds_read_b128 v[136:139], v213 offset:2048
	ds_read_b128 v[140:143], v213 offset:3072
	ds_read_b128 v[144:147], v214
	ds_read_b128 v[148:151], v214 offset:1024
	ds_read_b128 v[152:155], v214 offset:2048
	ds_read_b128 v[156:159], v214 offset:3072
	s_mov_b32 m0, s18
	v_lshl_add_u64 v[228:229], v[216:217], 0, s[34:35]
	ds_read_b128 v[160:163], v212 offset:32768
	ds_read_b128 v[164:167], v212 offset:33792
	ds_read_b128 v[168:171], v212 offset:34816
	ds_read_b128 v[172:175], v212 offset:35840
	ds_read_b128 v[176:179], v212 offset:36864
	ds_read_b128 v[180:183], v212 offset:37888
	ds_read_b128 v[220:223], v212 offset:38912
	ds_read_b128 v[224:227], v212 offset:39936
	global_load_lds_dwordx4 v[228:229], off
	v_lshl_add_u64 v[228:229], v[216:217], 0, s[36:37]
	s_mov_b32 m0, s19
	s_nop 0
	global_load_lds_dwordx4 v[228:229], off
	s_waitcnt vmcnt(8)
	s_waitcnt lgkmcnt(0)
	s_barrier
	s_waitcnt lgkmcnt(0)
	v_mfma_f32_16x16x32_bf16 v[132:135], v[112:115], v[160:163], v[132:135]
	v_mfma_f32_16x16x32_bf16 v[128:131], v[136:139], v[160:163], v[128:131]
	v_mfma_f32_16x16x32_bf16 v[108:111], v[112:115], v[168:171], v[108:111]
	v_mfma_f32_16x16x32_bf16 v[104:107], v[136:139], v[168:171], v[104:107]
	v_mfma_f32_16x16x32_bf16 v[92:95], v[112:115], v[176:179], v[92:95]
	v_mfma_f32_16x16x32_bf16 v[88:91], v[136:139], v[176:179], v[88:91]
	v_mfma_f32_16x16x32_bf16 v[76:79], v[112:115], v[220:223], v[76:79]
	v_mfma_f32_16x16x32_bf16 v[72:75], v[136:139], v[220:223], v[72:75]
	v_mfma_f32_16x16x32_bf16 v[132:135], v[124:127], v[164:167], v[132:135]
	v_mfma_f32_16x16x32_bf16 v[128:131], v[140:143], v[164:167], v[128:131]
	v_mfma_f32_16x16x32_bf16 v[108:111], v[124:127], v[172:175], v[108:111]
	v_mfma_f32_16x16x32_bf16 v[104:107], v[140:143], v[172:175], v[104:107]
	v_mfma_f32_16x16x32_bf16 v[92:95], v[124:127], v[180:183], v[92:95]
	v_mfma_f32_16x16x32_bf16 v[88:91], v[140:143], v[180:183], v[88:91]
	v_mfma_f32_16x16x32_bf16 v[76:79], v[124:127], v[224:227], v[76:79]
	v_mfma_f32_16x16x32_bf16 v[72:75], v[140:143], v[224:227], v[72:75]
	v_mfma_f32_16x16x32_bf16 v[120:123], v[144:147], v[160:163], v[120:123]
	v_mfma_f32_16x16x32_bf16 v[116:119], v[152:155], v[160:163], v[116:119]
	v_mfma_f32_16x16x32_bf16 v[100:103], v[144:147], v[168:171], v[100:103]
	v_mfma_f32_16x16x32_bf16 v[96:99], v[152:155], v[168:171], v[96:99]
	v_mfma_f32_16x16x32_bf16 v[84:87], v[144:147], v[176:179], v[84:87]
	v_mfma_f32_16x16x32_bf16 v[80:83], v[152:155], v[176:179], v[80:83]
	v_mfma_f32_16x16x32_bf16 v[68:71], v[144:147], v[220:223], v[68:71]
	v_mfma_f32_16x16x32_bf16 v[64:67], v[152:155], v[220:223], v[64:67]
	v_mfma_f32_16x16x32_bf16 v[120:123], v[148:151], v[164:167], v[120:123]
	v_mfma_f32_16x16x32_bf16 v[116:119], v[156:159], v[164:167], v[116:119]
	v_mfma_f32_16x16x32_bf16 v[100:103], v[148:151], v[172:175], v[100:103]
	v_mfma_f32_16x16x32_bf16 v[96:99], v[156:159], v[172:175], v[96:99]
	v_mfma_f32_16x16x32_bf16 v[84:87], v[148:151], v[180:183], v[84:87]
	v_mfma_f32_16x16x32_bf16 v[80:83], v[156:159], v[180:183], v[80:83]
	v_mfma_f32_16x16x32_bf16 v[68:71], v[148:151], v[224:227], v[68:71]
	v_mfma_f32_16x16x32_bf16 v[64:67], v[156:159], v[224:227], v[64:67]
	s_barrier
	s_add_i32 s8, s91, s14
	v_lshl_add_u64 v[228:229], v[208:209], 0, s[38:39]
	s_mov_b32 m0, s8
	ds_read_b128 v[160:163], v212 offset:49152
	ds_read_b128 v[164:167], v212 offset:50176
	ds_read_b128 v[168:171], v212 offset:51200
	ds_read_b128 v[172:175], v212 offset:52224
	ds_read_b128 v[176:179], v212 offset:53248
	ds_read_b128 v[180:183], v212 offset:54272
	ds_read_b128 v[220:223], v212 offset:55296
	ds_read_b128 v[224:227], v212 offset:56320
	global_load_lds_dwordx4 v[228:229], off
	v_lshl_add_u64 v[228:229], v[208:209], 0, s[40:41]
	s_add_i32 m0, s8, 0x2000
	s_add_i32 s8, s92, s14
	global_load_lds_dwordx4 v[228:229], off
	v_lshl_add_u64 v[228:229], v[208:209], 0, s[52:53]
	s_mov_b32 m0, s8
	v_lshl_add_u64 v[208:209], v[208:209], 0, s[54:55]
	global_load_lds_dwordx4 v[228:229], off
	s_add_i32 m0, s8, 0x2000
	s_nop 0
	global_load_lds_dwordx4 v[208:209], off
	v_lshl_add_u64 v[208:209], v[216:217], 0, s[38:39]
	s_mov_b32 m0, s78
	s_nop 0
	global_load_lds_dwordx4 v[208:209], off
	v_lshl_add_u64 v[208:209], v[216:217], 0, s[40:41]
	s_mov_b32 m0, s79
	s_nop 0
	global_load_lds_dwordx4 v[208:209], off
	s_waitcnt vmcnt(8)
	s_waitcnt lgkmcnt(0)
	s_barrier
	s_waitcnt lgkmcnt(0)
	v_mfma_f32_16x16x32_bf16 v[60:63], v[112:115], v[160:163], v[60:63]
	v_mfma_f32_16x16x32_bf16 v[56:59], v[136:139], v[160:163], v[56:59]
	v_mfma_f32_16x16x32_bf16 v[44:47], v[112:115], v[168:171], v[44:47]
	v_mfma_f32_16x16x32_bf16 v[40:43], v[136:139], v[168:171], v[40:43]
	v_mfma_f32_16x16x32_bf16 v[28:31], v[112:115], v[176:179], v[28:31]
	v_mfma_f32_16x16x32_bf16 v[24:27], v[136:139], v[176:179], v[24:27]
	v_mfma_f32_16x16x32_bf16 v[12:15], v[112:115], v[220:223], v[12:15]
	v_mfma_f32_16x16x32_bf16 v[8:11], v[136:139], v[220:223], v[8:11]
	v_mfma_f32_16x16x32_bf16 v[60:63], v[124:127], v[164:167], v[60:63]
	v_mfma_f32_16x16x32_bf16 v[56:59], v[140:143], v[164:167], v[56:59]
	v_mfma_f32_16x16x32_bf16 v[44:47], v[124:127], v[172:175], v[44:47]
	v_mfma_f32_16x16x32_bf16 v[40:43], v[140:143], v[172:175], v[40:43]
	v_mfma_f32_16x16x32_bf16 v[28:31], v[124:127], v[180:183], v[28:31]
	v_mfma_f32_16x16x32_bf16 v[24:27], v[140:143], v[180:183], v[24:27]
	v_mfma_f32_16x16x32_bf16 v[12:15], v[124:127], v[224:227], v[12:15]
	v_mfma_f32_16x16x32_bf16 v[8:11], v[140:143], v[224:227], v[8:11]
	v_mfma_f32_16x16x32_bf16 v[52:55], v[144:147], v[160:163], v[52:55]
	v_mfma_f32_16x16x32_bf16 v[48:51], v[152:155], v[160:163], v[48:51]
	v_mfma_f32_16x16x32_bf16 v[36:39], v[144:147], v[168:171], v[36:39]
	v_mfma_f32_16x16x32_bf16 v[32:35], v[152:155], v[168:171], v[32:35]
	v_mfma_f32_16x16x32_bf16 v[20:23], v[144:147], v[176:179], v[20:23]
	v_mfma_f32_16x16x32_bf16 v[16:19], v[152:155], v[176:179], v[16:19]
	v_mfma_f32_16x16x32_bf16 v[4:7], v[144:147], v[220:223], v[4:7]
	v_mfma_f32_16x16x32_bf16 v[0:3], v[152:155], v[220:223], v[0:3]
	v_mfma_f32_16x16x32_bf16 v[52:55], v[148:151], v[164:167], v[52:55]
	v_mfma_f32_16x16x32_bf16 v[48:51], v[156:159], v[164:167], v[48:51]
	v_mfma_f32_16x16x32_bf16 v[36:39], v[148:151], v[172:175], v[36:39]
	v_mfma_f32_16x16x32_bf16 v[32:35], v[156:159], v[172:175], v[32:35]
	v_mfma_f32_16x16x32_bf16 v[20:23], v[148:151], v[180:183], v[20:23]
	v_mfma_f32_16x16x32_bf16 v[16:19], v[156:159], v[180:183], v[16:19]
	v_mfma_f32_16x16x32_bf16 v[4:7], v[148:151], v[224:227], v[4:7]
	v_mfma_f32_16x16x32_bf16 v[0:3], v[156:159], v[224:227], v[0:3]
	s_barrier
	s_add_i32 s73, s73, 2
	s_add_u32 s68, s68, 0x10000
	s_addc_u32 s69, s69, 0
	s_add_u32 s70, s70, 0x10000
	s_addc_u32 s71, s71, 0
	s_cmp_gt_u32 s73, 41

; #define PG8_STAGE(bufoff, gbase, voff) do { _Pragma("unroll") for (int _i = 0; _i < 2; ++_i) \
;         __builtin_amdgcn_global_load_lds((const unsigned*)((const char*)(gbase) + (voff)[_i]), (PG8_LAS unsigned*)(lds + (bufoff) + ldsw + _i * 8192), 16, 0, 0); } while (0)
; #define PG8_LDA(dst, b, h) do { _Pragma("unroll") for (int m = 0; m < 4; ++m) _Pragma("unroll") for (int k = 0; k < 2; ++k) dst[m][k] = *(const PG8_LAS bf16x8*)(lds + PG8_SA(b, h) + aoff + m * 2048 + k * 1024); } while (0)
;     __host__ __device__ bool next(int i, Unit& u) const {
;         const long L = (long)i * G + c; if (L >= nwg) return false;
;         int wgid = (int)L; { const int q = nwg / NXCD, r = nwg % NXCD, xcd = wgid % NXCD, off = wgid / NXCD; wgid = (xcd < r ? xcd * (q + 1) : r * (q + 1) + (xcd - r) * q) + off; }
;         const int nig = wgm * nN, gid = wgid / nig, fm = gid * wgm, gsz = (nM - fm) < wgm ? (nM - fm) : wgm;
;         u.pm = fm + ((wgid % nig) % gsz); u.pn = (wgid % nig) / gsz; return true;
; template <class Epi, class Sched, bool ALIGN_EPI = false, bool SP2 = false>
; __device__ __forceinline__ void gemm_phase(PG8_LAS unsigned char* lds, const Gemm g, const Sched& S, const Epi& E) {
;     ...
;         const bool has_next = S.next(ui + 1, nxt);
;         const char* nA = has_next ? (const char*)g.A + (size_t)nxt.pm * tstepA : cA; const char* nB = has_next ? (const char*)g.Bt + (size_t)nxt.pn * tstepB : cB;
;         for (int t = 0; t < nt; t += 2) {
;             const bool last = (t == nt - 2);
;             const char* a1 = cA + (size_t)(t + 1) * kstepA;
;             const char* a2 = last ? nA : cA + (size_t)(t + 2) * kstepA; const char* b2 = last ? nB : cB + (size_t)(t + 2) * kstep;
;             const char* a3 = a2 + kstepA; const char* b3 = b2 + kstep;
;             if (last && has_next) S.a_ready(nxt);
;             if constexpr (SP2) {
;             PG8_LDB(B0, 0, 0); PG8_LDB(B1, 0, 1); PG8_SCHED; PG8_LDA(At, 0, 0); PG8_STAGE(PG8_SA(1, 1), a1 + hstepA, voffA);
;             PG8_WAIT_V(8); PG8_WAIT_L(0); PG8_BAR; PG8_MMA(0, 0, At, B0); PG8_MMA(0, 1, At, B1); PG8_BAR; PG8_SCHED;
;             PG8_LDA(At, 0, 1); PG8_STAGE(PG8_SB(0, 0), b2, voffB); PG8_STAGE(PG8_SB(0, 1), b2 + hstepB, voffB); PG8_STAGE(PG8_SA(0, 0), a2, voffA);
;             PG8_WAIT_V(8); PG8_WAIT_L(0); PG8_BAR; PG8_MMA(1, 0, At, B0); PG8_MMA(1, 1, At, B1); PG8_BAR; PG8_SCHED;
.LBB0_312:
	ds_read_b128 v[140:143], v159
	ds_read_b128 v[144:147], v159 offset:1024
	ds_read_b128 v[148:151], v159 offset:2048
	ds_read_b128 v[166:169], v159 offset:3072
	ds_read_b128 v[170:173], v160
	ds_read_b128 v[174:177], v160 offset:1024
	ds_read_b128 v[178:181], v160 offset:2048
	ds_read_b128 v[182:185], v160 offset:3072
	ds_read_b128 v[190:193], v161
	ds_read_b128 v[194:197], v161 offset:1024
	ds_read_b128 v[198:201], v161 offset:2048
	ds_read_b128 v[202:205], v161 offset:3072
	ds_read_b128 v[206:209], v161 offset:4096
	ds_read_b128 v[210:213], v161 offset:5120
	ds_read_b128 v[214:217], v161 offset:6144
	ds_read_b128 v[220:223], v161 offset:7168
	s_add_i32 s96, s96, 1
	s_mul_i32 s2, s96, s97
	s_mul_hi_u32 s3, s96, s82
	s_add_i32 s3, s3, s2
	s_mul_i32 s2, s96, s82
	s_add_u32 s68, s2, s16
	s_addc_u32 s69, s3, s17
	v_cmp_gt_i64_e32 vcc, s[68:69], v[138:139]
	v_cmp_lt_i64_e64 s[2:3], s[68:69], v[136:137]
	s_cbranch_vccnz .LBB0_314
	s_ashr_i32 s7, s68, 31
	s_lshr_b32 s7, s7, 29
	s_add_i32 s7, s68, s7
	s_ashr_i32 s8, s7, 3
	s_and_b32 s7, s7, -8
	s_sub_i32 s7, s68, s7
	s_cmp_lt_i32 s7, 0
	s_movk_i32 s9, 0xf1
	s_cselect_b32 s9, s9, 0xf0
	s_mul_i32 s7, s7, s9
	s_add_i32 s7, s7, s8
	s_mul_hi_i32 s8, s7, 0x88888889
	s_add_i32 s8, s8, s7
	s_lshr_b32 s9, s8, 31
	s_ashr_i32 s8, s8, 5
	s_add_i32 s8, s8, s9
	s_lshl_b32 s9, s8, 2
	s_mul_i32 s8, s8, 60
	s_sub_i32 s7, s7, s8
	s_abs_i32 s8, s7
	s_ashr_i32 s60, s7, 2
	s_and_b32 s7, s7, 3
	s_add_i32 s62, s9, s7
.LBB0_314:
	s_ashr_i32 s63, s62, 31
	s_lshl_b64 s[8:9], s[62:63], 19
	s_add_u32 s68, s12, s8
	s_addc_u32 s69, s13, s9
	s_and_b64 s[8:9], s[2:3], exec
	s_cselect_b32 s7, s69, s5
	s_cselect_b32 s63, s68, s4
	s_ashr_i32 s61, s60, 31
	s_lshl_b64 s[8:9], s[60:61], 19
	s_add_u32 s70, s87, s8
	s_addc_u32 s71, s88, s9
	s_and_b64 s[8:9], s[2:3], exec
	s_cselect_b32 s61, s71, s75
	s_cselect_b32 s73, s70, s74
	s_add_u32 s4, s4, 0x10000
	s_addc_u32 s5, s5, 0
	s_add_u32 s74, s74, 0x10000
	s_addc_u32 s75, s75, 0
	s_mov_b32 s76, -2
	s_cmp_eq_u32 s76, 12
	s_cselect_b32 s9, s7, s5
	s_cselect_b32 s8, s63, s4
	s_cselect_b32 vcc_hi, s61, s75
	s_cselect_b32 vcc_lo, s73, s74
	s_movk_i32 s78, 0xc000
	v_lshl_add_u64 v[2:3], s[4:5], 0, v[132:133]
	s_mov_b32 s79, -1
	v_lshl_add_u64 v[152:153], v[2:3], 0, s[78:79]
	s_movk_i32 s78, 0xe000
	s_add_i32 m0, s90, 0xc000
	s_mov_b32 s79, -1
	global_load_lds_dwordx4 v[152:153], off
	v_lshl_add_u64 v[2:3], v[2:3], 0, s[78:79]
	s_add_i32 m0, s90, 0xe000
	s_nop 0
	global_load_lds_dwordx4 v[2:3], off
	s_waitcnt vmcnt(8)
	s_waitcnt lgkmcnt(0)
	s_barrier
	s_waitcnt lgkmcnt(0)
	v_mfma_f32_16x16x32_bf16 v[128:131], v[140:143], v[190:193], 0
	v_mfma_f32_16x16x32_bf16 v[124:127], v[148:151], v[190:193], 0
	v_mfma_f32_16x16x32_bf16 v[112:115], v[140:143], v[198:201], 0
	v_mfma_f32_16x16x32_bf16 v[108:111], v[148:151], v[198:201], 0
	v_mfma_f32_16x16x32_bf16 v[96:99], v[140:143], v[206:209], 0
	v_mfma_f32_16x16x32_bf16 v[92:95], v[148:151], v[206:209], 0
	v_mfma_f32_16x16x32_bf16 v[80:83], v[140:143], v[214:217], 0
	v_mfma_f32_16x16x32_bf16 v[76:79], v[148:151], v[214:217], 0
	v_mfma_f32_16x16x32_bf16 v[128:131], v[144:147], v[194:197], v[128:131]
	v_mfma_f32_16x16x32_bf16 v[124:127], v[166:169], v[194:197], v[124:127]
	v_mfma_f32_16x16x32_bf16 v[112:115], v[144:147], v[202:205], v[112:115]
	v_mfma_f32_16x16x32_bf16 v[108:111], v[166:169], v[202:205], v[108:111]
	v_mfma_f32_16x16x32_bf16 v[96:99], v[144:147], v[210:213], v[96:99]
	v_mfma_f32_16x16x32_bf16 v[92:95], v[166:169], v[210:213], v[92:95]
	v_mfma_f32_16x16x32_bf16 v[80:83], v[144:147], v[220:223], v[80:83]
	v_mfma_f32_16x16x32_bf16 v[76:79], v[166:169], v[220:223], v[76:79]
	v_mfma_f32_16x16x32_bf16 v[120:123], v[170:173], v[190:193], 0
	v_mfma_f32_16x16x32_bf16 v[116:119], v[178:181], v[190:193], 0
	v_mfma_f32_16x16x32_bf16 v[104:107], v[170:173], v[198:201], 0
	v_mfma_f32_16x16x32_bf16 v[100:103], v[178:181], v[198:201], 0
	v_mfma_f32_16x16x32_bf16 v[88:91], v[170:173], v[206:209], 0
	v_mfma_f32_16x16x32_bf16 v[84:87], v[178:181], v[206:209], 0
	v_mfma_f32_16x16x32_bf16 v[72:75], v[170:173], v[214:217], 0
	v_mfma_f32_16x16x32_bf16 v[68:71], v[178:181], v[214:217], 0
	v_mfma_f32_16x16x32_bf16 v[120:123], v[174:177], v[194:197], v[120:123]
	v_mfma_f32_16x16x32_bf16 v[116:119], v[182:185], v[194:197], v[116:119]
	v_mfma_f32_16x16x32_bf16 v[104:107], v[174:177], v[202:205], v[104:107]
	v_mfma_f32_16x16x32_bf16 v[100:103], v[182:185], v[202:205], v[100:103]
	v_mfma_f32_16x16x32_bf16 v[88:91], v[174:177], v[210:213], v[88:91]
	v_mfma_f32_16x16x32_bf16 v[84:87], v[182:185], v[210:213], v[84:87]
	v_mfma_f32_16x16x32_bf16 v[72:75], v[174:177], v[220:223], v[72:75]
	v_mfma_f32_16x16x32_bf16 v[68:71], v[182:185], v[220:223], v[68:71]
	s_barrier
	s_add_i32 s77, s15, s89
	v_lshl_add_u64 v[152:153], vcc, 0, v[132:133]
	s_mov_b32 m0, s77
	ds_read_b128 v[190:193], v161 offset:16384
	ds_read_b128 v[194:197], v161 offset:17408
	ds_read_b128 v[198:201], v161 offset:18432
	ds_read_b128 v[202:205], v161 offset:19456
	ds_read_b128 v[206:209], v161 offset:20480
	ds_read_b128 v[210:213], v161 offset:21504
	ds_read_b128 v[214:217], v161 offset:22528
	ds_read_b128 v[220:223], v161 offset:23552
	global_load_lds_dwordx4 v[152:153], off
	v_lshl_add_u64 v[2:3], v[152:153], 0, s[30:31]
	s_add_i32 m0, s77, 0x2000
	s_add_i32 s77, s18, s89
	global_load_lds_dwordx4 v[2:3], off
	v_lshl_add_u64 v[2:3], v[152:153], 0, s[34:35]
	s_mov_b32 m0, s77
	v_lshl_add_u64 v[186:187], s[8:9], 0, v[132:133]
	global_load_lds_dwordx4 v[2:3], off
	v_lshl_add_u64 v[2:3], v[152:153], 0, s[36:37]
	s_add_i32 m0, s77, 0x2000
	s_nop 0
	global_load_lds_dwordx4 v[2:3], off
	s_mov_b32 m0, s90
	v_lshl_add_u64 v[2:3], v[186:187], 0, s[30:31]
	global_load_lds_dwordx4 v[186:187], off
	s_mov_b32 m0, s91
	s_nop 0
	global_load_lds_dwordx4 v[2:3], off
	s_waitcnt vmcnt(8)
	s_waitcnt lgkmcnt(0)
	s_barrier
; #define PG8_STAGE(bufoff, gbase, voff) do { _Pragma("unroll") for (int _i = 0; _i < 2; ++_i) \
;         __builtin_amdgcn_global_load_lds((const unsigned*)((const char*)(gbase) + (voff)[_i]), (PG8_LAS unsigned*)(lds + (bufoff) + ldsw + _i * 8192), 16, 0, 0); } while (0)
; #define PG8_LDA(dst, b, h) do { _Pragma("unroll") for (int m = 0; m < 4; ++m) _Pragma("unroll") for (int k = 0; k < 2; ++k) dst[m][k] = *(const PG8_LAS bf16x8*)(lds + PG8_SA(b, h) + aoff + m * 2048 + k * 1024); } while (0)
; #define PG8_LDB(dst, b, h) do { _Pragma("unroll") for (int n = 0; n < 2; ++n) _Pragma("unroll") for (int k = 0; k < 2; ++k) dst[n][k] = *(const PG8_LAS bf16x8*)(lds + PG8_SB(b, h) + boff + n * 2048 + k * 1024); } while (0)
; #define PG8_MMA(ai, bj, At, Bt) do { __builtin_amdgcn_s_setprio(1); _Pragma("unroll") for (int m = 0; m < 4; ++m) _Pragma("unroll") for (int n = 0; n < 2; ++n) _Pragma("unroll") for (int k = 0; k < 2; ++k) \
;         acc[ai][bj][m][n] = __builtin_amdgcn_mfma_f32_16x16x32_bf16(Bt[n][k], At[m][k], acc[ai][bj][m][n], 0, 0, 0); __builtin_amdgcn_s_setprio(0); } while (0)
; #define PG8_WAIT_V(n) asm volatile("s_waitcnt vmcnt(" #n ")" ::: "memory")
; #define PG8_WAIT_L(n) asm volatile("s_waitcnt lgkmcnt(" #n ")" ::: "memory")
; #define PG8_BAR __builtin_amdgcn_s_barrier()
; #define PG8_SCHED __builtin_amdgcn_sched_barrier(0)
; template <class Epi, class Sched, bool ALIGN_EPI = false, bool SP2 = false>
; __device__ __forceinline__ void gemm_phase(PG8_LAS unsigned char* lds, const Gemm g, const Sched& S, const Epi& E) {
;     ...
;             PG8_WAIT_V(8); PG8_WAIT_L(0); PG8_BAR; PG8_MMA(1, 0, At, B0); PG8_MMA(1, 1, At, B1); PG8_BAR; PG8_SCHED;
;             PG8_LDB(B0, 1, 0); PG8_LDB(B1, 1, 1); PG8_SCHED; PG8_LDA(At, 1, 0); PG8_STAGE(PG8_SA(0, 1), a2 + hstepA, voffA);
;             PG8_WAIT_V(8); PG8_WAIT_L(0); PG8_BAR; PG8_MMA(0, 0, At, B0); PG8_MMA(0, 1, At, B1); PG8_BAR; PG8_SCHED;
	s_waitcnt lgkmcnt(0)
	v_mfma_f32_16x16x32_bf16 v[64:67], v[140:143], v[190:193], 0
	v_mfma_f32_16x16x32_bf16 v[60:63], v[148:151], v[190:193], 0
	v_mfma_f32_16x16x32_bf16 v[48:51], v[140:143], v[198:201], 0
	v_mfma_f32_16x16x32_bf16 v[44:47], v[148:151], v[198:201], 0
	v_mfma_f32_16x16x32_bf16 v[32:35], v[140:143], v[206:209], 0
	v_mfma_f32_16x16x32_bf16 v[28:31], v[148:151], v[206:209], 0
	v_mfma_f32_16x16x32_bf16 v[16:19], v[140:143], v[214:217], 0
	v_mfma_f32_16x16x32_bf16 v[12:15], v[148:151], v[214:217], 0
	v_mfma_f32_16x16x32_bf16 v[64:67], v[144:147], v[194:197], v[64:67]
	v_mfma_f32_16x16x32_bf16 v[60:63], v[166:169], v[194:197], v[60:63]
	v_mfma_f32_16x16x32_bf16 v[48:51], v[144:147], v[202:205], v[48:51]
	v_mfma_f32_16x16x32_bf16 v[44:47], v[166:169], v[202:205], v[44:47]
	v_mfma_f32_16x16x32_bf16 v[32:35], v[144:147], v[210:213], v[32:35]
	v_mfma_f32_16x16x32_bf16 v[28:31], v[166:169], v[210:213], v[28:31]
	v_mfma_f32_16x16x32_bf16 v[16:19], v[144:147], v[220:223], v[16:19]
	v_mfma_f32_16x16x32_bf16 v[12:15], v[166:169], v[220:223], v[12:15]
	v_mfma_f32_16x16x32_bf16 v[56:59], v[170:173], v[190:193], 0
	v_mfma_f32_16x16x32_bf16 v[52:55], v[178:181], v[190:193], 0
	v_mfma_f32_16x16x32_bf16 v[40:43], v[170:173], v[198:201], 0
	v_mfma_f32_16x16x32_bf16 v[36:39], v[178:181], v[198:201], 0
	v_mfma_f32_16x16x32_bf16 v[24:27], v[170:173], v[206:209], 0
	v_mfma_f32_16x16x32_bf16 v[20:23], v[178:181], v[206:209], 0
	v_mfma_f32_16x16x32_bf16 v[8:11], v[170:173], v[214:217], 0
	v_mfma_f32_16x16x32_bf16 v[2:5], v[178:181], v[214:217], 0
	v_mfma_f32_16x16x32_bf16 v[56:59], v[174:177], v[194:197], v[56:59]
	v_mfma_f32_16x16x32_bf16 v[52:55], v[182:185], v[194:197], v[52:55]
	v_mfma_f32_16x16x32_bf16 v[40:43], v[174:177], v[202:205], v[40:43]
	v_mfma_f32_16x16x32_bf16 v[36:39], v[182:185], v[202:205], v[36:39]
	v_mfma_f32_16x16x32_bf16 v[24:27], v[174:177], v[210:213], v[24:27]
	v_mfma_f32_16x16x32_bf16 v[20:23], v[182:185], v[210:213], v[20:23]
	v_mfma_f32_16x16x32_bf16 v[8:11], v[174:177], v[220:223], v[8:11]
	v_mfma_f32_16x16x32_bf16 v[2:5], v[182:185], v[220:223], v[2:5]
	s_barrier
	ds_read_b128 v[140:143], v162
	ds_read_b128 v[144:147], v162 offset:1024
	ds_read_b128 v[148:151], v162 offset:2048
	ds_read_b128 v[166:169], v162 offset:3072
	ds_read_b128 v[170:173], v163
	ds_read_b128 v[174:177], v163 offset:1024
	ds_read_b128 v[178:181], v163 offset:2048
	ds_read_b128 v[182:185], v163 offset:3072
	s_mov_b32 m0, s92
	v_lshl_add_u64 v[6:7], v[186:187], 0, s[34:35]
	ds_read_b128 v[190:193], v161 offset:32768
	ds_read_b128 v[194:197], v161 offset:33792
	ds_read_b128 v[198:201], v161 offset:34816
	ds_read_b128 v[202:205], v161 offset:35840
	ds_read_b128 v[206:209], v161 offset:36864
	ds_read_b128 v[210:213], v161 offset:37888
	ds_read_b128 v[214:217], v161 offset:38912
	ds_read_b128 v[220:223], v161 offset:39936
	global_load_lds_dwordx4 v[6:7], off
	v_lshl_add_u64 v[6:7], v[186:187], 0, s[36:37]
	s_mov_b32 m0, s93
	s_nop 0
	global_load_lds_dwordx4 v[6:7], off
	s_waitcnt vmcnt(8)
	s_waitcnt lgkmcnt(0)
	s_barrier
	s_waitcnt lgkmcnt(0)
	v_mfma_f32_16x16x32_bf16 v[128:131], v[140:143], v[190:193], v[128:131]
	v_mfma_f32_16x16x32_bf16 v[124:127], v[148:151], v[190:193], v[124:127]
	v_mfma_f32_16x16x32_bf16 v[112:115], v[140:143], v[198:201], v[112:115]
	v_mfma_f32_16x16x32_bf16 v[108:111], v[148:151], v[198:201], v[108:111]
	v_mfma_f32_16x16x32_bf16 v[96:99], v[140:143], v[206:209], v[96:99]
	v_mfma_f32_16x16x32_bf16 v[92:95], v[148:151], v[206:209], v[92:95]
	v_mfma_f32_16x16x32_bf16 v[80:83], v[140:143], v[214:217], v[80:83]
	v_mfma_f32_16x16x32_bf16 v[76:79], v[148:151], v[214:217], v[76:79]
	v_mfma_f32_16x16x32_bf16 v[128:131], v[144:147], v[194:197], v[128:131]
	v_mfma_f32_16x16x32_bf16 v[124:127], v[166:169], v[194:197], v[124:127]
	v_mfma_f32_16x16x32_bf16 v[112:115], v[144:147], v[202:205], v[112:115]
	v_mfma_f32_16x16x32_bf16 v[108:111], v[166:169], v[202:205], v[108:111]
	v_mfma_f32_16x16x32_bf16 v[96:99], v[144:147], v[210:213], v[96:99]
	v_mfma_f32_16x16x32_bf16 v[92:95], v[166:169], v[210:213], v[92:95]
	v_mfma_f32_16x16x32_bf16 v[80:83], v[144:147], v[220:223], v[80:83]
	v_mfma_f32_16x16x32_bf16 v[76:79], v[166:169], v[220:223], v[76:79]
	v_mfma_f32_16x16x32_bf16 v[120:123], v[170:173], v[190:193], v[120:123]
	v_mfma_f32_16x16x32_bf16 v[116:119], v[178:181], v[190:193], v[116:119]
	v_mfma_f32_16x16x32_bf16 v[104:107], v[170:173], v[198:201], v[104:107]
	v_mfma_f32_16x16x32_bf16 v[100:103], v[178:181], v[198:201], v[100:103]
	v_mfma_f32_16x16x32_bf16 v[88:91], v[170:173], v[206:209], v[88:91]
	v_mfma_f32_16x16x32_bf16 v[84:87], v[178:181], v[206:209], v[84:87]
	v_mfma_f32_16x16x32_bf16 v[72:75], v[170:173], v[214:217], v[72:75]
	v_mfma_f32_16x16x32_bf16 v[68:71], v[178:181], v[214:217], v[68:71]
	v_mfma_f32_16x16x32_bf16 v[120:123], v[174:177], v[194:197], v[120:123]
	v_mfma_f32_16x16x32_bf16 v[116:119], v[182:185], v[194:197], v[116:119]
	v_mfma_f32_16x16x32_bf16 v[104:107], v[174:177], v[202:205], v[104:107]
	v_mfma_f32_16x16x32_bf16 v[100:103], v[182:185], v[202:205], v[100:103]
	v_mfma_f32_16x16x32_bf16 v[88:91], v[174:177], v[210:213], v[88:91]
	v_mfma_f32_16x16x32_bf16 v[84:87], v[182:185], v[210:213], v[84:87]
	v_mfma_f32_16x16x32_bf16 v[72:75], v[174:177], v[220:223], v[72:75]
	v_mfma_f32_16x16x32_bf16 v[68:71], v[182:185], v[220:223], v[68:71]
	s_barrier
; #define PG8_STAGE(bufoff, gbase, voff) do { _Pragma("unroll") for (int _i = 0; _i < 2; ++_i) \
;         __builtin_amdgcn_global_load_lds((const unsigned*)((const char*)(gbase) + (voff)[_i]), (PG8_LAS unsigned*)(lds + (bufoff) + ldsw + _i * 8192), 16, 0, 0); } while (0)
; #define PG8_LDA(dst, b, h) do { _Pragma("unroll") for (int m = 0; m < 4; ++m) _Pragma("unroll") for (int k = 0; k < 2; ++k) dst[m][k] = *(const PG8_LAS bf16x8*)(lds + PG8_SA(b, h) + aoff + m * 2048 + k * 1024); } while (0)
; #define PG8_MMA(ai, bj, At, Bt) do { __builtin_amdgcn_s_setprio(1); _Pragma("unroll") for (int m = 0; m < 4; ++m) _Pragma("unroll") for (int n = 0; n < 2; ++n) _Pragma("unroll") for (int k = 0; k < 2; ++k) \
;         acc[ai][bj][m][n] = __builtin_amdgcn_mfma_f32_16x16x32_bf16(Bt[n][k], At[m][k], acc[ai][bj][m][n], 0, 0, 0); __builtin_amdgcn_s_setprio(0); } while (0)
; #define PG8_WAIT_V(n) asm volatile("s_waitcnt vmcnt(" #n ")" ::: "memory")
; #define PG8_WAIT_L(n) asm volatile("s_waitcnt lgkmcnt(" #n ")" ::: "memory")
; #define PG8_BAR __builtin_amdgcn_s_barrier()
; #define PG8_SCHED __builtin_amdgcn_sched_barrier(0)
; template <class Epi, class Sched, bool ALIGN_EPI = false, bool SP2 = false>
; __device__ __forceinline__ void gemm_phase(PG8_LAS unsigned char* lds, const Gemm g, const Sched& S, const Epi& E) {
;     ...
;             PG8_LDA(At, 1, 1); PG8_STAGE(PG8_SB(1, 0), b3, voffB); PG8_STAGE(PG8_SB(1, 1), b3 + hstepB, voffB); PG8_STAGE(PG8_SA(1, 0), a3, voffA);
;             PG8_WAIT_V(8); PG8_WAIT_L(0); PG8_BAR; PG8_MMA(1, 0, At, B0); PG8_MMA(1, 1, At, B1); PG8_BAR; PG8_SCHED;
	s_add_i32 s8, s19, s89
	v_lshl_add_u64 v[6:7], v[152:153], 0, s[38:39]
	s_mov_b32 m0, s8
	ds_read_b128 v[190:193], v161 offset:49152
	ds_read_b128 v[194:197], v161 offset:50176
	ds_read_b128 v[198:201], v161 offset:51200
	ds_read_b128 v[202:205], v161 offset:52224
	ds_read_b128 v[206:209], v161 offset:53248
	ds_read_b128 v[210:213], v161 offset:54272
	ds_read_b128 v[214:217], v161 offset:55296
	ds_read_b128 v[220:223], v161 offset:56320
	global_load_lds_dwordx4 v[6:7], off
	v_lshl_add_u64 v[6:7], v[152:153], 0, s[40:41]
	s_add_i32 m0, s8, 0x2000
	s_add_i32 s8, s80, s89
	global_load_lds_dwordx4 v[6:7], off
	v_lshl_add_u64 v[6:7], v[152:153], 0, s[52:53]
	s_mov_b32 m0, s8
	s_nop 0
	global_load_lds_dwordx4 v[6:7], off
	v_lshl_add_u64 v[6:7], v[152:153], 0, s[54:55]
	s_add_i32 m0, s8, 0x2000
	s_nop 0
	global_load_lds_dwordx4 v[6:7], off
	v_lshl_add_u64 v[6:7], v[186:187], 0, s[38:39]
	s_mov_b32 m0, s94
	s_nop 0
	global_load_lds_dwordx4 v[6:7], off
	v_lshl_add_u64 v[6:7], v[186:187], 0, s[40:41]
	s_mov_b32 m0, s95
	s_nop 0
	global_load_lds_dwordx4 v[6:7], off
	s_waitcnt vmcnt(8)
	s_waitcnt lgkmcnt(0)
	s_barrier
	s_waitcnt lgkmcnt(0)
	v_mfma_f32_16x16x32_bf16 v[64:67], v[140:143], v[190:193], v[64:67]
	v_mfma_f32_16x16x32_bf16 v[60:63], v[148:151], v[190:193], v[60:63]
	v_mfma_f32_16x16x32_bf16 v[48:51], v[140:143], v[198:201], v[48:51]
	v_mfma_f32_16x16x32_bf16 v[44:47], v[148:151], v[198:201], v[44:47]
	v_mfma_f32_16x16x32_bf16 v[32:35], v[140:143], v[206:209], v[32:35]
	v_mfma_f32_16x16x32_bf16 v[28:31], v[148:151], v[206:209], v[28:31]
	v_mfma_f32_16x16x32_bf16 v[16:19], v[140:143], v[214:217], v[16:19]
	v_mfma_f32_16x16x32_bf16 v[12:15], v[148:151], v[214:217], v[12:15]
	v_mfma_f32_16x16x32_bf16 v[64:67], v[144:147], v[194:197], v[64:67]
	v_mfma_f32_16x16x32_bf16 v[60:63], v[166:169], v[194:197], v[60:63]
	v_mfma_f32_16x16x32_bf16 v[48:51], v[144:147], v[202:205], v[48:51]
	v_mfma_f32_16x16x32_bf16 v[44:47], v[166:169], v[202:205], v[44:47]
	v_mfma_f32_16x16x32_bf16 v[32:35], v[144:147], v[210:213], v[32:35]
	v_mfma_f32_16x16x32_bf16 v[28:31], v[166:169], v[210:213], v[28:31]
	v_mfma_f32_16x16x32_bf16 v[16:19], v[144:147], v[220:223], v[16:19]
	v_mfma_f32_16x16x32_bf16 v[12:15], v[166:169], v[220:223], v[12:15]
	v_mfma_f32_16x16x32_bf16 v[56:59], v[170:173], v[190:193], v[56:59]
	v_mfma_f32_16x16x32_bf16 v[52:55], v[178:181], v[190:193], v[52:55]
	v_mfma_f32_16x16x32_bf16 v[40:43], v[170:173], v[198:201], v[40:43]
	v_mfma_f32_16x16x32_bf16 v[36:39], v[178:181], v[198:201], v[36:39]
	v_mfma_f32_16x16x32_bf16 v[24:27], v[170:173], v[206:209], v[24:27]
	v_mfma_f32_16x16x32_bf16 v[20:23], v[178:181], v[206:209], v[20:23]
	v_mfma_f32_16x16x32_bf16 v[6:9], v[170:173], v[214:217], v[8:11]
	v_mfma_f32_16x16x32_bf16 v[2:5], v[178:181], v[214:217], v[2:5]
	v_mfma_f32_16x16x32_bf16 v[56:59], v[174:177], v[194:197], v[56:59]
	v_mfma_f32_16x16x32_bf16 v[52:55], v[182:185], v[194:197], v[52:55]
	v_mfma_f32_16x16x32_bf16 v[40:43], v[174:177], v[202:205], v[40:43]
	v_mfma_f32_16x16x32_bf16 v[36:39], v[182:185], v[202:205], v[36:39]
	v_mfma_f32_16x16x32_bf16 v[24:27], v[174:177], v[210:213], v[24:27]
	v_mfma_f32_16x16x32_bf16 v[20:23], v[182:185], v[210:213], v[20:23]
	v_mfma_f32_16x16x32_bf16 v[8:11], v[174:177], v[220:223], v[6:9]
	v_mfma_f32_16x16x32_bf16 v[4:7], v[182:185], v[220:223], v[2:5]
	s_barrier
	s_add_i32 s76, s76, 2
	s_add_u32 s4, s4, 0x10000
	s_addc_u32 s5, s5, 0
	s_add_u32 s74, s74, 0x10000
	s_addc_u32 s75, s75, 0
	s_cmp_gt_u32 s76, 13

; #define PG8_STAGE(bufoff, gbase, voff) do { _Pragma("unroll") for (int _i = 0; _i < 2; ++_i) \
;         __builtin_amdgcn_global_load_lds((const unsigned*)((const char*)(gbase) + (voff)[_i]), (PG8_LAS unsigned*)(lds + (bufoff) + ldsw + _i * 8192), 16, 0, 0); } while (0)
; #define PG8_LDA(dst, b, h) do { _Pragma("unroll") for (int m = 0; m < 4; ++m) _Pragma("unroll") for (int k = 0; k < 2; ++k) dst[m][k] = *(const PG8_LAS bf16x8*)(lds + PG8_SA(b, h) + aoff + m * 2048 + k * 1024); } while (0)
; #define PG8_LDB(dst, b, h) do { _Pragma("unroll") for (int n = 0; n < 2; ++n) _Pragma("unroll") for (int k = 0; k < 2; ++k) dst[n][k] = *(const PG8_LAS bf16x8*)(lds + PG8_SB(b, h) + boff + n * 2048 + k * 1024); } while (0)
; #define PG8_SCHED __builtin_amdgcn_sched_barrier(0)
;     __host__ __device__ bool next(int i, Unit& u) const {
;         const long L = (long)i * G + c; if (L >= nwg) return false;
;         int wgid = (int)L; { const int q = nwg / NXCD, r = nwg % NXCD, xcd = wgid % NXCD, off = wgid / NXCD; wgid = (xcd < r ? xcd * (q + 1) : r * (q + 1) + (xcd - r) * q) + off; }
;         const int nig = wgm * nN, gid = wgid / nig, fm = gid * wgm, gsz = (nM - fm) < wgm ? (nM - fm) : wgm;
;         u.pm = fm + ((wgid % nig) % gsz); u.pn = (wgid % nig) / gsz; return true;
; template <class Epi, class Sched, bool ALIGN_EPI = false, bool SP2 = false>
; __device__ __forceinline__ void gemm_phase(PG8_LAS unsigned char* lds, const Gemm g, const Sched& S, const Epi& E) {
;     ...
;         const bool has_next = S.next(ui + 1, nxt);
;         const char* nA = has_next ? (const char*)g.A + (size_t)nxt.pm * tstepA : cA; const char* nB = has_next ? (const char*)g.Bt + (size_t)nxt.pn * tstepB : cB;
;         for (int t = 0; t < nt; t += 2) {
;             const bool last = (t == nt - 2);
;             const char* a1 = cA + (size_t)(t + 1) * kstepA;
;             const char* a2 = last ? nA : cA + (size_t)(t + 2) * kstepA; const char* b2 = last ? nB : cB + (size_t)(t + 2) * kstep;
;             const char* a3 = a2 + kstepA; const char* b3 = b2 + kstep;
;             if (last && has_next) S.a_ready(nxt);
;             if constexpr (SP2) {
;             PG8_LDB(B0, 0, 0); PG8_LDB(B1, 0, 1); PG8_SCHED; PG8_LDA(At, 0, 0); PG8_STAGE(PG8_SA(1, 1), a1 + hstepA, voffA);
.LBB0_637:
	ds_read_b128 v[128:131], v197
	ds_read_b128 v[132:135], v197 offset:1024
	ds_read_b128 v[136:139], v197 offset:2048
	ds_read_b128 v[140:143], v197 offset:3072
	ds_read_b128 v[144:147], v198
	ds_read_b128 v[148:151], v198 offset:1024
	ds_read_b128 v[152:155], v198 offset:2048
	ds_read_b128 v[156:159], v198 offset:3072
	ds_read_b128 v[202:205], v199
	ds_read_b128 v[206:209], v199 offset:1024
	ds_read_b128 v[210:213], v199 offset:2048
	ds_read_b128 v[214:217], v199 offset:3072
	ds_read_b128 v[220:223], v199 offset:4096
	ds_read_b128 v[224:227], v199 offset:5120
	ds_read_b128 v[228:231], v199 offset:6144
	ds_read_b128 v[232:235], v199 offset:7168
	s_add_i32 s72, s72, 1
	s_mul_i32 s0, s72, s74
	s_mul_hi_u32 s1, s72, s75
	s_add_i32 s1, s1, s0
	s_mul_i32 s0, s72, s75
	s_add_u32 s2, s0, s16
	s_addc_u32 s3, s1, s14
	v_cmp_gt_i64_e32 vcc, s[2:3], v[180:181]
	v_cmp_lt_i64_e64 s[0:1], s[2:3], v[178:179]
	s_cbranch_vccnz .LBB0_643
	s_ashr_i32 s3, s2, 31
	s_lshr_b32 s3, s3, 29
	s_add_i32 s60, s2, s3
	s_and_b32 s3, s60, -8
	s_sub_i32 s61, s2, s3
	s_cmp_gt_i32 s61, -1
	s_mov_b64 s[2:3], -1
	s_cbranch_scc0 .LBB0_640
	s_lshl_b32 s62, s61, 6
	s_mov_b64 s[2:3], 0

; #define PG8_STAGE(bufoff, gbase, voff) do { _Pragma("unroll") for (int _i = 0; _i < 2; ++_i) \
;         __builtin_amdgcn_global_load_lds((const unsigned*)((const char*)(gbase) + (voff)[_i]), (PG8_LAS unsigned*)(lds + (bufoff) + ldsw + _i * 8192), 16, 0, 0); } while (0)
; #define PG8_LDA(dst, b, h) do { _Pragma("unroll") for (int m = 0; m < 4; ++m) _Pragma("unroll") for (int k = 0; k < 2; ++k) dst[m][k] = *(const PG8_LAS bf16x8*)(lds + PG8_SA(b, h) + aoff + m * 2048 + k * 1024); } while (0)
; #define PG8_LDB(dst, b, h) do { _Pragma("unroll") for (int n = 0; n < 2; ++n) _Pragma("unroll") for (int k = 0; k < 2; ++k) dst[n][k] = *(const PG8_LAS bf16x8*)(lds + PG8_SB(b, h) + boff + n * 2048 + k * 1024); } while (0)
; #define PG8_WAIT_V(n) asm volatile("s_waitcnt vmcnt(" #n ")" ::: "memory")
; #define PG8_WAIT_L(n) asm volatile("s_waitcnt lgkmcnt(" #n ")" ::: "memory")
; #define PG8_BAR __builtin_amdgcn_s_barrier()
; #define PG8_SCHED __builtin_amdgcn_sched_barrier(0)
; template <class Epi, class Sched, bool ALIGN_EPI = false, bool SP2 = false>
; __device__ __forceinline__ void gemm_phase(PG8_LAS unsigned char* lds, const Gemm g, const Sched& S, const Epi& E) {
;     ...
;         const char* nA = has_next ? (const char*)g.A + (size_t)nxt.pm * tstepA : cA; const char* nB = has_next ? (const char*)g.Bt + (size_t)nxt.pn * tstepB : cB;
;         for (int t = 0; t < nt; t += 2) {
;             const bool last = (t == nt - 2);
;             const char* a1 = cA + (size_t)(t + 1) * kstepA;
;             const char* a2 = last ? nA : cA + (size_t)(t + 2) * kstepA; const char* b2 = last ? nB : cB + (size_t)(t + 2) * kstep;
;             const char* a3 = a2 + kstepA; const char* b3 = b2 + kstep;
;             if (last && has_next) S.a_ready(nxt);
;             if constexpr (SP2) {
;             PG8_LDB(B0, 0, 0); PG8_LDB(B1, 0, 1); PG8_SCHED; PG8_LDA(At, 0, 0); PG8_STAGE(PG8_SA(1, 1), a1 + hstepA, voffA);
;             PG8_WAIT_V(8); PG8_WAIT_L(0); PG8_BAR; PG8_MMA(0, 0, At, B0); PG8_MMA(0, 1, At, B1); PG8_BAR; PG8_SCHED;
;             PG8_LDA(At, 0, 1); PG8_STAGE(PG8_SB(0, 0), b2, voffB); PG8_STAGE(PG8_SB(0, 1), b2 + hstepB, voffB); PG8_STAGE(PG8_SA(0, 0), a2, voffA);
;             PG8_WAIT_V(8); PG8_WAIT_L(0); PG8_BAR; PG8_MMA(1, 0, At, B0); PG8_MMA(1, 1, At, B1); PG8_BAR; PG8_SCHED;
.LBB0_645:
	s_ashr_i32 s61, s60, 31
	s_lshl_b64 s[8:9], s[60:61], 19
	s_add_u32 s64, s85, s8
	s_addc_u32 s65, s86, s9
	s_and_b64 s[0:1], s[0:1], exec
	s_cselect_b32 s61, s65, s67
	s_cselect_b32 s90, s64, s66
	s_add_u32 s91, s66, 0x10000
	s_addc_u32 s92, s67, 0
	s_add_u32 s0, s68, 0xf0080
	s_addc_u32 s1, s69, 0
	s_mov_b32 s68, -2
	s_add_u32 s8, s0, 0xfff10080
	s_addc_u32 s9, s1, -1
	s_cmp_eq_u32 s68, 12
	s_cselect_b32 s67, s63, s9
	s_cselect_b32 s66, s62, s8
	s_cselect_b32 s9, s61, s92
	s_cselect_b32 s8, s90, s91
	v_lshl_add_u64 v[236:237], s[0:1], 0, v[174:175]
	s_add_i32 m0, s17, 0xc000
	global_load_lds_dwordx4 v[236:237], off
	v_lshl_add_u64 v[236:237], s[0:1], 0, v[176:177]
	s_add_i32 m0, s17, 0xe000
	s_nop 0
	global_load_lds_dwordx4 v[236:237], off
	s_waitcnt vmcnt(8)
	s_waitcnt lgkmcnt(0)
	s_barrier
	s_waitcnt lgkmcnt(0)
	v_mfma_f32_16x16x32_bf16 v[124:127], v[128:131], v[202:205], 0
	v_mfma_f32_16x16x32_bf16 v[120:123], v[136:139], v[202:205], 0
	v_mfma_f32_16x16x32_bf16 v[108:111], v[128:131], v[210:213], 0
	v_mfma_f32_16x16x32_bf16 v[104:107], v[136:139], v[210:213], 0
	v_mfma_f32_16x16x32_bf16 v[96:99], v[128:131], v[220:223], 0
	v_mfma_f32_16x16x32_bf16 v[88:91], v[136:139], v[220:223], 0
	v_mfma_f32_16x16x32_bf16 v[80:83], v[128:131], v[228:231], 0
	v_mfma_f32_16x16x32_bf16 v[72:75], v[136:139], v[228:231], 0
	v_mfma_f32_16x16x32_bf16 v[124:127], v[132:135], v[206:209], v[124:127]
	v_mfma_f32_16x16x32_bf16 v[120:123], v[140:143], v[206:209], v[120:123]
	v_mfma_f32_16x16x32_bf16 v[108:111], v[132:135], v[214:217], v[108:111]
	v_mfma_f32_16x16x32_bf16 v[104:107], v[140:143], v[214:217], v[104:107]
	v_mfma_f32_16x16x32_bf16 v[96:99], v[132:135], v[224:227], v[96:99]
	v_mfma_f32_16x16x32_bf16 v[88:91], v[140:143], v[224:227], v[88:91]
	v_mfma_f32_16x16x32_bf16 v[80:83], v[132:135], v[232:235], v[80:83]
	v_mfma_f32_16x16x32_bf16 v[72:75], v[140:143], v[232:235], v[72:75]
	v_mfma_f32_16x16x32_bf16 v[116:119], v[144:147], v[202:205], 0
	v_mfma_f32_16x16x32_bf16 v[112:115], v[152:155], v[202:205], 0
	v_mfma_f32_16x16x32_bf16 v[100:103], v[144:147], v[210:213], 0
	v_mfma_f32_16x16x32_bf16 v[92:95], v[152:155], v[210:213], 0
	v_mfma_f32_16x16x32_bf16 v[84:87], v[144:147], v[220:223], 0
	v_mfma_f32_16x16x32_bf16 v[76:79], v[152:155], v[220:223], 0
	v_mfma_f32_16x16x32_bf16 v[68:71], v[144:147], v[228:231], 0
	v_mfma_f32_16x16x32_bf16 v[64:67], v[152:155], v[228:231], 0
	v_mfma_f32_16x16x32_bf16 v[116:119], v[148:151], v[206:209], v[116:119]
	v_mfma_f32_16x16x32_bf16 v[112:115], v[156:159], v[206:209], v[112:115]
	v_mfma_f32_16x16x32_bf16 v[100:103], v[148:151], v[214:217], v[100:103]
	v_mfma_f32_16x16x32_bf16 v[92:95], v[156:159], v[214:217], v[92:95]
	v_mfma_f32_16x16x32_bf16 v[84:87], v[148:151], v[224:227], v[84:87]
	v_mfma_f32_16x16x32_bf16 v[76:79], v[156:159], v[224:227], v[76:79]
	v_mfma_f32_16x16x32_bf16 v[68:71], v[148:151], v[232:235], v[68:71]
	v_mfma_f32_16x16x32_bf16 v[64:67], v[156:159], v[232:235], v[64:67]
	s_barrier
	v_lshl_add_u64 v[236:237], s[8:9], 0, v[190:191]
	s_add_i32 s8, s77, s15
	s_mov_b32 m0, s8
	ds_read_b128 v[202:205], v199 offset:16384
	ds_read_b128 v[206:209], v199 offset:17408
	ds_read_b128 v[210:213], v199 offset:18432
	ds_read_b128 v[214:217], v199 offset:19456
	ds_read_b128 v[220:223], v199 offset:20480
	ds_read_b128 v[224:227], v199 offset:21504
	ds_read_b128 v[228:231], v199 offset:22528
	ds_read_b128 v[232:235], v199 offset:23552
	global_load_lds_dwordx4 v[236:237], off
	v_lshl_add_u64 v[238:239], v[236:237], 0, s[36:37]
	s_add_i32 m0, s8, 0x2000
	s_add_i32 s8, s80, s15
	global_load_lds_dwordx4 v[238:239], off
	v_lshl_add_u64 v[238:239], v[236:237], 0, s[38:39]
	s_mov_b32 m0, s8
	v_lshl_add_u64 v[240:241], s[66:67], 0, v[162:163]
	global_load_lds_dwordx4 v[238:239], off
	v_lshl_add_u64 v[238:239], v[236:237], 0, s[40:41]
	s_add_i32 m0, s8, 0x2000
	s_nop 0
	global_load_lds_dwordx4 v[238:239], off
	v_lshl_add_u64 v[238:239], s[66:67], 0, v[160:161]
	s_mov_b32 m0, s17
	s_nop 0
	global_load_lds_dwordx4 v[238:239], off
	s_mov_b32 m0, s18
	s_nop 0
	global_load_lds_dwordx4 v[240:241], off
	s_waitcnt vmcnt(8)
	s_waitcnt lgkmcnt(0)
	s_barrier
	s_waitcnt lgkmcnt(0)
	v_mfma_f32_16x16x32_bf16 v[60:63], v[128:131], v[202:205], 0
	v_mfma_f32_16x16x32_bf16 v[56:59], v[136:139], v[202:205], 0
	v_mfma_f32_16x16x32_bf16 v[48:51], v[128:131], v[210:213], 0
	v_mfma_f32_16x16x32_bf16 v[40:43], v[136:139], v[210:213], 0
	v_mfma_f32_16x16x32_bf16 v[32:35], v[128:131], v[220:223], 0
	v_mfma_f32_16x16x32_bf16 v[24:27], v[136:139], v[220:223], 0
	v_mfma_f32_16x16x32_bf16 v[16:19], v[128:131], v[228:231], 0
	v_mfma_f32_16x16x32_bf16 v[8:11], v[136:139], v[228:231], 0
	v_mfma_f32_16x16x32_bf16 v[60:63], v[132:135], v[206:209], v[60:63]
	v_mfma_f32_16x16x32_bf16 v[56:59], v[140:143], v[206:209], v[56:59]
	v_mfma_f32_16x16x32_bf16 v[48:51], v[132:135], v[214:217], v[48:51]
	v_mfma_f32_16x16x32_bf16 v[40:43], v[140:143], v[214:217], v[40:43]
	v_mfma_f32_16x16x32_bf16 v[32:35], v[132:135], v[224:227], v[32:35]
	v_mfma_f32_16x16x32_bf16 v[24:27], v[140:143], v[224:227], v[24:27]
	v_mfma_f32_16x16x32_bf16 v[16:19], v[132:135], v[232:235], v[16:19]
	v_mfma_f32_16x16x32_bf16 v[8:11], v[140:143], v[232:235], v[8:11]
	v_mfma_f32_16x16x32_bf16 v[52:55], v[144:147], v[202:205], 0
	v_mfma_f32_16x16x32_bf16 v[44:47], v[152:155], v[202:205], 0
	v_mfma_f32_16x16x32_bf16 v[36:39], v[144:147], v[210:213], 0
	v_mfma_f32_16x16x32_bf16 v[28:31], v[152:155], v[210:213], 0
	v_mfma_f32_16x16x32_bf16 v[20:23], v[144:147], v[220:223], 0
	v_mfma_f32_16x16x32_bf16 v[12:15], v[152:155], v[220:223], 0
	v_mfma_f32_16x16x32_bf16 v[4:7], v[144:147], v[228:231], 0
	v_mfma_f32_16x16x32_bf16 v[0:3], v[152:155], v[228:231], 0
	v_mfma_f32_16x16x32_bf16 v[52:55], v[148:151], v[206:209], v[52:55]
	v_mfma_f32_16x16x32_bf16 v[44:47], v[156:159], v[206:209], v[44:47]
	v_mfma_f32_16x16x32_bf16 v[36:39], v[148:151], v[214:217], v[36:39]
	v_mfma_f32_16x16x32_bf16 v[28:31], v[156:159], v[214:217], v[28:31]
	v_mfma_f32_16x16x32_bf16 v[20:23], v[148:151], v[224:227], v[20:23]
	v_mfma_f32_16x16x32_bf16 v[12:15], v[156:159], v[224:227], v[12:15]
	v_mfma_f32_16x16x32_bf16 v[4:7], v[148:151], v[232:235], v[4:7]
	v_mfma_f32_16x16x32_bf16 v[0:3], v[156:159], v[232:235], v[0:3]
	s_barrier
; #define PG8_STAGE(bufoff, gbase, voff) do { _Pragma("unroll") for (int _i = 0; _i < 2; ++_i) \
;         __builtin_amdgcn_global_load_lds((const unsigned*)((const char*)(gbase) + (voff)[_i]), (PG8_LAS unsigned*)(lds + (bufoff) + ldsw + _i * 8192), 16, 0, 0); } while (0)
; #define PG8_LDA(dst, b, h) do { _Pragma("unroll") for (int m = 0; m < 4; ++m) _Pragma("unroll") for (int k = 0; k < 2; ++k) dst[m][k] = *(const PG8_LAS bf16x8*)(lds + PG8_SA(b, h) + aoff + m * 2048 + k * 1024); } while (0)
; #define PG8_LDB(dst, b, h) do { _Pragma("unroll") for (int n = 0; n < 2; ++n) _Pragma("unroll") for (int k = 0; k < 2; ++k) dst[n][k] = *(const PG8_LAS bf16x8*)(lds + PG8_SB(b, h) + boff + n * 2048 + k * 1024); } while (0)
; #define PG8_MMA(ai, bj, At, Bt) do { __builtin_amdgcn_s_setprio(1); _Pragma("unroll") for (int m = 0; m < 4; ++m) _Pragma("unroll") for (int n = 0; n < 2; ++n) _Pragma("unroll") for (int k = 0; k < 2; ++k) \
;         acc[ai][bj][m][n] = __builtin_amdgcn_mfma_f32_16x16x32_bf16(Bt[n][k], At[m][k], acc[ai][bj][m][n], 0, 0, 0); __builtin_amdgcn_s_setprio(0); } while (0)
; #define PG8_WAIT_V(n) asm volatile("s_waitcnt vmcnt(" #n ")" ::: "memory")
; #define PG8_WAIT_L(n) asm volatile("s_waitcnt lgkmcnt(" #n ")" ::: "memory")
; #define PG8_BAR __builtin_amdgcn_s_barrier()
; #define PG8_SCHED __builtin_amdgcn_sched_barrier(0)
; template <class Epi, class Sched, bool ALIGN_EPI = false, bool SP2 = false>
; __device__ __forceinline__ void gemm_phase(PG8_LAS unsigned char* lds, const Gemm g, const Sched& S, const Epi& E) {
;     ...
;             PG8_LDB(B0, 1, 0); PG8_LDB(B1, 1, 1); PG8_SCHED; PG8_LDA(At, 1, 0); PG8_STAGE(PG8_SA(0, 1), a2 + hstepA, voffA);
;             PG8_WAIT_V(8); PG8_WAIT_L(0); PG8_BAR; PG8_MMA(0, 0, At, B0); PG8_MMA(0, 1, At, B1); PG8_BAR; PG8_SCHED;
;             PG8_LDA(At, 1, 1); PG8_STAGE(PG8_SB(1, 0), b3, voffB); PG8_STAGE(PG8_SB(1, 1), b3 + hstepB, voffB); PG8_STAGE(PG8_SA(1, 0), a3, voffA);
;             PG8_WAIT_V(8); PG8_WAIT_L(0); PG8_BAR; PG8_MMA(1, 0, At, B0); PG8_MMA(1, 1, At, B1); PG8_BAR; PG8_SCHED;
	ds_read_b128 v[128:131], v200
	ds_read_b128 v[132:135], v200 offset:1024
	ds_read_b128 v[136:139], v200 offset:2048
	ds_read_b128 v[140:143], v200 offset:3072
	ds_read_b128 v[144:147], v201
	ds_read_b128 v[148:151], v201 offset:1024
	ds_read_b128 v[152:155], v201 offset:2048
	ds_read_b128 v[156:159], v201 offset:3072
	s_add_u32 s8, s66, 0xf0000
	s_addc_u32 s9, s67, 0
	s_mov_b32 m0, s19
	v_lshl_add_u64 v[242:243], s[8:9], 0, v[160:161]
	ds_read_b128 v[202:205], v199 offset:32768
	ds_read_b128 v[206:209], v199 offset:33792
	ds_read_b128 v[210:213], v199 offset:34816
	ds_read_b128 v[214:217], v199 offset:35840
	ds_read_b128 v[220:223], v199 offset:36864
	ds_read_b128 v[224:227], v199 offset:37888
	ds_read_b128 v[228:231], v199 offset:38912
	ds_read_b128 v[232:235], v199 offset:39936
	global_load_lds_dwordx4 v[242:243], off
	v_lshl_add_u64 v[242:243], s[8:9], 0, v[162:163]
	s_mov_b32 m0, s59
	s_nop 0
	global_load_lds_dwordx4 v[242:243], off
	s_waitcnt vmcnt(8)
	s_waitcnt lgkmcnt(0)
	s_barrier
	s_waitcnt lgkmcnt(0)
	v_mfma_f32_16x16x32_bf16 v[124:127], v[128:131], v[202:205], v[124:127]
	v_mfma_f32_16x16x32_bf16 v[120:123], v[136:139], v[202:205], v[120:123]
	v_mfma_f32_16x16x32_bf16 v[108:111], v[128:131], v[210:213], v[108:111]
	v_mfma_f32_16x16x32_bf16 v[104:107], v[136:139], v[210:213], v[104:107]
	v_mfma_f32_16x16x32_bf16 v[96:99], v[128:131], v[220:223], v[96:99]
	v_mfma_f32_16x16x32_bf16 v[88:91], v[136:139], v[220:223], v[88:91]
	v_mfma_f32_16x16x32_bf16 v[80:83], v[128:131], v[228:231], v[80:83]
	v_mfma_f32_16x16x32_bf16 v[72:75], v[136:139], v[228:231], v[72:75]
	v_mfma_f32_16x16x32_bf16 v[124:127], v[132:135], v[206:209], v[124:127]
	v_mfma_f32_16x16x32_bf16 v[120:123], v[140:143], v[206:209], v[120:123]
	v_mfma_f32_16x16x32_bf16 v[108:111], v[132:135], v[214:217], v[108:111]
	v_mfma_f32_16x16x32_bf16 v[104:107], v[140:143], v[214:217], v[104:107]
	v_mfma_f32_16x16x32_bf16 v[96:99], v[132:135], v[224:227], v[96:99]
	v_mfma_f32_16x16x32_bf16 v[88:91], v[140:143], v[224:227], v[88:91]
	v_mfma_f32_16x16x32_bf16 v[80:83], v[132:135], v[232:235], v[80:83]
	v_mfma_f32_16x16x32_bf16 v[72:75], v[140:143], v[232:235], v[72:75]
	v_mfma_f32_16x16x32_bf16 v[116:119], v[144:147], v[202:205], v[116:119]
	v_mfma_f32_16x16x32_bf16 v[112:115], v[152:155], v[202:205], v[112:115]
	v_mfma_f32_16x16x32_bf16 v[100:103], v[144:147], v[210:213], v[100:103]
	v_mfma_f32_16x16x32_bf16 v[92:95], v[152:155], v[210:213], v[92:95]
	v_mfma_f32_16x16x32_bf16 v[84:87], v[144:147], v[220:223], v[84:87]
	v_mfma_f32_16x16x32_bf16 v[76:79], v[152:155], v[220:223], v[76:79]
	v_mfma_f32_16x16x32_bf16 v[68:71], v[144:147], v[228:231], v[68:71]
	v_mfma_f32_16x16x32_bf16 v[64:67], v[152:155], v[228:231], v[64:67]
	v_mfma_f32_16x16x32_bf16 v[116:119], v[148:151], v[206:209], v[116:119]
	v_mfma_f32_16x16x32_bf16 v[112:115], v[156:159], v[206:209], v[112:115]
	v_mfma_f32_16x16x32_bf16 v[100:103], v[148:151], v[214:217], v[100:103]
	v_mfma_f32_16x16x32_bf16 v[92:95], v[156:159], v[214:217], v[92:95]
	v_mfma_f32_16x16x32_bf16 v[84:87], v[148:151], v[224:227], v[84:87]
	v_mfma_f32_16x16x32_bf16 v[76:79], v[156:159], v[224:227], v[76:79]
	v_mfma_f32_16x16x32_bf16 v[68:71], v[148:151], v[232:235], v[68:71]
	v_mfma_f32_16x16x32_bf16 v[64:67], v[156:159], v[232:235], v[64:67]
	s_barrier
	s_add_i32 s8, s81, s15
	v_lshl_add_u64 v[242:243], v[236:237], 0, s[42:43]
	s_mov_b32 m0, s8
	ds_read_b128 v[202:205], v199 offset:49152
	ds_read_b128 v[206:209], v199 offset:50176
	ds_read_b128 v[210:213], v199 offset:51200
	ds_read_b128 v[214:217], v199 offset:52224
	ds_read_b128 v[220:223], v199 offset:53248
	ds_read_b128 v[224:227], v199 offset:54272
	ds_read_b128 v[228:231], v199 offset:55296
	ds_read_b128 v[232:235], v199 offset:56320
	global_load_lds_dwordx4 v[242:243], off
	v_lshl_add_u64 v[242:243], v[236:237], 0, s[44:45]
	s_add_i32 m0, s8, 0x2000
	s_add_i32 s8, s82, s15
	global_load_lds_dwordx4 v[242:243], off
	v_lshl_add_u64 v[242:243], v[236:237], 0, s[48:49]
	s_mov_b32 m0, s8
	v_lshl_add_u64 v[236:237], v[236:237], 0, s[52:53]
	global_load_lds_dwordx4 v[242:243], off
	s_add_i32 m0, s8, 0x2000
	s_nop 0
	global_load_lds_dwordx4 v[236:237], off
	v_lshl_add_u64 v[236:237], v[238:239], 0, s[46:47]
	s_mov_b32 m0, s70
	s_nop 0
	global_load_lds_dwordx4 v[236:237], off
	v_lshl_add_u64 v[236:237], v[240:241], 0, s[46:47]
	s_mov_b32 m0, s71
	s_nop 0
	global_load_lds_dwordx4 v[236:237], off
	s_waitcnt vmcnt(8)
	s_waitcnt lgkmcnt(0)
	s_barrier
	s_waitcnt lgkmcnt(0)
	v_mfma_f32_16x16x32_bf16 v[60:63], v[128:131], v[202:205], v[60:63]
	v_mfma_f32_16x16x32_bf16 v[56:59], v[136:139], v[202:205], v[56:59]
	v_mfma_f32_16x16x32_bf16 v[48:51], v[128:131], v[210:213], v[48:51]
	v_mfma_f32_16x16x32_bf16 v[40:43], v[136:139], v[210:213], v[40:43]
	v_mfma_f32_16x16x32_bf16 v[32:35], v[128:131], v[220:223], v[32:35]
	v_mfma_f32_16x16x32_bf16 v[24:27], v[136:139], v[220:223], v[24:27]
	v_mfma_f32_16x16x32_bf16 v[16:19], v[128:131], v[228:231], v[16:19]
	v_mfma_f32_16x16x32_bf16 v[8:11], v[136:139], v[228:231], v[8:11]
	v_mfma_f32_16x16x32_bf16 v[60:63], v[132:135], v[206:209], v[60:63]
	v_mfma_f32_16x16x32_bf16 v[56:59], v[140:143], v[206:209], v[56:59]
	v_mfma_f32_16x16x32_bf16 v[48:51], v[132:135], v[214:217], v[48:51]
	v_mfma_f32_16x16x32_bf16 v[40:43], v[140:143], v[214:217], v[40:43]
	v_mfma_f32_16x16x32_bf16 v[32:35], v[132:135], v[224:227], v[32:35]
	v_mfma_f32_16x16x32_bf16 v[24:27], v[140:143], v[224:227], v[24:27]
	v_mfma_f32_16x16x32_bf16 v[16:19], v[132:135], v[232:235], v[16:19]
	v_mfma_f32_16x16x32_bf16 v[8:11], v[140:143], v[232:235], v[8:11]
	v_mfma_f32_16x16x32_bf16 v[52:55], v[144:147], v[202:205], v[52:55]
	v_mfma_f32_16x16x32_bf16 v[44:47], v[152:155], v[202:205], v[44:47]
	v_mfma_f32_16x16x32_bf16 v[36:39], v[144:147], v[210:213], v[36:39]
	v_mfma_f32_16x16x32_bf16 v[28:31], v[152:155], v[210:213], v[28:31]
	v_mfma_f32_16x16x32_bf16 v[20:23], v[144:147], v[220:223], v[20:23]
	v_mfma_f32_16x16x32_bf16 v[12:15], v[152:155], v[220:223], v[12:15]
	v_mfma_f32_16x16x32_bf16 v[4:7], v[144:147], v[228:231], v[4:7]
	v_mfma_f32_16x16x32_bf16 v[0:3], v[152:155], v[228:231], v[0:3]
	v_mfma_f32_16x16x32_bf16 v[52:55], v[148:151], v[206:209], v[52:55]
	v_mfma_f32_16x16x32_bf16 v[44:47], v[156:159], v[206:209], v[44:47]
	v_mfma_f32_16x16x32_bf16 v[36:39], v[148:151], v[214:217], v[36:39]
	v_mfma_f32_16x16x32_bf16 v[28:31], v[156:159], v[214:217], v[28:31]
	v_mfma_f32_16x16x32_bf16 v[20:23], v[148:151], v[224:227], v[20:23]
	v_mfma_f32_16x16x32_bf16 v[12:15], v[156:159], v[224:227], v[12:15]
	v_mfma_f32_16x16x32_bf16 v[4:7], v[148:151], v[232:235], v[4:7]
	v_mfma_f32_16x16x32_bf16 v[0:3], v[156:159], v[232:235], v[0:3]
	s_barrier
	s_add_i32 s68, s68, 2
	s_add_u32 s91, s91, 0x10000
	s_addc_u32 s92, s92, 0
	s_add_u32 s0, s0, 0x100
	s_addc_u32 s1, s1, 0
	s_cmp_gt_u32 s68, 13

; #define PG8_STAGE(bufoff, gbase, voff) do { _Pragma("unroll") for (int _i = 0; _i < 2; ++_i) \
;         __builtin_amdgcn_global_load_lds((const unsigned*)((const char*)(gbase) + (voff)[_i]), (PG8_LAS unsigned*)(lds + (bufoff) + ldsw + _i * 8192), 16, 0, 0); } while (0)
; #define PG8_LDA(dst, b, h) do { _Pragma("unroll") for (int m = 0; m < 4; ++m) _Pragma("unroll") for (int k = 0; k < 2; ++k) dst[m][k] = *(const PG8_LAS bf16x8*)(lds + PG8_SA(b, h) + aoff + m * 2048 + k * 1024); } while (0)
; #define PG8_LDB(dst, b, h) do { _Pragma("unroll") for (int n = 0; n < 2; ++n) _Pragma("unroll") for (int k = 0; k < 2; ++k) dst[n][k] = *(const PG8_LAS bf16x8*)(lds + PG8_SB(b, h) + boff + n * 2048 + k * 1024); } while (0)
; #define PG8_SCHED __builtin_amdgcn_sched_barrier(0)
;     __host__ __device__ bool next(int i, Unit& u) const {
;         const long L = (long)i * G + c; if (L >= nwg) return false;
;         int wgid = (int)L; { const int q = nwg / NXCD, r = nwg % NXCD, xcd = wgid % NXCD, off = wgid / NXCD; wgid = (xcd < r ? xcd * (q + 1) : r * (q + 1) + (xcd - r) * q) + off; }
;         const int nig = wgm * nN, gid = wgid / nig, fm = gid * wgm, gsz = (nM - fm) < wgm ? (nM - fm) : wgm;
;         u.pm = fm + ((wgid % nig) % gsz); u.pn = (wgid % nig) / gsz; return true;
; template <class Epi, class Sched, bool ALIGN_EPI = false, bool SP2 = false>
; __device__ __forceinline__ void gemm_phase(PG8_LAS unsigned char* lds, const Gemm g, const Sched& S, const Epi& E) {
;     ...
;         const bool has_next = S.next(ui + 1, nxt);
;         const char* nA = has_next ? (const char*)g.A + (size_t)nxt.pm * tstepA : cA; const char* nB = has_next ? (const char*)g.Bt + (size_t)nxt.pn * tstepB : cB;
;         for (int t = 0; t < nt; t += 2) {
;             const bool last = (t == nt - 2);
;             const char* a1 = cA + (size_t)(t + 1) * kstepA;
;             const char* a2 = last ? nA : cA + (size_t)(t + 2) * kstepA; const char* b2 = last ? nB : cB + (size_t)(t + 2) * kstep;
;             const char* a3 = a2 + kstepA; const char* b3 = b2 + kstep;
;             if (last && has_next) S.a_ready(nxt);
;             if constexpr (SP2) {
;             PG8_LDB(B0, 0, 0); PG8_LDB(B1, 0, 1); PG8_SCHED; PG8_LDA(At, 0, 0); PG8_STAGE(PG8_SA(1, 1), a1 + hstepA, voffA);
.LBB0_663:
	ds_read_b128 v[108:111], v200
	ds_read_b128 v[132:135], v200 offset:1024
	ds_read_b128 v[136:139], v200 offset:2048
	ds_read_b128 v[140:143], v200 offset:3072
	ds_read_b128 v[144:147], v201
	ds_read_b128 v[148:151], v201 offset:1024
	ds_read_b128 v[152:155], v201 offset:2048
	ds_read_b128 v[156:159], v201 offset:3072
	ds_read_b128 v[160:163], v202
	ds_read_b128 v[164:167], v202 offset:1024
	ds_read_b128 v[168:171], v202 offset:2048
	ds_read_b128 v[204:207], v202 offset:3072
	ds_read_b128 v[208:211], v202 offset:4096
	ds_read_b128 v[212:215], v202 offset:5120
	ds_read_b128 v[220:223], v202 offset:6144
	ds_read_b128 v[224:227], v202 offset:7168
	s_add_i32 s73, s73, 1
	s_mul_i32 s2, s73, s75
	s_mul_hi_u32 s3, s73, s76
	s_add_i32 s3, s3, s2
	s_mul_i32 s2, s73, s76
	s_add_u32 s58, s2, s16
	s_addc_u32 s59, s3, s14
	v_cmp_gt_i64_e32 vcc, s[58:59], v[196:197]
	v_cmp_lt_i64_e64 s[2:3], s[58:59], v[194:195]
	s_cbranch_vccnz .LBB0_669
	s_ashr_i32 s8, s58, 31
	s_lshr_b32 s8, s8, 29
	s_add_i32 s56, s58, s8
	s_and_b32 s8, s56, -8
	s_sub_i32 s57, s58, s8
	s_cmp_gt_i32 s57, -1
	s_mov_b64 s[54:55], -1
	s_cbranch_scc0 .LBB0_666
	s_lshl_b32 s58, s57, 6
	s_mov_b64 s[54:55], 0

; #define PG8_STAGE(bufoff, gbase, voff) do { _Pragma("unroll") for (int _i = 0; _i < 2; ++_i) \
;         __builtin_amdgcn_global_load_lds((const unsigned*)((const char*)(gbase) + (voff)[_i]), (PG8_LAS unsigned*)(lds + (bufoff) + ldsw + _i * 8192), 16, 0, 0); } while (0)
; #define PG8_LDA(dst, b, h) do { _Pragma("unroll") for (int m = 0; m < 4; ++m) _Pragma("unroll") for (int k = 0; k < 2; ++k) dst[m][k] = *(const PG8_LAS bf16x8*)(lds + PG8_SA(b, h) + aoff + m * 2048 + k * 1024); } while (0)
; #define PG8_LDB(dst, b, h) do { _Pragma("unroll") for (int n = 0; n < 2; ++n) _Pragma("unroll") for (int k = 0; k < 2; ++k) dst[n][k] = *(const PG8_LAS bf16x8*)(lds + PG8_SB(b, h) + boff + n * 2048 + k * 1024); } while (0)
; #define PG8_WAIT_V(n) asm volatile("s_waitcnt vmcnt(" #n ")" ::: "memory")
; #define PG8_WAIT_L(n) asm volatile("s_waitcnt lgkmcnt(" #n ")" ::: "memory")
; #define PG8_BAR __builtin_amdgcn_s_barrier()
; #define PG8_SCHED __builtin_amdgcn_sched_barrier(0)
; template <class Epi, class Sched, bool ALIGN_EPI = false, bool SP2 = false>
; __device__ __forceinline__ void gemm_phase(PG8_LAS unsigned char* lds, const Gemm g, const Sched& S, const Epi& E) {
;     ...
;         const char* nA = has_next ? (const char*)g.A + (size_t)nxt.pm * tstepA : cA; const char* nB = has_next ? (const char*)g.Bt + (size_t)nxt.pn * tstepB : cB;
;         for (int t = 0; t < nt; t += 2) {
;             const bool last = (t == nt - 2);
;             const char* a1 = cA + (size_t)(t + 1) * kstepA;
;             const char* a2 = last ? nA : cA + (size_t)(t + 2) * kstepA; const char* b2 = last ? nB : cB + (size_t)(t + 2) * kstep;
;             const char* a3 = a2 + kstepA; const char* b3 = b2 + kstep;
;             if (last && has_next) S.a_ready(nxt);
;             if constexpr (SP2) {
;             PG8_LDB(B0, 0, 0); PG8_LDB(B1, 0, 1); PG8_SCHED; PG8_LDA(At, 0, 0); PG8_STAGE(PG8_SA(1, 1), a1 + hstepA, voffA);
;             PG8_WAIT_V(8); PG8_WAIT_L(0); PG8_BAR; PG8_MMA(0, 0, At, B0); PG8_MMA(0, 1, At, B1); PG8_BAR; PG8_SCHED;
;             PG8_LDA(At, 0, 1); PG8_STAGE(PG8_SB(0, 0), b2, voffB); PG8_STAGE(PG8_SB(0, 1), b2 + hstepB, voffB); PG8_STAGE(PG8_SA(0, 0), a2, voffA);
;             PG8_WAIT_V(8); PG8_WAIT_L(0); PG8_BAR; PG8_MMA(1, 0, At, B0); PG8_MMA(1, 1, At, B1); PG8_BAR; PG8_SCHED;
.LBB0_669:
	s_ashr_i32 s57, s56, 31
	s_lshl_b64 s[8:9], s[56:57], 18
	s_add_u32 s58, s30, s8
	s_addc_u32 s59, s31, s9
	s_and_b64 s[8:9], s[2:3], exec
	s_cselect_b32 s57, s59, s67
	s_cselect_b32 s68, s58, s66
	s_ashr_i32 s55, s54, 31
	s_lshl_b64 s[8:9], s[54:55], 18
	v_readlane_b32 s60, v246, 7
	v_readlane_b32 s61, v246, 8
	s_add_u32 s60, s60, s8
	s_addc_u32 s61, s61, s9
	s_and_b64 s[8:9], s[2:3], exec
	s_cselect_b32 s55, s61, s65
	s_cselect_b32 s69, s60, s64
	s_add_u32 s82, s64, 0x10000
	s_addc_u32 s85, s65, 0
	s_add_u32 s64, s66, 0x20080
	s_addc_u32 s65, s67, 0
	s_mov_b32 s86, -2
	s_add_u32 s8, s64, 0xfffe0080
	s_addc_u32 s9, s65, -1
	s_cmp_eq_u32 s86, 4
	s_cselect_b32 s67, s57, s9
	s_cselect_b32 s66, s68, s8
	s_cselect_b32 s9, s55, s85
	s_cselect_b32 s8, s69, s82
	v_lshl_add_u64 v[216:217], s[64:65], 0, v[186:187]
	s_add_i32 m0, s17, 0xc000
	global_load_lds_dwordx4 v[216:217], off
	v_lshl_add_u64 v[216:217], s[64:65], 0, v[192:193]
	s_add_i32 m0, s17, 0xe000
	s_nop 0
	global_load_lds_dwordx4 v[216:217], off
	s_waitcnt vmcnt(8)
	s_waitcnt lgkmcnt(0)
	s_barrier
	s_waitcnt lgkmcnt(0)
	v_mfma_f32_16x16x32_bf16 v[128:131], v[108:111], v[160:163], 0
	v_mfma_f32_16x16x32_bf16 v[124:127], v[136:139], v[160:163], 0
	v_mfma_f32_16x16x32_bf16 v[112:115], v[108:111], v[168:171], 0
	v_mfma_f32_16x16x32_bf16 v[104:107], v[136:139], v[168:171], 0
	v_mfma_f32_16x16x32_bf16 v[92:95], v[108:111], v[208:211], 0
	v_mfma_f32_16x16x32_bf16 v[88:91], v[136:139], v[208:211], 0
	v_mfma_f32_16x16x32_bf16 v[76:79], v[108:111], v[220:223], 0
	v_mfma_f32_16x16x32_bf16 v[72:75], v[136:139], v[220:223], 0
	v_mfma_f32_16x16x32_bf16 v[128:131], v[132:135], v[164:167], v[128:131]
	v_mfma_f32_16x16x32_bf16 v[124:127], v[140:143], v[164:167], v[124:127]
	v_mfma_f32_16x16x32_bf16 v[112:115], v[132:135], v[204:207], v[112:115]
	v_mfma_f32_16x16x32_bf16 v[104:107], v[140:143], v[204:207], v[104:107]
	v_mfma_f32_16x16x32_bf16 v[92:95], v[132:135], v[212:215], v[92:95]
	v_mfma_f32_16x16x32_bf16 v[88:91], v[140:143], v[212:215], v[88:91]
	v_mfma_f32_16x16x32_bf16 v[76:79], v[132:135], v[224:227], v[76:79]
	v_mfma_f32_16x16x32_bf16 v[72:75], v[140:143], v[224:227], v[72:75]
	v_mfma_f32_16x16x32_bf16 v[120:123], v[144:147], v[160:163], 0
	v_mfma_f32_16x16x32_bf16 v[116:119], v[152:155], v[160:163], 0
	v_mfma_f32_16x16x32_bf16 v[100:103], v[144:147], v[168:171], 0
	v_mfma_f32_16x16x32_bf16 v[96:99], v[152:155], v[168:171], 0
	v_mfma_f32_16x16x32_bf16 v[84:87], v[144:147], v[208:211], 0
	v_mfma_f32_16x16x32_bf16 v[80:83], v[152:155], v[208:211], 0
	v_mfma_f32_16x16x32_bf16 v[68:71], v[144:147], v[220:223], 0
	v_mfma_f32_16x16x32_bf16 v[64:67], v[152:155], v[220:223], 0
	v_mfma_f32_16x16x32_bf16 v[120:123], v[148:151], v[164:167], v[120:123]
	v_mfma_f32_16x16x32_bf16 v[116:119], v[156:159], v[164:167], v[116:119]
	v_mfma_f32_16x16x32_bf16 v[100:103], v[148:151], v[204:207], v[100:103]
	v_mfma_f32_16x16x32_bf16 v[96:99], v[156:159], v[204:207], v[96:99]
	v_mfma_f32_16x16x32_bf16 v[84:87], v[148:151], v[212:215], v[84:87]
	v_mfma_f32_16x16x32_bf16 v[80:83], v[156:159], v[212:215], v[80:83]
	v_mfma_f32_16x16x32_bf16 v[68:71], v[148:151], v[224:227], v[68:71]
	v_mfma_f32_16x16x32_bf16 v[64:67], v[156:159], v[224:227], v[64:67]
	s_barrier
	v_lshl_add_u64 v[216:217], s[8:9], 0, v[190:191]
	s_add_i32 s8, s11, s15
	s_mov_b32 m0, s8
	ds_read_b128 v[160:163], v202 offset:16384
	ds_read_b128 v[164:167], v202 offset:17408
	ds_read_b128 v[168:171], v202 offset:18432
	ds_read_b128 v[204:207], v202 offset:19456
	ds_read_b128 v[208:211], v202 offset:20480
	ds_read_b128 v[212:215], v202 offset:21504
	ds_read_b128 v[220:223], v202 offset:22528
	ds_read_b128 v[224:227], v202 offset:23552
	global_load_lds_dwordx4 v[216:217], off
	v_lshl_add_u64 v[228:229], v[216:217], 0, s[0:1]
	s_add_i32 m0, s8, 0x2000
	s_add_i32 s8, s80, s15
	global_load_lds_dwordx4 v[228:229], off
	v_lshl_add_u64 v[228:229], v[216:217], 0, s[34:35]
	s_mov_b32 m0, s8
	v_lshl_add_u64 v[230:231], s[66:67], 0, v[174:175]
	global_load_lds_dwordx4 v[228:229], off
	v_lshl_add_u64 v[228:229], v[216:217], 0, s[36:37]
	s_add_i32 m0, s8, 0x2000
	s_nop 0
	global_load_lds_dwordx4 v[228:229], off
	v_lshl_add_u64 v[228:229], s[66:67], 0, v[172:173]
	s_mov_b32 m0, s17
	s_nop 0
	global_load_lds_dwordx4 v[228:229], off
	s_mov_b32 m0, s18
	s_nop 0
	global_load_lds_dwordx4 v[230:231], off
	s_waitcnt vmcnt(8)
	s_waitcnt lgkmcnt(0)
	s_barrier
	s_waitcnt lgkmcnt(0)
	v_mfma_f32_16x16x32_bf16 v[60:63], v[108:111], v[160:163], 0
	v_mfma_f32_16x16x32_bf16 v[56:59], v[136:139], v[160:163], 0
	v_mfma_f32_16x16x32_bf16 v[44:47], v[108:111], v[168:171], 0
	v_mfma_f32_16x16x32_bf16 v[40:43], v[136:139], v[168:171], 0
	v_mfma_f32_16x16x32_bf16 v[28:31], v[108:111], v[208:211], 0
	v_mfma_f32_16x16x32_bf16 v[24:27], v[136:139], v[208:211], 0
	v_mfma_f32_16x16x32_bf16 v[12:15], v[108:111], v[220:223], 0
	v_mfma_f32_16x16x32_bf16 v[8:11], v[136:139], v[220:223], 0
	v_mfma_f32_16x16x32_bf16 v[60:63], v[132:135], v[164:167], v[60:63]
	v_mfma_f32_16x16x32_bf16 v[56:59], v[140:143], v[164:167], v[56:59]
	v_mfma_f32_16x16x32_bf16 v[44:47], v[132:135], v[204:207], v[44:47]
	v_mfma_f32_16x16x32_bf16 v[40:43], v[140:143], v[204:207], v[40:43]
	v_mfma_f32_16x16x32_bf16 v[28:31], v[132:135], v[212:215], v[28:31]
	v_mfma_f32_16x16x32_bf16 v[24:27], v[140:143], v[212:215], v[24:27]
	v_mfma_f32_16x16x32_bf16 v[12:15], v[132:135], v[224:227], v[12:15]
	v_mfma_f32_16x16x32_bf16 v[8:11], v[140:143], v[224:227], v[8:11]
	v_mfma_f32_16x16x32_bf16 v[52:55], v[144:147], v[160:163], 0
	v_mfma_f32_16x16x32_bf16 v[48:51], v[152:155], v[160:163], 0
	v_mfma_f32_16x16x32_bf16 v[36:39], v[144:147], v[168:171], 0
	v_mfma_f32_16x16x32_bf16 v[32:35], v[152:155], v[168:171], 0
	v_mfma_f32_16x16x32_bf16 v[20:23], v[144:147], v[208:211], 0
	v_mfma_f32_16x16x32_bf16 v[16:19], v[152:155], v[208:211], 0
	v_mfma_f32_16x16x32_bf16 v[4:7], v[144:147], v[220:223], 0
	v_mfma_f32_16x16x32_bf16 v[0:3], v[152:155], v[220:223], 0
	v_mfma_f32_16x16x32_bf16 v[52:55], v[148:151], v[164:167], v[52:55]
	v_mfma_f32_16x16x32_bf16 v[48:51], v[156:159], v[164:167], v[48:51]
	v_mfma_f32_16x16x32_bf16 v[36:39], v[148:151], v[204:207], v[36:39]
	v_mfma_f32_16x16x32_bf16 v[32:35], v[156:159], v[204:207], v[32:35]
	v_mfma_f32_16x16x32_bf16 v[20:23], v[148:151], v[212:215], v[20:23]
	v_mfma_f32_16x16x32_bf16 v[16:19], v[156:159], v[212:215], v[16:19]
	v_mfma_f32_16x16x32_bf16 v[4:7], v[148:151], v[224:227], v[4:7]
	v_mfma_f32_16x16x32_bf16 v[0:3], v[156:159], v[224:227], v[0:3]
	s_barrier
; #define PG8_STAGE(bufoff, gbase, voff) do { _Pragma("unroll") for (int _i = 0; _i < 2; ++_i) \
;         __builtin_amdgcn_global_load_lds((const unsigned*)((const char*)(gbase) + (voff)[_i]), (PG8_LAS unsigned*)(lds + (bufoff) + ldsw + _i * 8192), 16, 0, 0); } while (0)
; #define PG8_LDA(dst, b, h) do { _Pragma("unroll") for (int m = 0; m < 4; ++m) _Pragma("unroll") for (int k = 0; k < 2; ++k) dst[m][k] = *(const PG8_LAS bf16x8*)(lds + PG8_SA(b, h) + aoff + m * 2048 + k * 1024); } while (0)
; #define PG8_LDB(dst, b, h) do { _Pragma("unroll") for (int n = 0; n < 2; ++n) _Pragma("unroll") for (int k = 0; k < 2; ++k) dst[n][k] = *(const PG8_LAS bf16x8*)(lds + PG8_SB(b, h) + boff + n * 2048 + k * 1024); } while (0)
; #define PG8_MMA(ai, bj, At, Bt) do { __builtin_amdgcn_s_setprio(1); _Pragma("unroll") for (int m = 0; m < 4; ++m) _Pragma("unroll") for (int n = 0; n < 2; ++n) _Pragma("unroll") for (int k = 0; k < 2; ++k) \
;         acc[ai][bj][m][n] = __builtin_amdgcn_mfma_f32_16x16x32_bf16(Bt[n][k], At[m][k], acc[ai][bj][m][n], 0, 0, 0); __builtin_amdgcn_s_setprio(0); } while (0)
; #define PG8_WAIT_V(n) asm volatile("s_waitcnt vmcnt(" #n ")" ::: "memory")
; #define PG8_WAIT_L(n) asm volatile("s_waitcnt lgkmcnt(" #n ")" ::: "memory")
; #define PG8_BAR __builtin_amdgcn_s_barrier()
; #define PG8_SCHED __builtin_amdgcn_sched_barrier(0)
; template <class Epi, class Sched, bool ALIGN_EPI = false, bool SP2 = false>
; __device__ __forceinline__ void gemm_phase(PG8_LAS unsigned char* lds, const Gemm g, const Sched& S, const Epi& E) {
;     ...
;             PG8_LDB(B0, 1, 0); PG8_LDB(B1, 1, 1); PG8_SCHED; PG8_LDA(At, 1, 0); PG8_STAGE(PG8_SA(0, 1), a2 + hstepA, voffA);
;             PG8_WAIT_V(8); PG8_WAIT_L(0); PG8_BAR; PG8_MMA(0, 0, At, B0); PG8_MMA(0, 1, At, B1); PG8_BAR; PG8_SCHED;
;             PG8_LDA(At, 1, 1); PG8_STAGE(PG8_SB(1, 0), b3, voffB); PG8_STAGE(PG8_SB(1, 1), b3 + hstepB, voffB); PG8_STAGE(PG8_SA(1, 0), a3, voffA);
;             PG8_WAIT_V(8); PG8_WAIT_L(0); PG8_BAR; PG8_MMA(1, 0, At, B0); PG8_MMA(1, 1, At, B1); PG8_BAR; PG8_SCHED;
	s_add_i32 s78, 0, 0x1c000
	v_add_u32_e32 v156, s78, v199
	ds_read_b128 v[108:111], v203
	ds_read_b128 v[132:135], v203 offset:1024
	ds_read_b128 v[136:139], v203 offset:2048
	ds_read_b128 v[140:143], v203 offset:3072
	ds_read_b128 v[144:147], v156
	ds_read_b128 v[148:151], v156 offset:1024
	ds_read_b128 v[152:155], v156 offset:2048
	ds_read_b128 v[156:159], v156 offset:3072
	s_add_u32 s8, s66, 0x20000
	s_addc_u32 s9, s67, 0
	s_mov_b32 m0, s19
	v_lshl_add_u64 v[232:233], s[8:9], 0, v[172:173]
	ds_read_b128 v[160:163], v202 offset:32768
	ds_read_b128 v[164:167], v202 offset:33792
	ds_read_b128 v[168:171], v202 offset:34816
	ds_read_b128 v[204:207], v202 offset:35840
	ds_read_b128 v[208:211], v202 offset:36864
	ds_read_b128 v[212:215], v202 offset:37888
	ds_read_b128 v[220:223], v202 offset:38912
	ds_read_b128 v[224:227], v202 offset:39936
	global_load_lds_dwordx4 v[232:233], off
	v_lshl_add_u64 v[232:233], s[8:9], 0, v[174:175]
	s_mov_b32 m0, s70
	s_nop 0
	global_load_lds_dwordx4 v[232:233], off
	s_waitcnt vmcnt(8)
	s_waitcnt lgkmcnt(0)
	s_barrier
	s_waitcnt lgkmcnt(0)
	v_mfma_f32_16x16x32_bf16 v[128:131], v[108:111], v[160:163], v[128:131]
	v_mfma_f32_16x16x32_bf16 v[124:127], v[136:139], v[160:163], v[124:127]
	v_mfma_f32_16x16x32_bf16 v[112:115], v[108:111], v[168:171], v[112:115]
	v_mfma_f32_16x16x32_bf16 v[104:107], v[136:139], v[168:171], v[104:107]
	v_mfma_f32_16x16x32_bf16 v[92:95], v[108:111], v[208:211], v[92:95]
	v_mfma_f32_16x16x32_bf16 v[88:91], v[136:139], v[208:211], v[88:91]
	v_mfma_f32_16x16x32_bf16 v[76:79], v[108:111], v[220:223], v[76:79]
	v_mfma_f32_16x16x32_bf16 v[72:75], v[136:139], v[220:223], v[72:75]
	v_mfma_f32_16x16x32_bf16 v[128:131], v[132:135], v[164:167], v[128:131]
	v_mfma_f32_16x16x32_bf16 v[124:127], v[140:143], v[164:167], v[124:127]
	v_mfma_f32_16x16x32_bf16 v[112:115], v[132:135], v[204:207], v[112:115]
	v_mfma_f32_16x16x32_bf16 v[104:107], v[140:143], v[204:207], v[104:107]
	v_mfma_f32_16x16x32_bf16 v[92:95], v[132:135], v[212:215], v[92:95]
	v_mfma_f32_16x16x32_bf16 v[88:91], v[140:143], v[212:215], v[88:91]
	v_mfma_f32_16x16x32_bf16 v[76:79], v[132:135], v[224:227], v[76:79]
	v_mfma_f32_16x16x32_bf16 v[72:75], v[140:143], v[224:227], v[72:75]
	v_mfma_f32_16x16x32_bf16 v[120:123], v[144:147], v[160:163], v[120:123]
	v_mfma_f32_16x16x32_bf16 v[116:119], v[152:155], v[160:163], v[116:119]
	v_mfma_f32_16x16x32_bf16 v[100:103], v[144:147], v[168:171], v[100:103]
	v_mfma_f32_16x16x32_bf16 v[96:99], v[152:155], v[168:171], v[96:99]
	v_mfma_f32_16x16x32_bf16 v[84:87], v[144:147], v[208:211], v[84:87]
	v_mfma_f32_16x16x32_bf16 v[80:83], v[152:155], v[208:211], v[80:83]
	v_mfma_f32_16x16x32_bf16 v[68:71], v[144:147], v[220:223], v[68:71]
	v_mfma_f32_16x16x32_bf16 v[64:67], v[152:155], v[220:223], v[64:67]
	v_mfma_f32_16x16x32_bf16 v[120:123], v[148:151], v[164:167], v[120:123]
	v_mfma_f32_16x16x32_bf16 v[116:119], v[156:159], v[164:167], v[116:119]
	v_mfma_f32_16x16x32_bf16 v[100:103], v[148:151], v[204:207], v[100:103]
	v_mfma_f32_16x16x32_bf16 v[96:99], v[156:159], v[204:207], v[96:99]
	v_mfma_f32_16x16x32_bf16 v[84:87], v[148:151], v[212:215], v[84:87]
	v_mfma_f32_16x16x32_bf16 v[80:83], v[156:159], v[212:215], v[80:83]
	v_mfma_f32_16x16x32_bf16 v[68:71], v[148:151], v[224:227], v[68:71]
	v_mfma_f32_16x16x32_bf16 v[64:67], v[156:159], v[224:227], v[64:67]
	s_barrier
	s_add_i32 s8, s81, s15
	v_lshl_add_u64 v[232:233], v[216:217], 0, s[38:39]
	s_mov_b32 m0, s8
	ds_read_b128 v[160:163], v202 offset:49152
	ds_read_b128 v[164:167], v202 offset:50176
	ds_read_b128 v[168:171], v202 offset:51200
	ds_read_b128 v[204:207], v202 offset:52224
	ds_read_b128 v[208:211], v202 offset:53248
	ds_read_b128 v[212:215], v202 offset:54272
	ds_read_b128 v[220:223], v202 offset:55296
	ds_read_b128 v[224:227], v202 offset:56320
	global_load_lds_dwordx4 v[232:233], off
	v_lshl_add_u64 v[232:233], v[216:217], 0, s[40:41]
	s_add_i32 m0, s8, 0x2000
	s_add_i32 s8, s78, s15
	global_load_lds_dwordx4 v[232:233], off
	v_lshl_add_u64 v[232:233], v[216:217], 0, s[44:45]
	s_mov_b32 m0, s8
	v_lshl_add_u64 v[216:217], v[216:217], 0, s[46:47]
	global_load_lds_dwordx4 v[232:233], off
	s_add_i32 m0, s8, 0x2000
	s_nop 0
	global_load_lds_dwordx4 v[216:217], off
	v_lshl_add_u64 v[216:217], v[228:229], 0, s[42:43]
	s_mov_b32 m0, s71
	s_nop 0
	global_load_lds_dwordx4 v[216:217], off
	v_lshl_add_u64 v[216:217], v[230:231], 0, s[42:43]
	s_mov_b32 m0, s72
	s_nop 0
	global_load_lds_dwordx4 v[216:217], off
	s_waitcnt vmcnt(8)
	s_waitcnt lgkmcnt(0)
	s_barrier
	s_waitcnt lgkmcnt(0)
	v_mfma_f32_16x16x32_bf16 v[60:63], v[108:111], v[160:163], v[60:63]
	v_mfma_f32_16x16x32_bf16 v[56:59], v[136:139], v[160:163], v[56:59]
	v_mfma_f32_16x16x32_bf16 v[44:47], v[108:111], v[168:171], v[44:47]
	v_mfma_f32_16x16x32_bf16 v[40:43], v[136:139], v[168:171], v[40:43]
	v_mfma_f32_16x16x32_bf16 v[28:31], v[108:111], v[208:211], v[28:31]
	v_mfma_f32_16x16x32_bf16 v[24:27], v[136:139], v[208:211], v[24:27]
	v_mfma_f32_16x16x32_bf16 v[12:15], v[108:111], v[220:223], v[12:15]
	v_mfma_f32_16x16x32_bf16 v[8:11], v[136:139], v[220:223], v[8:11]
	v_mfma_f32_16x16x32_bf16 v[60:63], v[132:135], v[164:167], v[60:63]
	v_mfma_f32_16x16x32_bf16 v[56:59], v[140:143], v[164:167], v[56:59]
	v_mfma_f32_16x16x32_bf16 v[44:47], v[132:135], v[204:207], v[44:47]
	v_mfma_f32_16x16x32_bf16 v[40:43], v[140:143], v[204:207], v[40:43]
	v_mfma_f32_16x16x32_bf16 v[28:31], v[132:135], v[212:215], v[28:31]
	v_mfma_f32_16x16x32_bf16 v[24:27], v[140:143], v[212:215], v[24:27]
	v_mfma_f32_16x16x32_bf16 v[12:15], v[132:135], v[224:227], v[12:15]
	v_mfma_f32_16x16x32_bf16 v[8:11], v[140:143], v[224:227], v[8:11]
	v_mfma_f32_16x16x32_bf16 v[52:55], v[144:147], v[160:163], v[52:55]
	v_mfma_f32_16x16x32_bf16 v[48:51], v[152:155], v[160:163], v[48:51]
	v_mfma_f32_16x16x32_bf16 v[36:39], v[144:147], v[168:171], v[36:39]
	v_mfma_f32_16x16x32_bf16 v[32:35], v[152:155], v[168:171], v[32:35]
	v_mfma_f32_16x16x32_bf16 v[20:23], v[144:147], v[208:211], v[20:23]
	v_mfma_f32_16x16x32_bf16 v[16:19], v[152:155], v[208:211], v[16:19]
	v_mfma_f32_16x16x32_bf16 v[4:7], v[144:147], v[220:223], v[4:7]
	v_mfma_f32_16x16x32_bf16 v[0:3], v[152:155], v[220:223], v[0:3]
	v_mfma_f32_16x16x32_bf16 v[52:55], v[148:151], v[164:167], v[52:55]
	v_mfma_f32_16x16x32_bf16 v[48:51], v[156:159], v[164:167], v[48:51]
	v_mfma_f32_16x16x32_bf16 v[36:39], v[148:151], v[204:207], v[36:39]
	v_mfma_f32_16x16x32_bf16 v[32:35], v[156:159], v[204:207], v[32:35]
	v_mfma_f32_16x16x32_bf16 v[20:23], v[148:151], v[212:215], v[20:23]
	v_mfma_f32_16x16x32_bf16 v[16:19], v[156:159], v[212:215], v[16:19]
	v_mfma_f32_16x16x32_bf16 v[4:7], v[148:151], v[224:227], v[4:7]
	v_mfma_f32_16x16x32_bf16 v[0:3], v[156:159], v[224:227], v[0:3]
	s_barrier
	s_add_i32 s86, s86, 2
	s_add_u32 s82, s82, 0x10000
	s_addc_u32 s85, s85, 0
	s_add_u32 s64, s64, 0x100
	s_addc_u32 s65, s65, 0
	s_cmp_gt_u32 s86, 5

; #define PG8_STAGE(bufoff, gbase, voff) do { _Pragma("unroll") for (int _i = 0; _i < 2; ++_i) \
;         __builtin_amdgcn_global_load_lds((const unsigned*)((const char*)(gbase) + (voff)[_i]), (PG8_LAS unsigned*)(lds + (bufoff) + ldsw + _i * 8192), 16, 0, 0); } while (0)
; #define PG8_LDA(dst, b, h) do { _Pragma("unroll") for (int m = 0; m < 4; ++m) _Pragma("unroll") for (int k = 0; k < 2; ++k) dst[m][k] = *(const PG8_LAS bf16x8*)(lds + PG8_SA(b, h) + aoff + m * 2048 + k * 1024); } while (0)
; #define PG8_LDB(dst, b, h) do { _Pragma("unroll") for (int n = 0; n < 2; ++n) _Pragma("unroll") for (int k = 0; k < 2; ++k) dst[n][k] = *(const PG8_LAS bf16x8*)(lds + PG8_SB(b, h) + boff + n * 2048 + k * 1024); } while (0)
; #define PG8_SCHED __builtin_amdgcn_sched_barrier(0)
;     __host__ __device__ bool next(int i, Unit& u) const {
;         const long L = (long)i * G + c; if (L >= nwg) return false;
;         int wgid = (int)L; { const int q = nwg / NXCD, r = nwg % NXCD, xcd = wgid % NXCD, off = wgid / NXCD; wgid = (xcd < r ? xcd * (q + 1) : r * (q + 1) + (xcd - r) * q) + off; }
;         const int nig = wgm * nN, gid = wgid / nig, fm = gid * wgm, gsz = (nM - fm) < wgm ? (nM - fm) : wgm;
;         u.pm = fm + ((wgid % nig) % gsz); u.pn = (wgid % nig) / gsz; return true;
; template <class Epi, class Sched, bool ALIGN_EPI = false, bool SP2 = false>
; __device__ __forceinline__ void gemm_phase(PG8_LAS unsigned char* lds, const Gemm g, const Sched& S, const Epi& E) {
;     ...
;         const bool has_next = S.next(ui + 1, nxt);
;         const char* nA = has_next ? (const char*)g.A + (size_t)nxt.pm * tstepA : cA; const char* nB = has_next ? (const char*)g.Bt + (size_t)nxt.pn * tstepB : cB;
;         for (int t = 0; t < nt; t += 2) {
;             const bool last = (t == nt - 2);
;             const char* a1 = cA + (size_t)(t + 1) * kstepA;
;             const char* a2 = last ? nA : cA + (size_t)(t + 2) * kstepA; const char* b2 = last ? nB : cB + (size_t)(t + 2) * kstep;
;             const char* a3 = a2 + kstepA; const char* b3 = b2 + kstep;
;             if (last && has_next) S.a_ready(nxt);
;             if constexpr (SP2) {
;             PG8_LDB(B0, 0, 0); PG8_LDB(B1, 0, 1); PG8_SCHED; PG8_LDA(At, 0, 0); PG8_STAGE(PG8_SA(1, 1), a1 + hstepA, voffA);
.LBB0_744:
	ds_read_b128 v[128:131], v211
	ds_read_b128 v[132:135], v211 offset:1024
	ds_read_b128 v[136:139], v211 offset:2048
	ds_read_b128 v[140:143], v211 offset:3072
	ds_read_b128 v[144:147], v212
	ds_read_b128 v[148:151], v212 offset:1024
	ds_read_b128 v[152:155], v212 offset:2048
	ds_read_b128 v[156:159], v212 offset:3072
	ds_read_b128 v[160:163], v213
	ds_read_b128 v[164:167], v213 offset:1024
	ds_read_b128 v[168:171], v213 offset:2048
	ds_read_b128 v[172:175], v213 offset:3072
	ds_read_b128 v[176:179], v213 offset:4096
	ds_read_b128 v[180:183], v213 offset:5120
	ds_read_b128 v[220:223], v213 offset:6144
	ds_read_b128 v[224:227], v213 offset:7168
	s_add_i32 s76, s76, 1
	s_mul_i32 s4, s76, s80
	s_mul_hi_u32 s5, s76, s81
	s_add_i32 s5, s5, s4
	s_mul_i32 s4, s76, s81
	s_add_u32 s60, s4, s16
	s_addc_u32 s61, s5, s82
	v_cmp_gt_i64_e32 vcc, s[60:61], v[206:207]
	v_cmp_lt_i64_e64 s[4:5], s[60:61], v[204:205]
	s_cbranch_vccnz .LBB0_750
	s_ashr_i32 s56, s60, 31
	s_lshr_b32 s56, s56, 29
	s_add_i32 s58, s60, s56
	s_and_b32 s56, s58, -8
	s_sub_i32 s59, s60, s56
	s_cmp_gt_i32 s59, -1
	s_mov_b64 s[56:57], -1
	s_cbranch_scc0 .LBB0_747
	s_lshl_b32 s60, s59, 6
	s_mov_b64 s[56:57], 0

; #define PG8_STAGE(bufoff, gbase, voff) do { _Pragma("unroll") for (int _i = 0; _i < 2; ++_i) \
;         __builtin_amdgcn_global_load_lds((const unsigned*)((const char*)(gbase) + (voff)[_i]), (PG8_LAS unsigned*)(lds + (bufoff) + ldsw + _i * 8192), 16, 0, 0); } while (0)
; #define PG8_LDA(dst, b, h) do { _Pragma("unroll") for (int m = 0; m < 4; ++m) _Pragma("unroll") for (int k = 0; k < 2; ++k) dst[m][k] = *(const PG8_LAS bf16x8*)(lds + PG8_SA(b, h) + aoff + m * 2048 + k * 1024); } while (0)
; #define PG8_LDB(dst, b, h) do { _Pragma("unroll") for (int n = 0; n < 2; ++n) _Pragma("unroll") for (int k = 0; k < 2; ++k) dst[n][k] = *(const PG8_LAS bf16x8*)(lds + PG8_SB(b, h) + boff + n * 2048 + k * 1024); } while (0)
; #define PG8_WAIT_V(n) asm volatile("s_waitcnt vmcnt(" #n ")" ::: "memory")
; #define PG8_WAIT_L(n) asm volatile("s_waitcnt lgkmcnt(" #n ")" ::: "memory")
; #define PG8_BAR __builtin_amdgcn_s_barrier()
; #define PG8_SCHED __builtin_amdgcn_sched_barrier(0)
; template <class Epi, class Sched, bool ALIGN_EPI = false, bool SP2 = false>
; __device__ __forceinline__ void gemm_phase(PG8_LAS unsigned char* lds, const Gemm g, const Sched& S, const Epi& E) {
;     ...
;         const char* nA = has_next ? (const char*)g.A + (size_t)nxt.pm * tstepA : cA; const char* nB = has_next ? (const char*)g.Bt + (size_t)nxt.pn * tstepB : cB;
;         for (int t = 0; t < nt; t += 2) {
;             const bool last = (t == nt - 2);
;             const char* a1 = cA + (size_t)(t + 1) * kstepA;
;             const char* a2 = last ? nA : cA + (size_t)(t + 2) * kstepA; const char* b2 = last ? nB : cB + (size_t)(t + 2) * kstep;
;             const char* a3 = a2 + kstepA; const char* b3 = b2 + kstep;
;             if (last && has_next) S.a_ready(nxt);
;             if constexpr (SP2) {
;             PG8_LDB(B0, 0, 0); PG8_LDB(B1, 0, 1); PG8_SCHED; PG8_LDA(At, 0, 0); PG8_STAGE(PG8_SA(1, 1), a1 + hstepA, voffA);
;             PG8_WAIT_V(8); PG8_WAIT_L(0); PG8_BAR; PG8_MMA(0, 0, At, B0); PG8_MMA(0, 1, At, B1); PG8_BAR; PG8_SCHED;
;             PG8_LDA(At, 0, 1); PG8_STAGE(PG8_SB(0, 0), b2, voffB); PG8_STAGE(PG8_SB(0, 1), b2 + hstepB, voffB); PG8_STAGE(PG8_SA(0, 0), a2, voffA);
;             PG8_WAIT_V(8); PG8_WAIT_L(0); PG8_BAR; PG8_MMA(1, 0, At, B0); PG8_MMA(1, 1, At, B1); PG8_BAR; PG8_SCHED;
.LBB0_750:
	s_ashr_i32 s59, s58, 31
	s_lshl_b64 s[60:61], s[58:59], 19
	s_add_u32 s60, s6, s60
	s_addc_u32 s61, s7, s61
	s_and_b64 s[62:63], s[4:5], exec
	s_cselect_b32 s59, s61, s69
	s_cselect_b32 s65, s60, s68
	s_ashr_i32 s57, s56, 31
	s_lshl_b64 s[62:63], s[56:57], 19
	s_add_u32 s62, s93, s62
	s_addc_u32 s63, s84, s63
	s_and_b64 s[72:73], s[4:5], exec
	s_cselect_b32 s57, s63, s71
	s_cselect_b32 s67, s62, s70
	s_add_u32 s68, s68, 0x10000
	s_addc_u32 s69, s69, 0
	s_add_u32 s70, s70, 0x10000
	s_addc_u32 s71, s71, 0
	s_mov_b32 s72, -2
	s_waitcnt lgkmcnt(0)
	s_cmp_eq_u32 s72, 12
	s_cselect_b32 s79, s59, s69
	s_cselect_b32 s78, s65, s68
	s_cselect_b32 s91, s57, s71
	s_cselect_b32 s90, s67, s70
	v_lshl_add_u64 v[208:209], s[68:69], 0, v[190:191]
	v_lshl_add_u64 v[228:229], v[208:209], 0, s[52:53]
	s_add_i32 m0, s15, 0xc000
	global_load_lds_dwordx4 v[228:229], off
	v_lshl_add_u64 v[208:209], v[208:209], 0, s[54:55]
	s_add_i32 m0, s15, 0xe000
	s_nop 0
	global_load_lds_dwordx4 v[208:209], off
	s_waitcnt vmcnt(8)
	s_waitcnt lgkmcnt(0)
	s_barrier
	s_waitcnt lgkmcnt(0)
	v_mfma_f32_16x16x32_bf16 v[124:127], v[128:131], v[160:163], 0
	v_mfma_f32_16x16x32_bf16 v[120:123], v[136:139], v[160:163], 0
	v_mfma_f32_16x16x32_bf16 v[108:111], v[128:131], v[168:171], 0
	v_mfma_f32_16x16x32_bf16 v[104:107], v[136:139], v[168:171], 0
	v_mfma_f32_16x16x32_bf16 v[92:95], v[128:131], v[176:179], 0
	v_mfma_f32_16x16x32_bf16 v[88:91], v[136:139], v[176:179], 0
	v_mfma_f32_16x16x32_bf16 v[76:79], v[128:131], v[220:223], 0
	v_mfma_f32_16x16x32_bf16 v[72:75], v[136:139], v[220:223], 0
	v_mfma_f32_16x16x32_bf16 v[124:127], v[132:135], v[164:167], v[124:127]
	v_mfma_f32_16x16x32_bf16 v[120:123], v[140:143], v[164:167], v[120:123]
	v_mfma_f32_16x16x32_bf16 v[108:111], v[132:135], v[172:175], v[108:111]
	v_mfma_f32_16x16x32_bf16 v[104:107], v[140:143], v[172:175], v[104:107]
	v_mfma_f32_16x16x32_bf16 v[92:95], v[132:135], v[180:183], v[92:95]
	v_mfma_f32_16x16x32_bf16 v[88:91], v[140:143], v[180:183], v[88:91]
	v_mfma_f32_16x16x32_bf16 v[76:79], v[132:135], v[224:227], v[76:79]
	v_mfma_f32_16x16x32_bf16 v[72:75], v[140:143], v[224:227], v[72:75]
	v_mfma_f32_16x16x32_bf16 v[116:119], v[144:147], v[160:163], 0
	v_mfma_f32_16x16x32_bf16 v[112:115], v[152:155], v[160:163], 0
	v_mfma_f32_16x16x32_bf16 v[100:103], v[144:147], v[168:171], 0
	v_mfma_f32_16x16x32_bf16 v[96:99], v[152:155], v[168:171], 0
	v_mfma_f32_16x16x32_bf16 v[84:87], v[144:147], v[176:179], 0
	v_mfma_f32_16x16x32_bf16 v[80:83], v[152:155], v[176:179], 0
	v_mfma_f32_16x16x32_bf16 v[68:71], v[144:147], v[220:223], 0
	v_mfma_f32_16x16x32_bf16 v[64:67], v[152:155], v[220:223], 0
	v_mfma_f32_16x16x32_bf16 v[116:119], v[148:151], v[164:167], v[116:119]
	v_mfma_f32_16x16x32_bf16 v[112:115], v[156:159], v[164:167], v[112:115]
	v_mfma_f32_16x16x32_bf16 v[100:103], v[148:151], v[172:175], v[100:103]
	v_mfma_f32_16x16x32_bf16 v[96:99], v[156:159], v[172:175], v[96:99]
	v_mfma_f32_16x16x32_bf16 v[84:87], v[148:151], v[180:183], v[84:87]
	v_mfma_f32_16x16x32_bf16 v[80:83], v[156:159], v[180:183], v[80:83]
	v_mfma_f32_16x16x32_bf16 v[68:71], v[148:151], v[224:227], v[68:71]
	v_mfma_f32_16x16x32_bf16 v[64:67], v[156:159], v[224:227], v[64:67]
	s_barrier
	s_add_i32 s73, s85, s14
	v_lshl_add_u64 v[208:209], s[90:91], 0, v[190:191]
	s_mov_b32 m0, s73
	ds_read_b128 v[160:163], v213 offset:16384
	ds_read_b128 v[164:167], v213 offset:17408
	ds_read_b128 v[168:171], v213 offset:18432
	ds_read_b128 v[172:175], v213 offset:19456
	ds_read_b128 v[176:179], v213 offset:20480
	ds_read_b128 v[180:183], v213 offset:21504
	ds_read_b128 v[220:223], v213 offset:22528
	ds_read_b128 v[224:227], v213 offset:23552
	global_load_lds_dwordx4 v[208:209], off
	v_lshl_add_u64 v[228:229], v[208:209], 0, s[10:11]
	s_add_i32 m0, s73, 0x2000
	s_add_i32 s73, s86, s14
	global_load_lds_dwordx4 v[228:229], off
	v_lshl_add_u64 v[228:229], v[208:209], 0, s[34:35]
	s_mov_b32 m0, s73
	s_nop 0
	global_load_lds_dwordx4 v[228:229], off
	v_lshl_add_u64 v[228:229], v[208:209], 0, s[36:37]
	s_add_i32 m0, s73, 0x2000
	s_nop 0
	global_load_lds_dwordx4 v[228:229], off
	v_lshl_add_u64 v[228:229], s[78:79], 0, v[190:191]
	s_mov_b32 m0, s15
	v_lshl_add_u64 v[230:231], v[228:229], 0, s[10:11]
	global_load_lds_dwordx4 v[228:229], off
	s_mov_b32 m0, s17
	s_nop 0
	global_load_lds_dwordx4 v[230:231], off
	s_waitcnt vmcnt(8)
	s_waitcnt lgkmcnt(0)
	s_barrier
	s_waitcnt lgkmcnt(0)
	v_mfma_f32_16x16x32_bf16 v[60:63], v[128:131], v[160:163], 0
	v_mfma_f32_16x16x32_bf16 v[56:59], v[136:139], v[160:163], 0
	v_mfma_f32_16x16x32_bf16 v[44:47], v[128:131], v[168:171], 0
	v_mfma_f32_16x16x32_bf16 v[40:43], v[136:139], v[168:171], 0
	v_mfma_f32_16x16x32_bf16 v[28:31], v[128:131], v[176:179], 0
	v_mfma_f32_16x16x32_bf16 v[24:27], v[136:139], v[176:179], 0
	v_mfma_f32_16x16x32_bf16 v[12:15], v[128:131], v[220:223], 0
	v_mfma_f32_16x16x32_bf16 v[8:11], v[136:139], v[220:223], 0
	v_mfma_f32_16x16x32_bf16 v[60:63], v[132:135], v[164:167], v[60:63]
	v_mfma_f32_16x16x32_bf16 v[56:59], v[140:143], v[164:167], v[56:59]
	v_mfma_f32_16x16x32_bf16 v[44:47], v[132:135], v[172:175], v[44:47]
	v_mfma_f32_16x16x32_bf16 v[40:43], v[140:143], v[172:175], v[40:43]
	v_mfma_f32_16x16x32_bf16 v[28:31], v[132:135], v[180:183], v[28:31]
	v_mfma_f32_16x16x32_bf16 v[24:27], v[140:143], v[180:183], v[24:27]
	v_mfma_f32_16x16x32_bf16 v[12:15], v[132:135], v[224:227], v[12:15]
	v_mfma_f32_16x16x32_bf16 v[8:11], v[140:143], v[224:227], v[8:11]
	v_mfma_f32_16x16x32_bf16 v[52:55], v[144:147], v[160:163], 0
	v_mfma_f32_16x16x32_bf16 v[48:51], v[152:155], v[160:163], 0
	v_mfma_f32_16x16x32_bf16 v[36:39], v[144:147], v[168:171], 0
	v_mfma_f32_16x16x32_bf16 v[32:35], v[152:155], v[168:171], 0
	v_mfma_f32_16x16x32_bf16 v[20:23], v[144:147], v[176:179], 0
	v_mfma_f32_16x16x32_bf16 v[16:19], v[152:155], v[176:179], 0
	v_mfma_f32_16x16x32_bf16 v[4:7], v[144:147], v[220:223], 0
	v_mfma_f32_16x16x32_bf16 v[0:3], v[152:155], v[220:223], 0
	v_mfma_f32_16x16x32_bf16 v[52:55], v[148:151], v[164:167], v[52:55]
	v_mfma_f32_16x16x32_bf16 v[48:51], v[156:159], v[164:167], v[48:51]
	v_mfma_f32_16x16x32_bf16 v[36:39], v[148:151], v[172:175], v[36:39]
	v_mfma_f32_16x16x32_bf16 v[32:35], v[156:159], v[172:175], v[32:35]
	v_mfma_f32_16x16x32_bf16 v[20:23], v[148:151], v[180:183], v[20:23]
	v_mfma_f32_16x16x32_bf16 v[16:19], v[156:159], v[180:183], v[16:19]
	v_mfma_f32_16x16x32_bf16 v[4:7], v[148:151], v[224:227], v[4:7]
	v_mfma_f32_16x16x32_bf16 v[0:3], v[156:159], v[224:227], v[0:3]
	s_barrier
; #define PG8_STAGE(bufoff, gbase, voff) do { _Pragma("unroll") for (int _i = 0; _i < 2; ++_i) \
;         __builtin_amdgcn_global_load_lds((const unsigned*)((const char*)(gbase) + (voff)[_i]), (PG8_LAS unsigned*)(lds + (bufoff) + ldsw + _i * 8192), 16, 0, 0); } while (0)
; #define PG8_LDA(dst, b, h) do { _Pragma("unroll") for (int m = 0; m < 4; ++m) _Pragma("unroll") for (int k = 0; k < 2; ++k) dst[m][k] = *(const PG8_LAS bf16x8*)(lds + PG8_SA(b, h) + aoff + m * 2048 + k * 1024); } while (0)
; #define PG8_LDB(dst, b, h) do { _Pragma("unroll") for (int n = 0; n < 2; ++n) _Pragma("unroll") for (int k = 0; k < 2; ++k) dst[n][k] = *(const PG8_LAS bf16x8*)(lds + PG8_SB(b, h) + boff + n * 2048 + k * 1024); } while (0)
; #define PG8_MMA(ai, bj, At, Bt) do { __builtin_amdgcn_s_setprio(1); _Pragma("unroll") for (int m = 0; m < 4; ++m) _Pragma("unroll") for (int n = 0; n < 2; ++n) _Pragma("unroll") for (int k = 0; k < 2; ++k) \
;         acc[ai][bj][m][n] = __builtin_amdgcn_mfma_f32_16x16x32_bf16(Bt[n][k], At[m][k], acc[ai][bj][m][n], 0, 0, 0); __builtin_amdgcn_s_setprio(0); } while (0)
; #define PG8_WAIT_V(n) asm volatile("s_waitcnt vmcnt(" #n ")" ::: "memory")
; #define PG8_WAIT_L(n) asm volatile("s_waitcnt lgkmcnt(" #n ")" ::: "memory")
; #define PG8_BAR __builtin_amdgcn_s_barrier()
; #define PG8_SCHED __builtin_amdgcn_sched_barrier(0)
; template <class Epi, class Sched, bool ALIGN_EPI = false, bool SP2 = false>
; __device__ __forceinline__ void gemm_phase(PG8_LAS unsigned char* lds, const Gemm g, const Sched& S, const Epi& E) {
;     ...
;             PG8_LDB(B0, 1, 0); PG8_LDB(B1, 1, 1); PG8_SCHED; PG8_LDA(At, 1, 0); PG8_STAGE(PG8_SA(0, 1), a2 + hstepA, voffA);
;             PG8_WAIT_V(8); PG8_WAIT_L(0); PG8_BAR; PG8_MMA(0, 0, At, B0); PG8_MMA(0, 1, At, B1); PG8_BAR; PG8_SCHED;
;             PG8_LDA(At, 1, 1); PG8_STAGE(PG8_SB(1, 0), b3, voffB); PG8_STAGE(PG8_SB(1, 1), b3 + hstepB, voffB); PG8_STAGE(PG8_SA(1, 0), a3, voffA);
;             PG8_WAIT_V(8); PG8_WAIT_L(0); PG8_BAR; PG8_MMA(1, 0, At, B0); PG8_MMA(1, 1, At, B1); PG8_BAR; PG8_SCHED;
	ds_read_b128 v[128:131], v214
	ds_read_b128 v[132:135], v214 offset:1024
	ds_read_b128 v[136:139], v214 offset:2048
	ds_read_b128 v[140:143], v214 offset:3072
	ds_read_b128 v[144:147], v215
	ds_read_b128 v[148:151], v215 offset:1024
	ds_read_b128 v[152:155], v215 offset:2048
	ds_read_b128 v[156:159], v215 offset:3072
	s_mov_b32 m0, s18
	v_lshl_add_u64 v[230:231], v[228:229], 0, s[34:35]
	ds_read_b128 v[160:163], v213 offset:32768
	ds_read_b128 v[164:167], v213 offset:33792
	ds_read_b128 v[168:171], v213 offset:34816
	ds_read_b128 v[172:175], v213 offset:35840
	ds_read_b128 v[176:179], v213 offset:36864
	ds_read_b128 v[180:183], v213 offset:37888
	ds_read_b128 v[220:223], v213 offset:38912
	ds_read_b128 v[224:227], v213 offset:39936
	global_load_lds_dwordx4 v[230:231], off
	v_lshl_add_u64 v[230:231], v[228:229], 0, s[36:37]
	s_mov_b32 m0, s19
	s_nop 0
	global_load_lds_dwordx4 v[230:231], off
	s_waitcnt vmcnt(8)
	s_waitcnt lgkmcnt(0)
	s_barrier
	s_waitcnt lgkmcnt(0)
	v_mfma_f32_16x16x32_bf16 v[124:127], v[128:131], v[160:163], v[124:127]
	v_mfma_f32_16x16x32_bf16 v[120:123], v[136:139], v[160:163], v[120:123]
	v_mfma_f32_16x16x32_bf16 v[108:111], v[128:131], v[168:171], v[108:111]
	v_mfma_f32_16x16x32_bf16 v[104:107], v[136:139], v[168:171], v[104:107]
	v_mfma_f32_16x16x32_bf16 v[92:95], v[128:131], v[176:179], v[92:95]
	v_mfma_f32_16x16x32_bf16 v[88:91], v[136:139], v[176:179], v[88:91]
	v_mfma_f32_16x16x32_bf16 v[76:79], v[128:131], v[220:223], v[76:79]
	v_mfma_f32_16x16x32_bf16 v[72:75], v[136:139], v[220:223], v[72:75]
	v_mfma_f32_16x16x32_bf16 v[124:127], v[132:135], v[164:167], v[124:127]
	v_mfma_f32_16x16x32_bf16 v[120:123], v[140:143], v[164:167], v[120:123]
	v_mfma_f32_16x16x32_bf16 v[108:111], v[132:135], v[172:175], v[108:111]
	v_mfma_f32_16x16x32_bf16 v[104:107], v[140:143], v[172:175], v[104:107]
	v_mfma_f32_16x16x32_bf16 v[92:95], v[132:135], v[180:183], v[92:95]
	v_mfma_f32_16x16x32_bf16 v[88:91], v[140:143], v[180:183], v[88:91]
	v_mfma_f32_16x16x32_bf16 v[76:79], v[132:135], v[224:227], v[76:79]
	v_mfma_f32_16x16x32_bf16 v[72:75], v[140:143], v[224:227], v[72:75]
	v_mfma_f32_16x16x32_bf16 v[116:119], v[144:147], v[160:163], v[116:119]
	v_mfma_f32_16x16x32_bf16 v[112:115], v[152:155], v[160:163], v[112:115]
	v_mfma_f32_16x16x32_bf16 v[100:103], v[144:147], v[168:171], v[100:103]
	v_mfma_f32_16x16x32_bf16 v[96:99], v[152:155], v[168:171], v[96:99]
	v_mfma_f32_16x16x32_bf16 v[84:87], v[144:147], v[176:179], v[84:87]
	v_mfma_f32_16x16x32_bf16 v[80:83], v[152:155], v[176:179], v[80:83]
	v_mfma_f32_16x16x32_bf16 v[68:71], v[144:147], v[220:223], v[68:71]
	v_mfma_f32_16x16x32_bf16 v[64:67], v[152:155], v[220:223], v[64:67]
	v_mfma_f32_16x16x32_bf16 v[116:119], v[148:151], v[164:167], v[116:119]
	v_mfma_f32_16x16x32_bf16 v[112:115], v[156:159], v[164:167], v[112:115]
	v_mfma_f32_16x16x32_bf16 v[100:103], v[148:151], v[172:175], v[100:103]
	v_mfma_f32_16x16x32_bf16 v[96:99], v[156:159], v[172:175], v[96:99]
	v_mfma_f32_16x16x32_bf16 v[84:87], v[148:151], v[180:183], v[84:87]
	v_mfma_f32_16x16x32_bf16 v[80:83], v[156:159], v[180:183], v[80:83]
	v_mfma_f32_16x16x32_bf16 v[68:71], v[148:151], v[224:227], v[68:71]
	v_mfma_f32_16x16x32_bf16 v[64:67], v[156:159], v[224:227], v[64:67]
	s_barrier
	s_add_i32 s73, s87, s14
	v_lshl_add_u64 v[230:231], v[208:209], 0, s[38:39]
	s_mov_b32 m0, s73
	ds_read_b128 v[160:163], v213 offset:49152
	ds_read_b128 v[164:167], v213 offset:50176
	ds_read_b128 v[168:171], v213 offset:51200
	ds_read_b128 v[172:175], v213 offset:52224
	ds_read_b128 v[176:179], v213 offset:53248
	ds_read_b128 v[180:183], v213 offset:54272
	ds_read_b128 v[220:223], v213 offset:55296
	ds_read_b128 v[224:227], v213 offset:56320
	global_load_lds_dwordx4 v[230:231], off
	v_lshl_add_u64 v[230:231], v[208:209], 0, s[40:41]
	s_add_i32 m0, s73, 0x2000
	s_add_i32 s73, s88, s14
	global_load_lds_dwordx4 v[230:231], off
	v_lshl_add_u64 v[230:231], v[208:209], 0, s[42:43]
	s_mov_b32 m0, s73
	v_lshl_add_u64 v[208:209], v[208:209], 0, s[44:45]
	global_load_lds_dwordx4 v[230:231], off
	s_add_i32 m0, s73, 0x2000
	s_nop 0
	global_load_lds_dwordx4 v[208:209], off
	v_lshl_add_u64 v[208:209], v[228:229], 0, s[38:39]
	s_mov_b32 m0, s74
	s_nop 0
	global_load_lds_dwordx4 v[208:209], off
	v_lshl_add_u64 v[208:209], v[228:229], 0, s[40:41]
	s_mov_b32 m0, s75
	s_nop 0
	global_load_lds_dwordx4 v[208:209], off
	s_waitcnt vmcnt(8)
	s_waitcnt lgkmcnt(0)
	s_barrier
	s_waitcnt lgkmcnt(0)
	v_mfma_f32_16x16x32_bf16 v[60:63], v[128:131], v[160:163], v[60:63]
	v_mfma_f32_16x16x32_bf16 v[56:59], v[136:139], v[160:163], v[56:59]
	v_mfma_f32_16x16x32_bf16 v[44:47], v[128:131], v[168:171], v[44:47]
	v_mfma_f32_16x16x32_bf16 v[40:43], v[136:139], v[168:171], v[40:43]
	v_mfma_f32_16x16x32_bf16 v[28:31], v[128:131], v[176:179], v[28:31]
	v_mfma_f32_16x16x32_bf16 v[24:27], v[136:139], v[176:179], v[24:27]
	v_mfma_f32_16x16x32_bf16 v[12:15], v[128:131], v[220:223], v[12:15]
	v_mfma_f32_16x16x32_bf16 v[8:11], v[136:139], v[220:223], v[8:11]
	v_mfma_f32_16x16x32_bf16 v[60:63], v[132:135], v[164:167], v[60:63]
	v_mfma_f32_16x16x32_bf16 v[56:59], v[140:143], v[164:167], v[56:59]
	v_mfma_f32_16x16x32_bf16 v[44:47], v[132:135], v[172:175], v[44:47]
	v_mfma_f32_16x16x32_bf16 v[40:43], v[140:143], v[172:175], v[40:43]
	v_mfma_f32_16x16x32_bf16 v[28:31], v[132:135], v[180:183], v[28:31]
	v_mfma_f32_16x16x32_bf16 v[24:27], v[140:143], v[180:183], v[24:27]
	v_mfma_f32_16x16x32_bf16 v[12:15], v[132:135], v[224:227], v[12:15]
	v_mfma_f32_16x16x32_bf16 v[8:11], v[140:143], v[224:227], v[8:11]
	v_mfma_f32_16x16x32_bf16 v[52:55], v[144:147], v[160:163], v[52:55]
	v_mfma_f32_16x16x32_bf16 v[48:51], v[152:155], v[160:163], v[48:51]
	v_mfma_f32_16x16x32_bf16 v[36:39], v[144:147], v[168:171], v[36:39]
	v_mfma_f32_16x16x32_bf16 v[32:35], v[152:155], v[168:171], v[32:35]
	v_mfma_f32_16x16x32_bf16 v[20:23], v[144:147], v[176:179], v[20:23]
	v_mfma_f32_16x16x32_bf16 v[16:19], v[152:155], v[176:179], v[16:19]
	v_mfma_f32_16x16x32_bf16 v[4:7], v[144:147], v[220:223], v[4:7]
	v_mfma_f32_16x16x32_bf16 v[0:3], v[152:155], v[220:223], v[0:3]
	v_mfma_f32_16x16x32_bf16 v[52:55], v[148:151], v[164:167], v[52:55]
	v_mfma_f32_16x16x32_bf16 v[48:51], v[156:159], v[164:167], v[48:51]
	v_mfma_f32_16x16x32_bf16 v[36:39], v[148:151], v[172:175], v[36:39]
	v_mfma_f32_16x16x32_bf16 v[32:35], v[156:159], v[172:175], v[32:35]
	v_mfma_f32_16x16x32_bf16 v[20:23], v[148:151], v[180:183], v[20:23]
	v_mfma_f32_16x16x32_bf16 v[16:19], v[156:159], v[180:183], v[16:19]
	v_mfma_f32_16x16x32_bf16 v[4:7], v[148:151], v[224:227], v[4:7]
	v_mfma_f32_16x16x32_bf16 v[0:3], v[156:159], v[224:227], v[0:3]
	s_barrier
	s_add_i32 s72, s72, 2
	s_add_u32 s68, s68, 0x10000
	s_addc_u32 s69, s69, 0
	s_add_u32 s70, s70, 0x10000
	s_addc_u32 s71, s71, 0
	s_cmp_gt_u32 s72, 13

; #define PG8_STAGE(bufoff, gbase, voff) do { _Pragma("unroll") for (int _i = 0; _i < 2; ++_i) \
;         __builtin_amdgcn_global_load_lds((const unsigned*)((const char*)(gbase) + (voff)[_i]), (PG8_LAS unsigned*)(lds + (bufoff) + ldsw + _i * 8192), 16, 0, 0); } while (0)
; #define PG8_LDA(dst, b, h) do { _Pragma("unroll") for (int m = 0; m < 4; ++m) _Pragma("unroll") for (int k = 0; k < 2; ++k) dst[m][k] = *(const PG8_LAS bf16x8*)(lds + PG8_SA(b, h) + aoff + m * 2048 + k * 1024); } while (0)
;     __host__ __device__ bool next(int i, Unit& u) const {
;         const long L = (long)i * G + c; if (L >= nwg) return false;
;         int wgid = (int)L; { const int q = nwg / NXCD, r = nwg % NXCD, xcd = wgid % NXCD, off = wgid / NXCD; wgid = (xcd < r ? xcd * (q + 1) : r * (q + 1) + (xcd - r) * q) + off; }
;         const int nig = wgm * nN, gid = wgid / nig, fm = gid * wgm, gsz = (nM - fm) < wgm ? (nM - fm) : wgm;
;         u.pm = fm + ((wgid % nig) % gsz); u.pn = (wgid % nig) / gsz; return true;
; template <class Epi, class Sched, bool ALIGN_EPI = false, bool SP2 = false>
; __device__ __forceinline__ void gemm_phase(PG8_LAS unsigned char* lds, const Gemm g, const Sched& S, const Epi& E) {
;     ...
;         const bool has_next = S.next(ui + 1, nxt);
;         const char* nA = has_next ? (const char*)g.A + (size_t)nxt.pm * tstepA : cA; const char* nB = has_next ? (const char*)g.Bt + (size_t)nxt.pn * tstepB : cB;
;         for (int t = 0; t < nt; t += 2) {
;             const bool last = (t == nt - 2);
;             const char* a1 = cA + (size_t)(t + 1) * kstepA;
;             const char* a2 = last ? nA : cA + (size_t)(t + 2) * kstepA; const char* b2 = last ? nB : cB + (size_t)(t + 2) * kstep;
;             const char* a3 = a2 + kstepA; const char* b3 = b2 + kstep;
;             if (last && has_next) S.a_ready(nxt);
;             if constexpr (SP2) {
;             PG8_LDB(B0, 0, 0); PG8_LDB(B1, 0, 1); PG8_SCHED; PG8_LDA(At, 0, 0); PG8_STAGE(PG8_SA(1, 1), a1 + hstepA, voffA);
;             PG8_WAIT_V(8); PG8_WAIT_L(0); PG8_BAR; PG8_MMA(0, 0, At, B0); PG8_MMA(0, 1, At, B1); PG8_BAR; PG8_SCHED;
;             PG8_LDA(At, 0, 1); PG8_STAGE(PG8_SB(0, 0), b2, voffB); PG8_STAGE(PG8_SB(0, 1), b2 + hstepB, voffB); PG8_STAGE(PG8_SA(0, 0), a2, voffA);
;             PG8_WAIT_V(8); PG8_WAIT_L(0); PG8_BAR; PG8_MMA(1, 0, At, B0); PG8_MMA(1, 1, At, B1); PG8_BAR; PG8_SCHED;
.LBB0_835:
	ds_read_b128 v[148:151], v141
	ds_read_b128 v[152:155], v141 offset:1024
	ds_read_b128 v[156:159], v141 offset:2048
	ds_read_b128 v[160:163], v141 offset:3072
	ds_read_b128 v[164:167], v142
	ds_read_b128 v[168:171], v142 offset:1024
	ds_read_b128 v[172:175], v142 offset:2048
	ds_read_b128 v[176:179], v142 offset:3072
	ds_read_b128 v[180:183], v143
	ds_read_b128 v[184:187], v143 offset:1024
	ds_read_b128 v[192:195], v143 offset:2048
	ds_read_b128 v[196:199], v143 offset:3072
	ds_read_b128 v[200:203], v143 offset:4096
	ds_read_b128 v[204:207], v143 offset:5120
	ds_read_b128 v[208:211], v143 offset:6144
	ds_read_b128 v[212:215], v143 offset:7168
	s_add_i32 s70, s70, 1
	s_mul_i32 s2, s70, s72
	s_mul_hi_u32 s3, s70, s73
	s_add_i32 s3, s3, s2
	s_mul_i32 s2, s70, s73
	s_add_u32 s56, s2, s16
	s_addc_u32 s57, s3, s15
	v_cmp_gt_i64_e32 vcc, s[56:57], v[138:139]
	v_cmp_lt_i64_e64 s[2:3], s[56:57], v[136:137]
	s_cbranch_vccnz .LBB0_837
	s_ashr_i32 s52, s56, 31
	s_lshr_b32 s52, s52, 29
	s_add_i32 s52, s56, s52
	s_ashr_i32 s53, s52, 3
	s_and_b32 s52, s52, -8
	s_sub_i32 s52, s56, s52
	s_cmp_lt_i32 s52, 0
	s_cselect_b32 s54, s17, 0x160
	s_mul_i32 s52, s52, s54
	s_add_i32 s52, s52, s53
	s_mul_hi_i32 s53, s52, 0x2e8ba2e9
	s_lshr_b32 s54, s53, 31
	s_ashr_i32 s53, s53, 4
	s_add_i32 s53, s53, s54
	s_lshl_b32 s54, s53, 2
	s_mulk_i32 s53, 0x58
	s_sub_i32 s53, s52, s53
	s_abs_i32 s52, s53
	s_ashr_i32 s52, s53, 2
	s_and_b32 s53, s53, 3
	s_add_i32 s54, s54, s53
.LBB0_837:
	s_ashr_i32 s55, s54, 31
	s_lshl_b64 s[56:57], s[54:55], 19
	s_add_u32 s56, s12, s56
	s_addc_u32 s57, s13, s57
	s_and_b64 s[58:59], s[2:3], exec
	s_cselect_b32 s55, s57, s63
	s_cselect_b32 s80, s56, s62
	s_ashr_i32 s53, s52, 31
	s_lshl_b64 s[58:59], s[52:53], 19
	s_add_u32 s58, s33, s58
	s_addc_u32 s59, s83, s59
	s_and_b64 s[78:79], s[2:3], exec
	s_cselect_b32 s53, s59, s65
	s_cselect_b32 s81, s58, s64
	s_add_u32 s62, s62, 0x10000
	s_addc_u32 s63, s63, 0
	s_add_u32 s64, s64, 0x10000
	s_addc_u32 s65, s65, 0
	s_mov_b32 s82, -2
	s_cmp_eq_u32 s82, 12
	s_cselect_b32 s79, s55, s63
	s_cselect_b32 s78, s80, s62
	s_cselect_b32 s85, s53, s65
	s_cselect_b32 s84, s81, s64
	v_lshl_add_u64 v[216:217], s[62:63], 0, v[190:191]
	v_lshl_add_u64 v[220:221], v[216:217], 0, s[46:47]
	s_add_i32 m0, s18, 0xc000
	global_load_lds_dwordx4 v[220:221], off
	v_lshl_add_u64 v[216:217], v[216:217], 0, s[48:49]
	s_add_i32 m0, s18, 0xe000
	s_nop 0
	global_load_lds_dwordx4 v[216:217], off
	s_waitcnt vmcnt(8)
	s_waitcnt lgkmcnt(0)
	s_barrier
	s_waitcnt lgkmcnt(0)
	v_mfma_f32_16x16x32_bf16 v[116:119], v[148:151], v[180:183], 0
	v_mfma_f32_16x16x32_bf16 v[112:115], v[156:159], v[180:183], 0
	v_mfma_f32_16x16x32_bf16 v[108:111], v[148:151], v[192:195], 0
	v_mfma_f32_16x16x32_bf16 v[100:103], v[156:159], v[192:195], 0
	v_mfma_f32_16x16x32_bf16 v[92:95], v[148:151], v[200:203], 0
	v_mfma_f32_16x16x32_bf16 v[84:87], v[156:159], v[200:203], 0
	v_mfma_f32_16x16x32_bf16 v[76:79], v[148:151], v[208:211], 0
	v_mfma_f32_16x16x32_bf16 v[68:71], v[156:159], v[208:211], 0
	v_mfma_f32_16x16x32_bf16 v[116:119], v[152:155], v[184:187], v[116:119]
	v_mfma_f32_16x16x32_bf16 v[112:115], v[160:163], v[184:187], v[112:115]
	v_mfma_f32_16x16x32_bf16 v[108:111], v[152:155], v[196:199], v[108:111]
	v_mfma_f32_16x16x32_bf16 v[100:103], v[160:163], v[196:199], v[100:103]
	v_mfma_f32_16x16x32_bf16 v[92:95], v[152:155], v[204:207], v[92:95]
	v_mfma_f32_16x16x32_bf16 v[84:87], v[160:163], v[204:207], v[84:87]
	v_mfma_f32_16x16x32_bf16 v[76:79], v[152:155], v[212:215], v[76:79]
	v_mfma_f32_16x16x32_bf16 v[68:71], v[160:163], v[212:215], v[68:71]
	v_mfma_f32_16x16x32_bf16 v[124:127], v[164:167], v[180:183], 0
	v_mfma_f32_16x16x32_bf16 v[120:123], v[172:175], v[180:183], 0
	v_mfma_f32_16x16x32_bf16 v[104:107], v[164:167], v[192:195], 0
	v_mfma_f32_16x16x32_bf16 v[96:99], v[172:175], v[192:195], 0
	v_mfma_f32_16x16x32_bf16 v[88:91], v[164:167], v[200:203], 0
	v_mfma_f32_16x16x32_bf16 v[80:83], v[172:175], v[200:203], 0
	v_mfma_f32_16x16x32_bf16 v[72:75], v[164:167], v[208:211], 0
	v_mfma_f32_16x16x32_bf16 v[64:67], v[172:175], v[208:211], 0
	v_mfma_f32_16x16x32_bf16 v[124:127], v[168:171], v[184:187], v[124:127]
	v_mfma_f32_16x16x32_bf16 v[120:123], v[176:179], v[184:187], v[120:123]
	v_mfma_f32_16x16x32_bf16 v[104:107], v[168:171], v[196:199], v[104:107]
	v_mfma_f32_16x16x32_bf16 v[96:99], v[176:179], v[196:199], v[96:99]
	v_mfma_f32_16x16x32_bf16 v[88:91], v[168:171], v[204:207], v[88:91]
	v_mfma_f32_16x16x32_bf16 v[80:83], v[176:179], v[204:207], v[80:83]
	v_mfma_f32_16x16x32_bf16 v[72:75], v[168:171], v[212:215], v[72:75]
	v_mfma_f32_16x16x32_bf16 v[64:67], v[176:179], v[212:215], v[64:67]
	s_barrier
	v_lshl_add_u64 v[216:217], s[84:85], 0, v[190:191]
	s_add_i32 s84, s74, s14
	s_mov_b32 m0, s84
	ds_read_b128 v[180:183], v143 offset:16384
	ds_read_b128 v[184:187], v143 offset:17408
	ds_read_b128 v[192:195], v143 offset:18432
	ds_read_b128 v[196:199], v143 offset:19456
	ds_read_b128 v[200:203], v143 offset:20480
	ds_read_b128 v[204:207], v143 offset:21504
	ds_read_b128 v[208:211], v143 offset:22528
	ds_read_b128 v[212:215], v143 offset:23552
	global_load_lds_dwordx4 v[216:217], off
	v_lshl_add_u64 v[220:221], v[216:217], 0, s[6:7]
	s_add_i32 m0, s84, 0x2000
	s_add_i32 s84, s75, s14
	global_load_lds_dwordx4 v[220:221], off
	v_lshl_add_u64 v[220:221], v[216:217], 0, s[8:9]
	s_mov_b32 m0, s84
	s_nop 0
	global_load_lds_dwordx4 v[220:221], off
	v_lshl_add_u64 v[220:221], v[216:217], 0, s[10:11]
	s_add_i32 m0, s84, 0x2000
	s_nop 0
	global_load_lds_dwordx4 v[220:221], off
	v_lshl_add_u64 v[220:221], s[78:79], 0, v[190:191]
	s_mov_b32 m0, s18
	v_lshl_add_u64 v[222:223], v[220:221], 0, s[6:7]
	global_load_lds_dwordx4 v[220:221], off
	s_mov_b32 m0, s19
	s_nop 0
	global_load_lds_dwordx4 v[222:223], off
	s_waitcnt vmcnt(8)
	s_waitcnt lgkmcnt(0)
	s_barrier
; #define PG8_STAGE(bufoff, gbase, voff) do { _Pragma("unroll") for (int _i = 0; _i < 2; ++_i) \
;         __builtin_amdgcn_global_load_lds((const unsigned*)((const char*)(gbase) + (voff)[_i]), (PG8_LAS unsigned*)(lds + (bufoff) + ldsw + _i * 8192), 16, 0, 0); } while (0)
; #define PG8_LDA(dst, b, h) do { _Pragma("unroll") for (int m = 0; m < 4; ++m) _Pragma("unroll") for (int k = 0; k < 2; ++k) dst[m][k] = *(const PG8_LAS bf16x8*)(lds + PG8_SA(b, h) + aoff + m * 2048 + k * 1024); } while (0)
; #define PG8_LDB(dst, b, h) do { _Pragma("unroll") for (int n = 0; n < 2; ++n) _Pragma("unroll") for (int k = 0; k < 2; ++k) dst[n][k] = *(const PG8_LAS bf16x8*)(lds + PG8_SB(b, h) + boff + n * 2048 + k * 1024); } while (0)
; #define PG8_MMA(ai, bj, At, Bt) do { __builtin_amdgcn_s_setprio(1); _Pragma("unroll") for (int m = 0; m < 4; ++m) _Pragma("unroll") for (int n = 0; n < 2; ++n) _Pragma("unroll") for (int k = 0; k < 2; ++k) \
;         acc[ai][bj][m][n] = __builtin_amdgcn_mfma_f32_16x16x32_bf16(Bt[n][k], At[m][k], acc[ai][bj][m][n], 0, 0, 0); __builtin_amdgcn_s_setprio(0); } while (0)
; #define PG8_WAIT_V(n) asm volatile("s_waitcnt vmcnt(" #n ")" ::: "memory")
; #define PG8_WAIT_L(n) asm volatile("s_waitcnt lgkmcnt(" #n ")" ::: "memory")
; #define PG8_BAR __builtin_amdgcn_s_barrier()
; #define PG8_SCHED __builtin_amdgcn_sched_barrier(0)
; template <class Epi, class Sched, bool ALIGN_EPI = false, bool SP2 = false>
; __device__ __forceinline__ void gemm_phase(PG8_LAS unsigned char* lds, const Gemm g, const Sched& S, const Epi& E) {
;     ...
;             PG8_WAIT_V(8); PG8_WAIT_L(0); PG8_BAR; PG8_MMA(1, 0, At, B0); PG8_MMA(1, 1, At, B1); PG8_BAR; PG8_SCHED;
;             PG8_LDB(B0, 1, 0); PG8_LDB(B1, 1, 1); PG8_SCHED; PG8_LDA(At, 1, 0); PG8_STAGE(PG8_SA(0, 1), a2 + hstepA, voffA);
;             PG8_WAIT_V(8); PG8_WAIT_L(0); PG8_BAR; PG8_MMA(0, 0, At, B0); PG8_MMA(0, 1, At, B1); PG8_BAR; PG8_SCHED;
	s_waitcnt lgkmcnt(0)
	v_mfma_f32_16x16x32_bf16 v[60:63], v[148:151], v[180:183], 0
	v_mfma_f32_16x16x32_bf16 v[52:55], v[156:159], v[180:183], 0
	v_mfma_f32_16x16x32_bf16 v[44:47], v[148:151], v[192:195], 0
	v_mfma_f32_16x16x32_bf16 v[36:39], v[156:159], v[192:195], 0
	v_mfma_f32_16x16x32_bf16 v[28:31], v[148:151], v[200:203], 0
	v_mfma_f32_16x16x32_bf16 v[20:23], v[156:159], v[200:203], 0
	v_mfma_f32_16x16x32_bf16 v[12:15], v[148:151], v[208:211], 0
	v_mfma_f32_16x16x32_bf16 v[4:7], v[156:159], v[208:211], 0
	v_mfma_f32_16x16x32_bf16 v[60:63], v[152:155], v[184:187], v[60:63]
	v_mfma_f32_16x16x32_bf16 v[52:55], v[160:163], v[184:187], v[52:55]
	v_mfma_f32_16x16x32_bf16 v[44:47], v[152:155], v[196:199], v[44:47]
	v_mfma_f32_16x16x32_bf16 v[36:39], v[160:163], v[196:199], v[36:39]
	v_mfma_f32_16x16x32_bf16 v[28:31], v[152:155], v[204:207], v[28:31]
	v_mfma_f32_16x16x32_bf16 v[20:23], v[160:163], v[204:207], v[20:23]
	v_mfma_f32_16x16x32_bf16 v[12:15], v[152:155], v[212:215], v[12:15]
	v_mfma_f32_16x16x32_bf16 v[4:7], v[160:163], v[212:215], v[4:7]
	v_mfma_f32_16x16x32_bf16 v[56:59], v[164:167], v[180:183], 0
	v_mfma_f32_16x16x32_bf16 v[48:51], v[172:175], v[180:183], 0
	v_mfma_f32_16x16x32_bf16 v[40:43], v[164:167], v[192:195], 0
	v_mfma_f32_16x16x32_bf16 v[32:35], v[172:175], v[192:195], 0
	v_mfma_f32_16x16x32_bf16 v[24:27], v[164:167], v[200:203], 0
	v_mfma_f32_16x16x32_bf16 v[16:19], v[172:175], v[200:203], 0
	v_mfma_f32_16x16x32_bf16 v[8:11], v[164:167], v[208:211], 0
	v_mfma_f32_16x16x32_bf16 v[0:3], v[172:175], v[208:211], 0
	v_mfma_f32_16x16x32_bf16 v[56:59], v[168:171], v[184:187], v[56:59]
	v_mfma_f32_16x16x32_bf16 v[48:51], v[176:179], v[184:187], v[48:51]
	v_mfma_f32_16x16x32_bf16 v[40:43], v[168:171], v[196:199], v[40:43]
	v_mfma_f32_16x16x32_bf16 v[32:35], v[176:179], v[196:199], v[32:35]
	v_mfma_f32_16x16x32_bf16 v[24:27], v[168:171], v[204:207], v[24:27]
	v_mfma_f32_16x16x32_bf16 v[16:19], v[176:179], v[204:207], v[16:19]
	v_mfma_f32_16x16x32_bf16 v[8:11], v[168:171], v[212:215], v[8:11]
	v_mfma_f32_16x16x32_bf16 v[0:3], v[176:179], v[212:215], v[0:3]
	s_barrier
	ds_read_b128 v[148:151], v144
	ds_read_b128 v[152:155], v144 offset:1024
	ds_read_b128 v[156:159], v144 offset:2048
	ds_read_b128 v[160:163], v144 offset:3072
	ds_read_b128 v[164:167], v145
	ds_read_b128 v[168:171], v145 offset:1024
	ds_read_b128 v[172:175], v145 offset:2048
	ds_read_b128 v[176:179], v145 offset:3072
	s_mov_b32 m0, s66
	v_lshl_add_u64 v[222:223], v[220:221], 0, s[8:9]
	ds_read_b128 v[180:183], v143 offset:32768
	ds_read_b128 v[184:187], v143 offset:33792
	ds_read_b128 v[192:195], v143 offset:34816
	ds_read_b128 v[196:199], v143 offset:35840
	ds_read_b128 v[200:203], v143 offset:36864
	ds_read_b128 v[204:207], v143 offset:37888
	ds_read_b128 v[208:211], v143 offset:38912
	ds_read_b128 v[212:215], v143 offset:39936
	global_load_lds_dwordx4 v[222:223], off
	v_lshl_add_u64 v[222:223], v[220:221], 0, s[10:11]
	s_mov_b32 m0, s67
	s_nop 0
	global_load_lds_dwordx4 v[222:223], off
	s_waitcnt vmcnt(8)
	s_waitcnt lgkmcnt(0)
	s_barrier
	s_waitcnt lgkmcnt(0)
	v_mfma_f32_16x16x32_bf16 v[116:119], v[148:151], v[180:183], v[116:119]
	v_mfma_f32_16x16x32_bf16 v[112:115], v[156:159], v[180:183], v[112:115]
	v_mfma_f32_16x16x32_bf16 v[108:111], v[148:151], v[192:195], v[108:111]
	v_mfma_f32_16x16x32_bf16 v[100:103], v[156:159], v[192:195], v[100:103]
	v_mfma_f32_16x16x32_bf16 v[92:95], v[148:151], v[200:203], v[92:95]
	v_mfma_f32_16x16x32_bf16 v[84:87], v[156:159], v[200:203], v[84:87]
	v_mfma_f32_16x16x32_bf16 v[76:79], v[148:151], v[208:211], v[76:79]
	v_mfma_f32_16x16x32_bf16 v[68:71], v[156:159], v[208:211], v[68:71]
	v_mfma_f32_16x16x32_bf16 v[116:119], v[152:155], v[184:187], v[116:119]
	v_mfma_f32_16x16x32_bf16 v[112:115], v[160:163], v[184:187], v[112:115]
	v_mfma_f32_16x16x32_bf16 v[108:111], v[152:155], v[196:199], v[108:111]
	v_mfma_f32_16x16x32_bf16 v[100:103], v[160:163], v[196:199], v[100:103]
	v_mfma_f32_16x16x32_bf16 v[92:95], v[152:155], v[204:207], v[92:95]
	v_mfma_f32_16x16x32_bf16 v[84:87], v[160:163], v[204:207], v[84:87]
	v_mfma_f32_16x16x32_bf16 v[76:79], v[152:155], v[212:215], v[76:79]
	v_mfma_f32_16x16x32_bf16 v[68:71], v[160:163], v[212:215], v[68:71]
	v_mfma_f32_16x16x32_bf16 v[124:127], v[164:167], v[180:183], v[124:127]
	v_mfma_f32_16x16x32_bf16 v[120:123], v[172:175], v[180:183], v[120:123]
	v_mfma_f32_16x16x32_bf16 v[104:107], v[164:167], v[192:195], v[104:107]
	v_mfma_f32_16x16x32_bf16 v[96:99], v[172:175], v[192:195], v[96:99]
	v_mfma_f32_16x16x32_bf16 v[88:91], v[164:167], v[200:203], v[88:91]
	v_mfma_f32_16x16x32_bf16 v[80:83], v[172:175], v[200:203], v[80:83]
	v_mfma_f32_16x16x32_bf16 v[72:75], v[164:167], v[208:211], v[72:75]
	v_mfma_f32_16x16x32_bf16 v[64:67], v[172:175], v[208:211], v[64:67]
	v_mfma_f32_16x16x32_bf16 v[124:127], v[168:171], v[184:187], v[124:127]
	v_mfma_f32_16x16x32_bf16 v[120:123], v[176:179], v[184:187], v[120:123]
	v_mfma_f32_16x16x32_bf16 v[104:107], v[168:171], v[196:199], v[104:107]
	v_mfma_f32_16x16x32_bf16 v[96:99], v[176:179], v[196:199], v[96:99]
	v_mfma_f32_16x16x32_bf16 v[88:91], v[168:171], v[204:207], v[88:91]
	v_mfma_f32_16x16x32_bf16 v[80:83], v[176:179], v[204:207], v[80:83]
	v_mfma_f32_16x16x32_bf16 v[72:75], v[168:171], v[212:215], v[72:75]
	v_mfma_f32_16x16x32_bf16 v[64:67], v[176:179], v[212:215], v[64:67]
	s_barrier
; #define PG8_STAGE(bufoff, gbase, voff) do { _Pragma("unroll") for (int _i = 0; _i < 2; ++_i) \
;         __builtin_amdgcn_global_load_lds((const unsigned*)((const char*)(gbase) + (voff)[_i]), (PG8_LAS unsigned*)(lds + (bufoff) + ldsw + _i * 8192), 16, 0, 0); } while (0)
; #define PG8_LDA(dst, b, h) do { _Pragma("unroll") for (int m = 0; m < 4; ++m) _Pragma("unroll") for (int k = 0; k < 2; ++k) dst[m][k] = *(const PG8_LAS bf16x8*)(lds + PG8_SA(b, h) + aoff + m * 2048 + k * 1024); } while (0)
; #define PG8_MMA(ai, bj, At, Bt) do { __builtin_amdgcn_s_setprio(1); _Pragma("unroll") for (int m = 0; m < 4; ++m) _Pragma("unroll") for (int n = 0; n < 2; ++n) _Pragma("unroll") for (int k = 0; k < 2; ++k) \
;         acc[ai][bj][m][n] = __builtin_amdgcn_mfma_f32_16x16x32_bf16(Bt[n][k], At[m][k], acc[ai][bj][m][n], 0, 0, 0); __builtin_amdgcn_s_setprio(0); } while (0)
; #define PG8_WAIT_V(n) asm volatile("s_waitcnt vmcnt(" #n ")" ::: "memory")
; #define PG8_WAIT_L(n) asm volatile("s_waitcnt lgkmcnt(" #n ")" ::: "memory")
; #define PG8_BAR __builtin_amdgcn_s_barrier()
; #define PG8_SCHED __builtin_amdgcn_sched_barrier(0)
; template <class Epi, class Sched, bool ALIGN_EPI = false, bool SP2 = false>
; __device__ __forceinline__ void gemm_phase(PG8_LAS unsigned char* lds, const Gemm g, const Sched& S, const Epi& E) {
;     ...
;             PG8_LDA(At, 1, 1); PG8_STAGE(PG8_SB(1, 0), b3, voffB); PG8_STAGE(PG8_SB(1, 1), b3 + hstepB, voffB); PG8_STAGE(PG8_SA(1, 0), a3, voffA);
;             PG8_WAIT_V(8); PG8_WAIT_L(0); PG8_BAR; PG8_MMA(1, 0, At, B0); PG8_MMA(1, 1, At, B1); PG8_BAR; PG8_SCHED;
	s_add_i32 s78, s76, s14
	v_lshl_add_u64 v[222:223], v[216:217], 0, s[34:35]
	s_mov_b32 m0, s78
	ds_read_b128 v[180:183], v143 offset:49152
	ds_read_b128 v[184:187], v143 offset:50176
	ds_read_b128 v[192:195], v143 offset:51200
	ds_read_b128 v[196:199], v143 offset:52224
	ds_read_b128 v[200:203], v143 offset:53248
	ds_read_b128 v[204:207], v143 offset:54272
	ds_read_b128 v[208:211], v143 offset:55296
	ds_read_b128 v[212:215], v143 offset:56320
	global_load_lds_dwordx4 v[222:223], off
	v_lshl_add_u64 v[222:223], v[216:217], 0, s[36:37]
	s_add_i32 m0, s78, 0x2000
	s_add_i32 s78, s77, s14
	global_load_lds_dwordx4 v[222:223], off
	v_lshl_add_u64 v[222:223], v[216:217], 0, s[38:39]
	s_mov_b32 m0, s78
	v_lshl_add_u64 v[216:217], v[216:217], 0, s[40:41]
	global_load_lds_dwordx4 v[222:223], off
	s_add_i32 m0, s78, 0x2000
	s_nop 0
	global_load_lds_dwordx4 v[216:217], off
	v_lshl_add_u64 v[216:217], v[220:221], 0, s[34:35]
	s_mov_b32 m0, s68
	s_nop 0
	global_load_lds_dwordx4 v[216:217], off
	v_lshl_add_u64 v[216:217], v[220:221], 0, s[36:37]
	s_mov_b32 m0, s69
	s_nop 0
	global_load_lds_dwordx4 v[216:217], off
	s_waitcnt vmcnt(8)
	s_waitcnt lgkmcnt(0)
	s_barrier
	s_waitcnt lgkmcnt(0)
	v_mfma_f32_16x16x32_bf16 v[60:63], v[148:151], v[180:183], v[60:63]
	v_mfma_f32_16x16x32_bf16 v[52:55], v[156:159], v[180:183], v[52:55]
	v_mfma_f32_16x16x32_bf16 v[44:47], v[148:151], v[192:195], v[44:47]
	v_mfma_f32_16x16x32_bf16 v[36:39], v[156:159], v[192:195], v[36:39]
	v_mfma_f32_16x16x32_bf16 v[28:31], v[148:151], v[200:203], v[28:31]
	v_mfma_f32_16x16x32_bf16 v[20:23], v[156:159], v[200:203], v[20:23]
	v_mfma_f32_16x16x32_bf16 v[12:15], v[148:151], v[208:211], v[12:15]
	v_mfma_f32_16x16x32_bf16 v[4:7], v[156:159], v[208:211], v[4:7]
	v_mfma_f32_16x16x32_bf16 v[60:63], v[152:155], v[184:187], v[60:63]
	v_mfma_f32_16x16x32_bf16 v[52:55], v[160:163], v[184:187], v[52:55]
	v_mfma_f32_16x16x32_bf16 v[44:47], v[152:155], v[196:199], v[44:47]
	v_mfma_f32_16x16x32_bf16 v[36:39], v[160:163], v[196:199], v[36:39]
	v_mfma_f32_16x16x32_bf16 v[28:31], v[152:155], v[204:207], v[28:31]
	v_mfma_f32_16x16x32_bf16 v[20:23], v[160:163], v[204:207], v[20:23]
	v_mfma_f32_16x16x32_bf16 v[12:15], v[152:155], v[212:215], v[12:15]
	v_mfma_f32_16x16x32_bf16 v[4:7], v[160:163], v[212:215], v[4:7]
	v_mfma_f32_16x16x32_bf16 v[56:59], v[164:167], v[180:183], v[56:59]
	v_mfma_f32_16x16x32_bf16 v[48:51], v[172:175], v[180:183], v[48:51]
	v_mfma_f32_16x16x32_bf16 v[40:43], v[164:167], v[192:195], v[40:43]
	v_mfma_f32_16x16x32_bf16 v[32:35], v[172:175], v[192:195], v[32:35]
	v_mfma_f32_16x16x32_bf16 v[24:27], v[164:167], v[200:203], v[24:27]
	v_mfma_f32_16x16x32_bf16 v[16:19], v[172:175], v[200:203], v[16:19]
	v_mfma_f32_16x16x32_bf16 v[8:11], v[164:167], v[208:211], v[8:11]
	v_mfma_f32_16x16x32_bf16 v[0:3], v[172:175], v[208:211], v[0:3]
	v_mfma_f32_16x16x32_bf16 v[56:59], v[168:171], v[184:187], v[56:59]
	v_mfma_f32_16x16x32_bf16 v[48:51], v[176:179], v[184:187], v[48:51]
	v_mfma_f32_16x16x32_bf16 v[40:43], v[168:171], v[196:199], v[40:43]
	v_mfma_f32_16x16x32_bf16 v[32:35], v[176:179], v[196:199], v[32:35]
	v_mfma_f32_16x16x32_bf16 v[24:27], v[168:171], v[204:207], v[24:27]
	v_mfma_f32_16x16x32_bf16 v[16:19], v[176:179], v[204:207], v[16:19]
	v_mfma_f32_16x16x32_bf16 v[8:11], v[168:171], v[212:215], v[8:11]
	v_mfma_f32_16x16x32_bf16 v[0:3], v[176:179], v[212:215], v[0:3]
	s_barrier
	s_add_i32 s82, s82, 2
	s_add_u32 s62, s62, 0x10000
	s_addc_u32 s63, s63, 0
	s_add_u32 s64, s64, 0x10000
	s_addc_u32 s65, s65, 0
	s_cmp_gt_u32 s82, 13

; #define PG8_STAGE(bufoff, gbase, voff) do { _Pragma("unroll") for (int _i = 0; _i < 2; ++_i) \
;         __builtin_amdgcn_global_load_lds((const unsigned*)((const char*)(gbase) + (voff)[_i]), (PG8_LAS unsigned*)(lds + (bufoff) + ldsw + _i * 8192), 16, 0, 0); } while (0)
; #define PG8_LDA(dst, b, h) do { _Pragma("unroll") for (int m = 0; m < 4; ++m) _Pragma("unroll") for (int k = 0; k < 2; ++k) dst[m][k] = *(const PG8_LAS bf16x8*)(lds + PG8_SA(b, h) + aoff + m * 2048 + k * 1024); } while (0)
; #define PG8_LDB(dst, b, h) do { _Pragma("unroll") for (int n = 0; n < 2; ++n) _Pragma("unroll") for (int k = 0; k < 2; ++k) dst[n][k] = *(const PG8_LAS bf16x8*)(lds + PG8_SB(b, h) + boff + n * 2048 + k * 1024); } while (0)
; #define PG8_SCHED __builtin_amdgcn_sched_barrier(0)
;     __host__ __device__ bool next(int i, Unit& u) const {
;         const long L = (long)i * G + c; if (L >= nwg) return false;
;         int wgid = (int)L; { const int q = nwg / NXCD, r = nwg % NXCD, xcd = wgid % NXCD, off = wgid / NXCD; wgid = (xcd < r ? xcd * (q + 1) : r * (q + 1) + (xcd - r) * q) + off; }
;         const int nig = wgm * nN, gid = wgid / nig, fm = gid * wgm, gsz = (nM - fm) < wgm ? (nM - fm) : wgm;
;         u.pm = fm + ((wgid % nig) % gsz); u.pn = (wgid % nig) / gsz; return true;
; template <class Epi, class Sched, bool ALIGN_EPI = false, bool SP2 = false>
; __device__ __forceinline__ void gemm_phase(PG8_LAS unsigned char* lds, const Gemm g, const Sched& S, const Epi& E) {
;     ...
;         const bool has_next = S.next(ui + 1, nxt);
;         const char* nA = has_next ? (const char*)g.A + (size_t)nxt.pm * tstepA : cA; const char* nB = has_next ? (const char*)g.Bt + (size_t)nxt.pn * tstepB : cB;
;         for (int t = 0; t < nt; t += 2) {
;             const bool last = (t == nt - 2);
;             const char* a1 = cA + (size_t)(t + 1) * kstepA;
;             const char* a2 = last ? nA : cA + (size_t)(t + 2) * kstepA; const char* b2 = last ? nB : cB + (size_t)(t + 2) * kstep;
;             const char* a3 = a2 + kstepA; const char* b3 = b2 + kstep;
;             if (last && has_next) S.a_ready(nxt);
;             if constexpr (SP2) {
;             PG8_LDB(B0, 0, 0); PG8_LDB(B1, 0, 1); PG8_SCHED; PG8_LDA(At, 0, 0); PG8_STAGE(PG8_SA(1, 1), a1 + hstepA, voffA);
.LBB0_913:
	ds_read_b128 v[84:87], v221
	ds_read_b128 v[92:95], v221 offset:1024
	ds_read_b128 v[104:107], v221 offset:2048
	ds_read_b128 v[116:119], v221 offset:3072
	ds_read_b128 v[128:131], v222
	ds_read_b128 v[140:143], v222 offset:1024
	ds_read_b128 v[152:155], v222 offset:2048
	ds_read_b128 v[156:159], v222 offset:3072
	ds_read_b128 v[160:163], v223
	ds_read_b128 v[164:167], v223 offset:1024
	ds_read_b128 v[168:171], v223 offset:2048
	ds_read_b128 v[172:175], v223 offset:3072
	ds_read_b128 v[176:179], v223 offset:4096
	ds_read_b128 v[180:183], v223 offset:5120
	ds_read_b128 v[184:187], v223 offset:6144
	ds_read_b128 v[212:215], v223 offset:7168
	s_add_i32 s76, s76, 1
	s_mul_i32 s0, s76, s78
	s_mul_hi_u32 s1, s76, s79
	s_add_i32 s1, s1, s0
	s_mul_i32 s0, s76, s79
	s_add_u32 s4, s0, s16
	s_addc_u32 s5, s1, s80
	v_cmp_gt_i64_e32 vcc, s[4:5], v[210:211]
	v_cmp_lt_i64_e64 s[0:1], s[4:5], v[208:209]
	s_cbranch_vccnz .LBB0_919
	s_ashr_i32 s5, s4, 31
	s_lshr_b32 s5, s5, 29
	s_add_i32 s62, s4, s5
	s_and_b32 s5, s62, -8
	s_sub_i32 s63, s4, s5
	s_cmp_gt_i32 s63, -1
	s_mov_b64 s[4:5], -1
	s_cbranch_scc0 .LBB0_916
	s_lshl_b32 s66, s63, 6
	s_mov_b64 s[4:5], 0

; #define PG8_STAGE(bufoff, gbase, voff) do { _Pragma("unroll") for (int _i = 0; _i < 2; ++_i) \
;         __builtin_amdgcn_global_load_lds((const unsigned*)((const char*)(gbase) + (voff)[_i]), (PG8_LAS unsigned*)(lds + (bufoff) + ldsw + _i * 8192), 16, 0, 0); } while (0)
; #define PG8_LDA(dst, b, h) do { _Pragma("unroll") for (int m = 0; m < 4; ++m) _Pragma("unroll") for (int k = 0; k < 2; ++k) dst[m][k] = *(const PG8_LAS bf16x8*)(lds + PG8_SA(b, h) + aoff + m * 2048 + k * 1024); } while (0)
; #define PG8_LDB(dst, b, h) do { _Pragma("unroll") for (int n = 0; n < 2; ++n) _Pragma("unroll") for (int k = 0; k < 2; ++k) dst[n][k] = *(const PG8_LAS bf16x8*)(lds + PG8_SB(b, h) + boff + n * 2048 + k * 1024); } while (0)
; #define PG8_MMA(ai, bj, At, Bt) do { __builtin_amdgcn_s_setprio(1); _Pragma("unroll") for (int m = 0; m < 4; ++m) _Pragma("unroll") for (int n = 0; n < 2; ++n) _Pragma("unroll") for (int k = 0; k < 2; ++k) \
;         acc[ai][bj][m][n] = __builtin_amdgcn_mfma_f32_16x16x32_bf16(Bt[n][k], At[m][k], acc[ai][bj][m][n], 0, 0, 0); __builtin_amdgcn_s_setprio(0); } while (0)
; #define PG8_WAIT_V(n) asm volatile("s_waitcnt vmcnt(" #n ")" ::: "memory")
; #define PG8_WAIT_L(n) asm volatile("s_waitcnt lgkmcnt(" #n ")" ::: "memory")
; template <class Epi, class Sched, bool ALIGN_EPI = false, bool SP2 = false>
; __device__ __forceinline__ void gemm_phase(PG8_LAS unsigned char* lds, const Gemm g, const Sched& S, const Epi& E) {
;     ...
;             const bool last = (t == nt - 2);
;             const char* a1 = cA + (size_t)(t + 1) * kstepA;
;             const char* a2 = last ? nA : cA + (size_t)(t + 2) * kstepA; const char* b2 = last ? nB : cB + (size_t)(t + 2) * kstep;
;             const char* a3 = a2 + kstepA; const char* b3 = b2 + kstep;
;             if (last && has_next) S.a_ready(nxt);
;             if constexpr (SP2) {
;             PG8_LDB(B0, 0, 0); PG8_LDB(B1, 0, 1); PG8_SCHED; PG8_LDA(At, 0, 0); PG8_STAGE(PG8_SA(1, 1), a1 + hstepA, voffA);
;             PG8_WAIT_V(8); PG8_WAIT_L(0); PG8_BAR; PG8_MMA(0, 0, At, B0); PG8_MMA(0, 1, At, B1); PG8_BAR; PG8_SCHED;
;             PG8_LDA(At, 0, 1); PG8_STAGE(PG8_SB(0, 0), b2, voffB); PG8_STAGE(PG8_SB(0, 1), b2 + hstepB, voffB); PG8_STAGE(PG8_SA(0, 0), a2, voffA);
;             PG8_WAIT_V(8); PG8_WAIT_L(0); PG8_BAR; PG8_MMA(1, 0, At, B0); PG8_MMA(1, 1, At, B1); PG8_BAR; PG8_SCHED;
.LBB0_923:
	s_add_u32 s6, s6, 0x10000
	s_addc_u32 s7, s7, 0
	s_add_u32 s64, s64, 0x10000
	s_addc_u32 s65, s65, 0
	s_mov_b32 s66, -2
	s_waitcnt lgkmcnt(0)
	s_cmp_eq_u32 s66, 40
	s_cselect_b32 s69, s1, s7
	s_cselect_b32 s68, s0, s6
	s_cselect_b32 s71, s63, s65
	s_cselect_b32 s70, s62, s64
	v_lshl_add_u64 v[216:217], s[6:7], 0, v[190:191]
	v_lshl_add_u64 v[228:229], v[216:217], 0, s[58:59]
	s_add_i32 m0, s15, 0xc000
	global_load_lds_dwordx4 v[228:229], off
	v_lshl_add_u64 v[216:217], v[216:217], 0, s[60:61]
	s_add_i32 m0, s15, 0xe000
	s_nop 0
	global_load_lds_dwordx4 v[216:217], off
	s_waitcnt vmcnt(8)
	s_waitcnt lgkmcnt(0)
	s_barrier
	s_waitcnt lgkmcnt(0)
	v_mfma_f32_16x16x32_bf16 v[148:151], v[84:87], v[160:163], 0
	v_mfma_f32_16x16x32_bf16 v[144:147], v[104:107], v[160:163], 0
	v_mfma_f32_16x16x32_bf16 v[124:127], v[84:87], v[168:171], 0
	v_mfma_f32_16x16x32_bf16 v[120:123], v[104:107], v[168:171], 0
	v_mfma_f32_16x16x32_bf16 v[100:103], v[84:87], v[176:179], 0
	v_mfma_f32_16x16x32_bf16 v[96:99], v[104:107], v[176:179], 0
	v_mfma_f32_16x16x32_bf16 v[76:79], v[84:87], v[184:187], 0
	v_mfma_f32_16x16x32_bf16 v[72:75], v[104:107], v[184:187], 0
	v_mfma_f32_16x16x32_bf16 v[148:151], v[92:95], v[164:167], v[148:151]
	v_mfma_f32_16x16x32_bf16 v[144:147], v[116:119], v[164:167], v[144:147]
	v_mfma_f32_16x16x32_bf16 v[124:127], v[92:95], v[172:175], v[124:127]
	v_mfma_f32_16x16x32_bf16 v[120:123], v[116:119], v[172:175], v[120:123]
	v_mfma_f32_16x16x32_bf16 v[100:103], v[92:95], v[180:183], v[100:103]
	v_mfma_f32_16x16x32_bf16 v[96:99], v[116:119], v[180:183], v[96:99]
	v_mfma_f32_16x16x32_bf16 v[76:79], v[92:95], v[212:215], v[76:79]
	v_mfma_f32_16x16x32_bf16 v[72:75], v[116:119], v[212:215], v[72:75]
	v_mfma_f32_16x16x32_bf16 v[136:139], v[128:131], v[160:163], 0
	v_mfma_f32_16x16x32_bf16 v[132:135], v[152:155], v[160:163], 0
	v_mfma_f32_16x16x32_bf16 v[112:115], v[128:131], v[168:171], 0
	v_mfma_f32_16x16x32_bf16 v[108:111], v[152:155], v[168:171], 0
	v_mfma_f32_16x16x32_bf16 v[88:91], v[128:131], v[176:179], 0
	v_mfma_f32_16x16x32_bf16 v[80:83], v[152:155], v[176:179], 0
	v_mfma_f32_16x16x32_bf16 v[68:71], v[128:131], v[184:187], 0
	v_mfma_f32_16x16x32_bf16 v[64:67], v[152:155], v[184:187], 0
	v_mfma_f32_16x16x32_bf16 v[136:139], v[140:143], v[164:167], v[136:139]
	v_mfma_f32_16x16x32_bf16 v[132:135], v[156:159], v[164:167], v[132:135]
	v_mfma_f32_16x16x32_bf16 v[112:115], v[140:143], v[172:175], v[112:115]
	v_mfma_f32_16x16x32_bf16 v[108:111], v[156:159], v[172:175], v[108:111]
	v_mfma_f32_16x16x32_bf16 v[88:91], v[140:143], v[180:183], v[88:91]
	v_mfma_f32_16x16x32_bf16 v[80:83], v[156:159], v[180:183], v[80:83]
	v_mfma_f32_16x16x32_bf16 v[68:71], v[140:143], v[212:215], v[68:71]
	v_mfma_f32_16x16x32_bf16 v[64:67], v[156:159], v[212:215], v[64:67]
	s_barrier
	s_add_i32 s33, s81, s14
	v_lshl_add_u64 v[216:217], s[70:71], 0, v[190:191]
	s_mov_b32 m0, s33
	ds_read_b128 v[160:163], v223 offset:16384
	ds_read_b128 v[164:167], v223 offset:17408
	ds_read_b128 v[168:171], v223 offset:18432
	ds_read_b128 v[172:175], v223 offset:19456
	ds_read_b128 v[176:179], v223 offset:20480
	ds_read_b128 v[180:183], v223 offset:21504
	ds_read_b128 v[184:187], v223 offset:22528
	ds_read_b128 v[212:215], v223 offset:23552
	global_load_lds_dwordx4 v[216:217], off
	v_lshl_add_u64 v[228:229], v[216:217], 0, s[8:9]
	s_add_i32 m0, s33, 0x2000
	s_add_i32 s33, s82, s14
	global_load_lds_dwordx4 v[228:229], off
	v_lshl_add_u64 v[228:229], v[216:217], 0, s[10:11]
	s_mov_b32 m0, s33
	s_nop 0
	global_load_lds_dwordx4 v[228:229], off
	v_lshl_add_u64 v[228:229], v[216:217], 0, s[40:41]
	s_add_i32 m0, s33, 0x2000
	s_nop 0
	global_load_lds_dwordx4 v[228:229], off
	v_lshl_add_u64 v[228:229], s[68:69], 0, v[190:191]
	s_mov_b32 m0, s15
	v_lshl_add_u64 v[230:231], v[228:229], 0, s[8:9]
	global_load_lds_dwordx4 v[228:229], off
	s_mov_b32 m0, s17
	s_nop 0
	global_load_lds_dwordx4 v[230:231], off
	s_waitcnt vmcnt(8)
	s_waitcnt lgkmcnt(0)
	s_barrier
	s_waitcnt lgkmcnt(0)
	v_mfma_f32_16x16x32_bf16 v[60:63], v[84:87], v[160:163], 0
	v_mfma_f32_16x16x32_bf16 v[56:59], v[104:107], v[160:163], 0
	v_mfma_f32_16x16x32_bf16 v[44:47], v[84:87], v[168:171], 0
	v_mfma_f32_16x16x32_bf16 v[40:43], v[104:107], v[168:171], 0
	v_mfma_f32_16x16x32_bf16 v[28:31], v[84:87], v[176:179], 0
	v_mfma_f32_16x16x32_bf16 v[24:27], v[104:107], v[176:179], 0
	v_mfma_f32_16x16x32_bf16 v[12:15], v[84:87], v[184:187], 0
	v_mfma_f32_16x16x32_bf16 v[8:11], v[104:107], v[184:187], 0
	v_mfma_f32_16x16x32_bf16 v[60:63], v[92:95], v[164:167], v[60:63]
	v_mfma_f32_16x16x32_bf16 v[56:59], v[116:119], v[164:167], v[56:59]
	v_mfma_f32_16x16x32_bf16 v[44:47], v[92:95], v[172:175], v[44:47]
	v_mfma_f32_16x16x32_bf16 v[40:43], v[116:119], v[172:175], v[40:43]
	v_mfma_f32_16x16x32_bf16 v[28:31], v[92:95], v[180:183], v[28:31]
	v_mfma_f32_16x16x32_bf16 v[24:27], v[116:119], v[180:183], v[24:27]
	v_mfma_f32_16x16x32_bf16 v[12:15], v[92:95], v[212:215], v[12:15]
	v_mfma_f32_16x16x32_bf16 v[8:11], v[116:119], v[212:215], v[8:11]
	v_mfma_f32_16x16x32_bf16 v[52:55], v[128:131], v[160:163], 0
	v_mfma_f32_16x16x32_bf16 v[48:51], v[152:155], v[160:163], 0
	v_mfma_f32_16x16x32_bf16 v[36:39], v[128:131], v[168:171], 0
	v_mfma_f32_16x16x32_bf16 v[32:35], v[152:155], v[168:171], 0
	v_mfma_f32_16x16x32_bf16 v[20:23], v[128:131], v[176:179], 0
	v_mfma_f32_16x16x32_bf16 v[16:19], v[152:155], v[176:179], 0
	v_mfma_f32_16x16x32_bf16 v[4:7], v[128:131], v[184:187], 0
	v_mfma_f32_16x16x32_bf16 v[0:3], v[152:155], v[184:187], 0
	v_mfma_f32_16x16x32_bf16 v[52:55], v[140:143], v[164:167], v[52:55]
	v_mfma_f32_16x16x32_bf16 v[48:51], v[156:159], v[164:167], v[48:51]
	v_mfma_f32_16x16x32_bf16 v[36:39], v[140:143], v[172:175], v[36:39]
	v_mfma_f32_16x16x32_bf16 v[32:35], v[156:159], v[172:175], v[32:35]
	v_mfma_f32_16x16x32_bf16 v[20:23], v[140:143], v[180:183], v[20:23]
	v_mfma_f32_16x16x32_bf16 v[16:19], v[156:159], v[180:183], v[16:19]
	v_mfma_f32_16x16x32_bf16 v[4:7], v[140:143], v[212:215], v[4:7]
	v_mfma_f32_16x16x32_bf16 v[0:3], v[156:159], v[212:215], v[0:3]
	s_barrier
; #define PG8_STAGE(bufoff, gbase, voff) do { _Pragma("unroll") for (int _i = 0; _i < 2; ++_i) \
;         __builtin_amdgcn_global_load_lds((const unsigned*)((const char*)(gbase) + (voff)[_i]), (PG8_LAS unsigned*)(lds + (bufoff) + ldsw + _i * 8192), 16, 0, 0); } while (0)
; #define PG8_LDA(dst, b, h) do { _Pragma("unroll") for (int m = 0; m < 4; ++m) _Pragma("unroll") for (int k = 0; k < 2; ++k) dst[m][k] = *(const PG8_LAS bf16x8*)(lds + PG8_SA(b, h) + aoff + m * 2048 + k * 1024); } while (0)
; #define PG8_LDB(dst, b, h) do { _Pragma("unroll") for (int n = 0; n < 2; ++n) _Pragma("unroll") for (int k = 0; k < 2; ++k) dst[n][k] = *(const PG8_LAS bf16x8*)(lds + PG8_SB(b, h) + boff + n * 2048 + k * 1024); } while (0)
; #define PG8_MMA(ai, bj, At, Bt) do { __builtin_amdgcn_s_setprio(1); _Pragma("unroll") for (int m = 0; m < 4; ++m) _Pragma("unroll") for (int n = 0; n < 2; ++n) _Pragma("unroll") for (int k = 0; k < 2; ++k) \
;         acc[ai][bj][m][n] = __builtin_amdgcn_mfma_f32_16x16x32_bf16(Bt[n][k], At[m][k], acc[ai][bj][m][n], 0, 0, 0); __builtin_amdgcn_s_setprio(0); } while (0)
; #define PG8_WAIT_V(n) asm volatile("s_waitcnt vmcnt(" #n ")" ::: "memory")
; #define PG8_WAIT_L(n) asm volatile("s_waitcnt lgkmcnt(" #n ")" ::: "memory")
; #define PG8_BAR __builtin_amdgcn_s_barrier()
; #define PG8_SCHED __builtin_amdgcn_sched_barrier(0)
; template <class Epi, class Sched, bool ALIGN_EPI = false, bool SP2 = false>
; __device__ __forceinline__ void gemm_phase(PG8_LAS unsigned char* lds, const Gemm g, const Sched& S, const Epi& E) {
;     ...
;             PG8_LDB(B0, 1, 0); PG8_LDB(B1, 1, 1); PG8_SCHED; PG8_LDA(At, 1, 0); PG8_STAGE(PG8_SA(0, 1), a2 + hstepA, voffA);
;             PG8_WAIT_V(8); PG8_WAIT_L(0); PG8_BAR; PG8_MMA(0, 0, At, B0); PG8_MMA(0, 1, At, B1); PG8_BAR; PG8_SCHED;
;             PG8_LDA(At, 1, 1); PG8_STAGE(PG8_SB(1, 0), b3, voffB); PG8_STAGE(PG8_SB(1, 1), b3 + hstepB, voffB); PG8_STAGE(PG8_SA(1, 0), a3, voffA);
;             PG8_WAIT_V(8); PG8_WAIT_L(0); PG8_BAR; PG8_MMA(1, 0, At, B0); PG8_MMA(1, 1, At, B1); PG8_BAR; PG8_SCHED;
	ds_read_b128 v[84:87], v224
	ds_read_b128 v[92:95], v224 offset:1024
	ds_read_b128 v[104:107], v224 offset:2048
	ds_read_b128 v[116:119], v224 offset:3072
	ds_read_b128 v[128:131], v225
	ds_read_b128 v[140:143], v225 offset:1024
	ds_read_b128 v[152:155], v225 offset:2048
	ds_read_b128 v[156:159], v225 offset:3072
	s_mov_b32 m0, s18
	v_lshl_add_u64 v[230:231], v[228:229], 0, s[10:11]
	ds_read_b128 v[160:163], v223 offset:32768
	ds_read_b128 v[164:167], v223 offset:33792
	ds_read_b128 v[168:171], v223 offset:34816
	ds_read_b128 v[172:175], v223 offset:35840
	ds_read_b128 v[176:179], v223 offset:36864
	ds_read_b128 v[180:183], v223 offset:37888
	ds_read_b128 v[184:187], v223 offset:38912
	ds_read_b128 v[212:215], v223 offset:39936
	global_load_lds_dwordx4 v[230:231], off
	v_lshl_add_u64 v[230:231], v[228:229], 0, s[40:41]
	s_mov_b32 m0, s19
	s_nop 0
	global_load_lds_dwordx4 v[230:231], off
	s_waitcnt vmcnt(8)
	s_waitcnt lgkmcnt(0)
	s_barrier
	s_waitcnt lgkmcnt(0)
	v_mfma_f32_16x16x32_bf16 v[148:151], v[84:87], v[160:163], v[148:151]
	v_mfma_f32_16x16x32_bf16 v[144:147], v[104:107], v[160:163], v[144:147]
	v_mfma_f32_16x16x32_bf16 v[124:127], v[84:87], v[168:171], v[124:127]
	v_mfma_f32_16x16x32_bf16 v[120:123], v[104:107], v[168:171], v[120:123]
	v_mfma_f32_16x16x32_bf16 v[100:103], v[84:87], v[176:179], v[100:103]
	v_mfma_f32_16x16x32_bf16 v[96:99], v[104:107], v[176:179], v[96:99]
	v_mfma_f32_16x16x32_bf16 v[76:79], v[84:87], v[184:187], v[76:79]
	v_mfma_f32_16x16x32_bf16 v[72:75], v[104:107], v[184:187], v[72:75]
	v_mfma_f32_16x16x32_bf16 v[148:151], v[92:95], v[164:167], v[148:151]
	v_mfma_f32_16x16x32_bf16 v[144:147], v[116:119], v[164:167], v[144:147]
	v_mfma_f32_16x16x32_bf16 v[124:127], v[92:95], v[172:175], v[124:127]
	v_mfma_f32_16x16x32_bf16 v[120:123], v[116:119], v[172:175], v[120:123]
	v_mfma_f32_16x16x32_bf16 v[100:103], v[92:95], v[180:183], v[100:103]
	v_mfma_f32_16x16x32_bf16 v[96:99], v[116:119], v[180:183], v[96:99]
	v_mfma_f32_16x16x32_bf16 v[76:79], v[92:95], v[212:215], v[76:79]
	v_mfma_f32_16x16x32_bf16 v[72:75], v[116:119], v[212:215], v[72:75]
	v_mfma_f32_16x16x32_bf16 v[136:139], v[128:131], v[160:163], v[136:139]
	v_mfma_f32_16x16x32_bf16 v[132:135], v[152:155], v[160:163], v[132:135]
	v_mfma_f32_16x16x32_bf16 v[112:115], v[128:131], v[168:171], v[112:115]
	v_mfma_f32_16x16x32_bf16 v[108:111], v[152:155], v[168:171], v[108:111]
	v_mfma_f32_16x16x32_bf16 v[88:91], v[128:131], v[176:179], v[88:91]
	v_mfma_f32_16x16x32_bf16 v[80:83], v[152:155], v[176:179], v[80:83]
	v_mfma_f32_16x16x32_bf16 v[68:71], v[128:131], v[184:187], v[68:71]
	v_mfma_f32_16x16x32_bf16 v[64:67], v[152:155], v[184:187], v[64:67]
	v_mfma_f32_16x16x32_bf16 v[136:139], v[140:143], v[164:167], v[136:139]
	v_mfma_f32_16x16x32_bf16 v[132:135], v[156:159], v[164:167], v[132:135]
	v_mfma_f32_16x16x32_bf16 v[112:115], v[140:143], v[172:175], v[112:115]
	v_mfma_f32_16x16x32_bf16 v[108:111], v[156:159], v[172:175], v[108:111]
	v_mfma_f32_16x16x32_bf16 v[88:91], v[140:143], v[180:183], v[88:91]
	v_mfma_f32_16x16x32_bf16 v[80:83], v[156:159], v[180:183], v[80:83]
	v_mfma_f32_16x16x32_bf16 v[68:71], v[140:143], v[212:215], v[68:71]
	v_mfma_f32_16x16x32_bf16 v[64:67], v[156:159], v[212:215], v[64:67]
	s_barrier
	s_add_i32 s33, s83, s14
	v_lshl_add_u64 v[230:231], v[216:217], 0, s[42:43]
	s_mov_b32 m0, s33
	ds_read_b128 v[160:163], v223 offset:49152
	ds_read_b128 v[164:167], v223 offset:50176
	ds_read_b128 v[168:171], v223 offset:51200
	ds_read_b128 v[172:175], v223 offset:52224
	ds_read_b128 v[176:179], v223 offset:53248
	ds_read_b128 v[180:183], v223 offset:54272
	ds_read_b128 v[184:187], v223 offset:55296
	ds_read_b128 v[212:215], v223 offset:56320
	global_load_lds_dwordx4 v[230:231], off
	v_lshl_add_u64 v[230:231], v[216:217], 0, s[44:45]
	s_add_i32 m0, s33, 0x2000
	s_add_i32 s33, s84, s14
	global_load_lds_dwordx4 v[230:231], off
	v_lshl_add_u64 v[230:231], v[216:217], 0, s[46:47]
	s_mov_b32 m0, s33
	v_lshl_add_u64 v[216:217], v[216:217], 0, s[48:49]
	global_load_lds_dwordx4 v[230:231], off
	s_add_i32 m0, s33, 0x2000
	s_nop 0
	global_load_lds_dwordx4 v[216:217], off
	v_lshl_add_u64 v[216:217], v[228:229], 0, s[42:43]
	s_mov_b32 m0, s74
	s_nop 0
	global_load_lds_dwordx4 v[216:217], off
	v_lshl_add_u64 v[216:217], v[228:229], 0, s[44:45]
	s_mov_b32 m0, s75
	s_nop 0
	global_load_lds_dwordx4 v[216:217], off
	s_waitcnt vmcnt(8)
	s_waitcnt lgkmcnt(0)
	s_barrier
	s_waitcnt lgkmcnt(0)
	v_mfma_f32_16x16x32_bf16 v[60:63], v[84:87], v[160:163], v[60:63]
	v_mfma_f32_16x16x32_bf16 v[56:59], v[104:107], v[160:163], v[56:59]
	v_mfma_f32_16x16x32_bf16 v[44:47], v[84:87], v[168:171], v[44:47]
	v_mfma_f32_16x16x32_bf16 v[40:43], v[104:107], v[168:171], v[40:43]
	v_mfma_f32_16x16x32_bf16 v[28:31], v[84:87], v[176:179], v[28:31]
	v_mfma_f32_16x16x32_bf16 v[24:27], v[104:107], v[176:179], v[24:27]
	v_mfma_f32_16x16x32_bf16 v[12:15], v[84:87], v[184:187], v[12:15]
	v_mfma_f32_16x16x32_bf16 v[8:11], v[104:107], v[184:187], v[8:11]
	v_mfma_f32_16x16x32_bf16 v[60:63], v[92:95], v[164:167], v[60:63]
	v_mfma_f32_16x16x32_bf16 v[56:59], v[116:119], v[164:167], v[56:59]
	v_mfma_f32_16x16x32_bf16 v[44:47], v[92:95], v[172:175], v[44:47]
	v_mfma_f32_16x16x32_bf16 v[40:43], v[116:119], v[172:175], v[40:43]
	v_mfma_f32_16x16x32_bf16 v[28:31], v[92:95], v[180:183], v[28:31]
	v_mfma_f32_16x16x32_bf16 v[24:27], v[116:119], v[180:183], v[24:27]
	v_mfma_f32_16x16x32_bf16 v[12:15], v[92:95], v[212:215], v[12:15]
	v_mfma_f32_16x16x32_bf16 v[8:11], v[116:119], v[212:215], v[8:11]
	v_mfma_f32_16x16x32_bf16 v[52:55], v[128:131], v[160:163], v[52:55]
	v_mfma_f32_16x16x32_bf16 v[48:51], v[152:155], v[160:163], v[48:51]
	v_mfma_f32_16x16x32_bf16 v[36:39], v[128:131], v[168:171], v[36:39]
	v_mfma_f32_16x16x32_bf16 v[32:35], v[152:155], v[168:171], v[32:35]
	v_mfma_f32_16x16x32_bf16 v[20:23], v[128:131], v[176:179], v[20:23]
	v_mfma_f32_16x16x32_bf16 v[16:19], v[152:155], v[176:179], v[16:19]
	v_mfma_f32_16x16x32_bf16 v[4:7], v[128:131], v[184:187], v[4:7]
	v_mfma_f32_16x16x32_bf16 v[0:3], v[152:155], v[184:187], v[0:3]
	v_mfma_f32_16x16x32_bf16 v[52:55], v[140:143], v[164:167], v[52:55]
	v_mfma_f32_16x16x32_bf16 v[48:51], v[156:159], v[164:167], v[48:51]
	v_mfma_f32_16x16x32_bf16 v[36:39], v[140:143], v[172:175], v[36:39]
	v_mfma_f32_16x16x32_bf16 v[32:35], v[156:159], v[172:175], v[32:35]
	v_mfma_f32_16x16x32_bf16 v[20:23], v[140:143], v[180:183], v[20:23]
	v_mfma_f32_16x16x32_bf16 v[16:19], v[156:159], v[180:183], v[16:19]
	v_mfma_f32_16x16x32_bf16 v[4:7], v[140:143], v[212:215], v[4:7]
	v_mfma_f32_16x16x32_bf16 v[0:3], v[156:159], v[212:215], v[0:3]
	s_barrier
	s_add_i32 s66, s66, 2
	s_add_u32 s6, s6, 0x10000
	s_addc_u32 s7, s7, 0
	s_add_u32 s64, s64, 0x10000
	s_addc_u32 s65, s65, 0
	s_cmp_gt_u32 s66, 41

; #define PG8_STAGE(bufoff, gbase, voff) do { _Pragma("unroll") for (int _i = 0; _i < 2; ++_i) \
;         __builtin_amdgcn_global_load_lds((const unsigned*)((const char*)(gbase) + (voff)[_i]), (PG8_LAS unsigned*)(lds + (bufoff) + ldsw + _i * 8192), 16, 0, 0); } while (0)
; #define PG8_LDA(dst, b, h) do { _Pragma("unroll") for (int m = 0; m < 4; ++m) _Pragma("unroll") for (int k = 0; k < 2; ++k) dst[m][k] = *(const PG8_LAS bf16x8*)(lds + PG8_SA(b, h) + aoff + m * 2048 + k * 1024); } while (0)
; #define PG8_LDB(dst, b, h) do { _Pragma("unroll") for (int n = 0; n < 2; ++n) _Pragma("unroll") for (int k = 0; k < 2; ++k) dst[n][k] = *(const PG8_LAS bf16x8*)(lds + PG8_SB(b, h) + boff + n * 2048 + k * 1024); } while (0)
; #define PG8_SCHED __builtin_amdgcn_sched_barrier(0)
;     __host__ __device__ bool next(int i, Unit& u) const {
;         const long L = (long)i * G + c; if (L >= nwg) return false;
;         int wgid = (int)L; { const int q = nwg / NXCD, r = nwg % NXCD, xcd = wgid % NXCD, off = wgid / NXCD; wgid = (xcd < r ? xcd * (q + 1) : r * (q + 1) + (xcd - r) * q) + off; }
;         const int nig = wgm * nN, gid = wgid / nig, fm = gid * wgm, gsz = (nM - fm) < wgm ? (nM - fm) : wgm;
;         u.pm = fm + ((wgid % nig) % gsz); u.pn = (wgid % nig) / gsz; return true;
; template <class Epi, class Sched, bool ALIGN_EPI = false, bool SP2 = false>
; __device__ __forceinline__ void gemm_phase(PG8_LAS unsigned char* lds, const Gemm g, const Sched& S, const Epi& E) {
;     ...
;         const bool has_next = S.next(ui + 1, nxt);
;         const char* nA = has_next ? (const char*)g.A + (size_t)nxt.pm * tstepA : cA; const char* nB = has_next ? (const char*)g.Bt + (size_t)nxt.pn * tstepB : cB;
;         for (int t = 0; t < nt; t += 2) {
;             const bool last = (t == nt - 2);
;             const char* a1 = cA + (size_t)(t + 1) * kstepA;
;             const char* a2 = last ? nA : cA + (size_t)(t + 2) * kstepA; const char* b2 = last ? nB : cB + (size_t)(t + 2) * kstep;
;             const char* a3 = a2 + kstepA; const char* b3 = b2 + kstep;
;             if (last && has_next) S.a_ready(nxt);
;             if constexpr (SP2) {
;             PG8_LDB(B0, 0, 0); PG8_LDB(B1, 0, 1); PG8_SCHED; PG8_LDA(At, 0, 0); PG8_STAGE(PG8_SA(1, 1), a1 + hstepA, voffA);
.LBB0_993:
	ds_read_b128 v[128:131], v220
	ds_read_b128 v[132:135], v220 offset:1024
	ds_read_b128 v[136:139], v220 offset:2048
	ds_read_b128 v[140:143], v220 offset:3072
	ds_read_b128 v[144:147], v221
	ds_read_b128 v[148:151], v221 offset:1024
	ds_read_b128 v[152:155], v221 offset:2048
	ds_read_b128 v[156:159], v221 offset:3072
	ds_read_b128 v[160:163], v222
	ds_read_b128 v[164:167], v222 offset:1024
	ds_read_b128 v[168:171], v222 offset:2048
	ds_read_b128 v[172:175], v222 offset:3072
	ds_read_b128 v[176:179], v222 offset:4096
	ds_read_b128 v[180:183], v222 offset:5120
	ds_read_b128 v[230:233], v222 offset:6144
	ds_read_b128 v[234:237], v222 offset:7168
	s_add_i32 s58, s58, 1
	s_lshl_b64 s[0:1], s[58:59], 8
	s_add_u32 s12, s0, s16
	s_addc_u32 s13, s1, s85
	v_cmp_gt_i64_e32 vcc, s[12:13], v[196:197]
	v_cmp_lt_i64_e64 s[0:1], s[12:13], v[194:195]
	s_cbranch_vccnz .LBB0_999
	s_ashr_i32 s13, s12, 31
	s_lshr_b32 s13, s13, 29
	s_add_i32 s66, s12, s13
	s_and_b32 s13, s66, -8
	s_sub_i32 s67, s12, s13
	s_cmp_gt_i32 s67, -1
	s_mov_b64 s[12:13], -1
	s_cbranch_scc0 .LBB0_996
	s_lshl_b32 s69, s67, 6
	s_mov_b64 s[12:13], 0

; #define PG8_STAGE(bufoff, gbase, voff) do { _Pragma("unroll") for (int _i = 0; _i < 2; ++_i) \
;         __builtin_amdgcn_global_load_lds((const unsigned*)((const char*)(gbase) + (voff)[_i]), (PG8_LAS unsigned*)(lds + (bufoff) + ldsw + _i * 8192), 16, 0, 0); } while (0)
; #define PG8_LDA(dst, b, h) do { _Pragma("unroll") for (int m = 0; m < 4; ++m) _Pragma("unroll") for (int k = 0; k < 2; ++k) dst[m][k] = *(const PG8_LAS bf16x8*)(lds + PG8_SA(b, h) + aoff + m * 2048 + k * 1024); } while (0)
; #define PG8_LDB(dst, b, h) do { _Pragma("unroll") for (int n = 0; n < 2; ++n) _Pragma("unroll") for (int k = 0; k < 2; ++k) dst[n][k] = *(const PG8_LAS bf16x8*)(lds + PG8_SB(b, h) + boff + n * 2048 + k * 1024); } while (0)
; #define PG8_MMA(ai, bj, At, Bt) do { __builtin_amdgcn_s_setprio(1); _Pragma("unroll") for (int m = 0; m < 4; ++m) _Pragma("unroll") for (int n = 0; n < 2; ++n) _Pragma("unroll") for (int k = 0; k < 2; ++k) \
;         acc[ai][bj][m][n] = __builtin_amdgcn_mfma_f32_16x16x32_bf16(Bt[n][k], At[m][k], acc[ai][bj][m][n], 0, 0, 0); __builtin_amdgcn_s_setprio(0); } while (0)
; #define PG8_WAIT_V(n) asm volatile("s_waitcnt vmcnt(" #n ")" ::: "memory")
; #define PG8_WAIT_L(n) asm volatile("s_waitcnt lgkmcnt(" #n ")" ::: "memory")
; template <class Epi, class Sched, bool ALIGN_EPI = false, bool SP2 = false>
; __device__ __forceinline__ void gemm_phase(PG8_LAS unsigned char* lds, const Gemm g, const Sched& S, const Epi& E) {
;     ...
;             const bool last = (t == nt - 2);
;             const char* a1 = cA + (size_t)(t + 1) * kstepA;
;             const char* a2 = last ? nA : cA + (size_t)(t + 2) * kstepA; const char* b2 = last ? nB : cB + (size_t)(t + 2) * kstep;
;             const char* a3 = a2 + kstepA; const char* b3 = b2 + kstep;
;             if (last && has_next) S.a_ready(nxt);
;             if constexpr (SP2) {
;             PG8_LDB(B0, 0, 0); PG8_LDB(B1, 0, 1); PG8_SCHED; PG8_LDA(At, 0, 0); PG8_STAGE(PG8_SA(1, 1), a1 + hstepA, voffA);
;             PG8_WAIT_V(8); PG8_WAIT_L(0); PG8_BAR; PG8_MMA(0, 0, At, B0); PG8_MMA(0, 1, At, B1); PG8_BAR; PG8_SCHED;
;             PG8_LDA(At, 0, 1); PG8_STAGE(PG8_SB(0, 0), b2, voffB); PG8_STAGE(PG8_SB(0, 1), b2 + hstepB, voffB); PG8_STAGE(PG8_SA(0, 0), a2, voffA);
;             PG8_WAIT_V(8); PG8_WAIT_L(0); PG8_BAR; PG8_MMA(1, 0, At, B0); PG8_MMA(1, 1, At, B1); PG8_BAR; PG8_SCHED;
.LBB0_1003:
	s_add_u32 s70, s70, 0x10000
	s_addc_u32 s71, s71, 0
	s_add_u32 s69, s72, 0x10000
	s_addc_u32 s72, s73, 0
	s_mov_b32 s73, -2
	s_cmp_eq_u32 s73, 40
	s_cselect_b32 s75, s1, s71
	s_cselect_b32 s74, s0, s70
	s_cselect_b32 s77, s67, s72
	s_cselect_b32 s76, s66, s69
	v_lshl_add_u64 v[238:239], s[70:71], 0, v[190:191]
	v_lshl_add_u64 v[240:241], v[238:239], 0, s[62:63]
	s_add_i32 m0, s15, 0xc000
	global_load_lds_dwordx4 v[240:241], off
	v_lshl_add_u64 v[238:239], v[238:239], 0, s[64:65]
	s_add_i32 m0, s15, 0xe000
	s_nop 0
	global_load_lds_dwordx4 v[238:239], off
	s_waitcnt vmcnt(8)
	s_waitcnt lgkmcnt(0)
	s_barrier
	s_waitcnt lgkmcnt(0)
	v_mfma_f32_16x16x32_bf16 v[124:127], v[128:131], v[160:163], 0
	v_mfma_f32_16x16x32_bf16 v[120:123], v[136:139], v[160:163], 0
	v_mfma_f32_16x16x32_bf16 v[108:111], v[128:131], v[168:171], 0
	v_mfma_f32_16x16x32_bf16 v[104:107], v[136:139], v[168:171], 0
	v_mfma_f32_16x16x32_bf16 v[92:95], v[128:131], v[176:179], 0
	v_mfma_f32_16x16x32_bf16 v[88:91], v[136:139], v[176:179], 0
	v_mfma_f32_16x16x32_bf16 v[76:79], v[128:131], v[230:233], 0
	v_mfma_f32_16x16x32_bf16 v[72:75], v[136:139], v[230:233], 0
	v_mfma_f32_16x16x32_bf16 v[124:127], v[132:135], v[164:167], v[124:127]
	v_mfma_f32_16x16x32_bf16 v[120:123], v[140:143], v[164:167], v[120:123]
	v_mfma_f32_16x16x32_bf16 v[108:111], v[132:135], v[172:175], v[108:111]
	v_mfma_f32_16x16x32_bf16 v[104:107], v[140:143], v[172:175], v[104:107]
	v_mfma_f32_16x16x32_bf16 v[92:95], v[132:135], v[180:183], v[92:95]
	v_mfma_f32_16x16x32_bf16 v[88:91], v[140:143], v[180:183], v[88:91]
	v_mfma_f32_16x16x32_bf16 v[76:79], v[132:135], v[234:237], v[76:79]
	v_mfma_f32_16x16x32_bf16 v[72:75], v[140:143], v[234:237], v[72:75]
	v_mfma_f32_16x16x32_bf16 v[116:119], v[144:147], v[160:163], 0
	v_mfma_f32_16x16x32_bf16 v[112:115], v[152:155], v[160:163], 0
	v_mfma_f32_16x16x32_bf16 v[100:103], v[144:147], v[168:171], 0
	v_mfma_f32_16x16x32_bf16 v[96:99], v[152:155], v[168:171], 0
	v_mfma_f32_16x16x32_bf16 v[84:87], v[144:147], v[176:179], 0
	v_mfma_f32_16x16x32_bf16 v[80:83], v[152:155], v[176:179], 0
	v_mfma_f32_16x16x32_bf16 v[68:71], v[144:147], v[230:233], 0
	v_mfma_f32_16x16x32_bf16 v[64:67], v[152:155], v[230:233], 0
	v_mfma_f32_16x16x32_bf16 v[116:119], v[148:151], v[164:167], v[116:119]
	v_mfma_f32_16x16x32_bf16 v[112:115], v[156:159], v[164:167], v[112:115]
	v_mfma_f32_16x16x32_bf16 v[100:103], v[148:151], v[172:175], v[100:103]
	v_mfma_f32_16x16x32_bf16 v[96:99], v[156:159], v[172:175], v[96:99]
	v_mfma_f32_16x16x32_bf16 v[84:87], v[148:151], v[180:183], v[84:87]
	v_mfma_f32_16x16x32_bf16 v[80:83], v[156:159], v[180:183], v[80:83]
	v_mfma_f32_16x16x32_bf16 v[68:71], v[148:151], v[234:237], v[68:71]
	v_mfma_f32_16x16x32_bf16 v[64:67], v[156:159], v[234:237], v[64:67]
	s_barrier
	s_add_i32 s33, s86, s14
	v_lshl_add_u64 v[238:239], s[76:77], 0, v[190:191]
	s_mov_b32 m0, s33
	ds_read_b128 v[160:163], v222 offset:16384
	ds_read_b128 v[164:167], v222 offset:17408
	ds_read_b128 v[168:171], v222 offset:18432
	ds_read_b128 v[172:175], v222 offset:19456
	ds_read_b128 v[176:179], v222 offset:20480
	ds_read_b128 v[180:183], v222 offset:21504
	ds_read_b128 v[230:233], v222 offset:22528
	ds_read_b128 v[234:237], v222 offset:23552
	global_load_lds_dwordx4 v[238:239], off
	v_lshl_add_u64 v[240:241], v[238:239], 0, s[40:41]
	s_add_i32 m0, s33, 0x2000
	s_add_i32 s33, s87, s14
	global_load_lds_dwordx4 v[240:241], off
	v_lshl_add_u64 v[240:241], v[238:239], 0, s[42:43]
	s_mov_b32 m0, s33
	s_nop 0
	global_load_lds_dwordx4 v[240:241], off
	v_lshl_add_u64 v[240:241], v[238:239], 0, s[44:45]
	s_add_i32 m0, s33, 0x2000
	s_nop 0
	global_load_lds_dwordx4 v[240:241], off
	v_lshl_add_u64 v[240:241], s[74:75], 0, v[190:191]
	s_mov_b32 m0, s15
	v_lshl_add_u64 v[242:243], v[240:241], 0, s[40:41]
	global_load_lds_dwordx4 v[240:241], off
	s_mov_b32 m0, s17
	s_nop 0
	global_load_lds_dwordx4 v[242:243], off
	s_waitcnt vmcnt(8)
	s_waitcnt lgkmcnt(0)
	s_barrier
	s_waitcnt lgkmcnt(0)
	v_mfma_f32_16x16x32_bf16 v[60:63], v[128:131], v[160:163], 0
	v_mfma_f32_16x16x32_bf16 v[56:59], v[136:139], v[160:163], 0
	v_mfma_f32_16x16x32_bf16 v[44:47], v[128:131], v[168:171], 0
	v_mfma_f32_16x16x32_bf16 v[40:43], v[136:139], v[168:171], 0
	v_mfma_f32_16x16x32_bf16 v[28:31], v[128:131], v[176:179], 0
	v_mfma_f32_16x16x32_bf16 v[24:27], v[136:139], v[176:179], 0
	v_mfma_f32_16x16x32_bf16 v[12:15], v[128:131], v[230:233], 0
	v_mfma_f32_16x16x32_bf16 v[8:11], v[136:139], v[230:233], 0
	v_mfma_f32_16x16x32_bf16 v[60:63], v[132:135], v[164:167], v[60:63]
	v_mfma_f32_16x16x32_bf16 v[56:59], v[140:143], v[164:167], v[56:59]
	v_mfma_f32_16x16x32_bf16 v[44:47], v[132:135], v[172:175], v[44:47]
	v_mfma_f32_16x16x32_bf16 v[40:43], v[140:143], v[172:175], v[40:43]
	v_mfma_f32_16x16x32_bf16 v[28:31], v[132:135], v[180:183], v[28:31]
	v_mfma_f32_16x16x32_bf16 v[24:27], v[140:143], v[180:183], v[24:27]
	v_mfma_f32_16x16x32_bf16 v[12:15], v[132:135], v[234:237], v[12:15]
	v_mfma_f32_16x16x32_bf16 v[8:11], v[140:143], v[234:237], v[8:11]
	v_mfma_f32_16x16x32_bf16 v[52:55], v[144:147], v[160:163], 0
	v_mfma_f32_16x16x32_bf16 v[48:51], v[152:155], v[160:163], 0
	v_mfma_f32_16x16x32_bf16 v[36:39], v[144:147], v[168:171], 0
	v_mfma_f32_16x16x32_bf16 v[32:35], v[152:155], v[168:171], 0
	v_mfma_f32_16x16x32_bf16 v[20:23], v[144:147], v[176:179], 0
	v_mfma_f32_16x16x32_bf16 v[16:19], v[152:155], v[176:179], 0
	v_mfma_f32_16x16x32_bf16 v[4:7], v[144:147], v[230:233], 0
	v_mfma_f32_16x16x32_bf16 v[0:3], v[152:155], v[230:233], 0
	v_mfma_f32_16x16x32_bf16 v[52:55], v[148:151], v[164:167], v[52:55]
	v_mfma_f32_16x16x32_bf16 v[48:51], v[156:159], v[164:167], v[48:51]
	v_mfma_f32_16x16x32_bf16 v[36:39], v[148:151], v[172:175], v[36:39]
	v_mfma_f32_16x16x32_bf16 v[32:35], v[156:159], v[172:175], v[32:35]
	v_mfma_f32_16x16x32_bf16 v[20:23], v[148:151], v[180:183], v[20:23]
	v_mfma_f32_16x16x32_bf16 v[16:19], v[156:159], v[180:183], v[16:19]
	v_mfma_f32_16x16x32_bf16 v[4:7], v[148:151], v[234:237], v[4:7]
	v_mfma_f32_16x16x32_bf16 v[0:3], v[156:159], v[234:237], v[0:3]
	s_barrier
; #define PG8_STAGE(bufoff, gbase, voff) do { _Pragma("unroll") for (int _i = 0; _i < 2; ++_i) \
;         __builtin_amdgcn_global_load_lds((const unsigned*)((const char*)(gbase) + (voff)[_i]), (PG8_LAS unsigned*)(lds + (bufoff) + ldsw + _i * 8192), 16, 0, 0); } while (0)
; #define PG8_LDA(dst, b, h) do { _Pragma("unroll") for (int m = 0; m < 4; ++m) _Pragma("unroll") for (int k = 0; k < 2; ++k) dst[m][k] = *(const PG8_LAS bf16x8*)(lds + PG8_SA(b, h) + aoff + m * 2048 + k * 1024); } while (0)
; #define PG8_LDB(dst, b, h) do { _Pragma("unroll") for (int n = 0; n < 2; ++n) _Pragma("unroll") for (int k = 0; k < 2; ++k) dst[n][k] = *(const PG8_LAS bf16x8*)(lds + PG8_SB(b, h) + boff + n * 2048 + k * 1024); } while (0)
; #define PG8_MMA(ai, bj, At, Bt) do { __builtin_amdgcn_s_setprio(1); _Pragma("unroll") for (int m = 0; m < 4; ++m) _Pragma("unroll") for (int n = 0; n < 2; ++n) _Pragma("unroll") for (int k = 0; k < 2; ++k) \
;         acc[ai][bj][m][n] = __builtin_amdgcn_mfma_f32_16x16x32_bf16(Bt[n][k], At[m][k], acc[ai][bj][m][n], 0, 0, 0); __builtin_amdgcn_s_setprio(0); } while (0)
; #define PG8_WAIT_V(n) asm volatile("s_waitcnt vmcnt(" #n ")" ::: "memory")
; #define PG8_WAIT_L(n) asm volatile("s_waitcnt lgkmcnt(" #n ")" ::: "memory")
; #define PG8_BAR __builtin_amdgcn_s_barrier()
; #define PG8_SCHED __builtin_amdgcn_sched_barrier(0)
; template <class Epi, class Sched, bool ALIGN_EPI = false, bool SP2 = false>
; __device__ __forceinline__ void gemm_phase(PG8_LAS unsigned char* lds, const Gemm g, const Sched& S, const Epi& E) {
;     ...
;             PG8_LDB(B0, 1, 0); PG8_LDB(B1, 1, 1); PG8_SCHED; PG8_LDA(At, 1, 0); PG8_STAGE(PG8_SA(0, 1), a2 + hstepA, voffA);
;             PG8_WAIT_V(8); PG8_WAIT_L(0); PG8_BAR; PG8_MMA(0, 0, At, B0); PG8_MMA(0, 1, At, B1); PG8_BAR; PG8_SCHED;
;             PG8_LDA(At, 1, 1); PG8_STAGE(PG8_SB(1, 0), b3, voffB); PG8_STAGE(PG8_SB(1, 1), b3 + hstepB, voffB); PG8_STAGE(PG8_SA(1, 0), a3, voffA);
;             PG8_WAIT_V(8); PG8_WAIT_L(0); PG8_BAR; PG8_MMA(1, 0, At, B0); PG8_MMA(1, 1, At, B1); PG8_BAR; PG8_SCHED;
	ds_read_b128 v[128:131], v223
	ds_read_b128 v[132:135], v223 offset:1024
	ds_read_b128 v[136:139], v223 offset:2048
	ds_read_b128 v[140:143], v223 offset:3072
	ds_read_b128 v[144:147], v224
	ds_read_b128 v[148:151], v224 offset:1024
	ds_read_b128 v[152:155], v224 offset:2048
	ds_read_b128 v[156:159], v224 offset:3072
	s_mov_b32 m0, s18
	v_lshl_add_u64 v[242:243], v[240:241], 0, s[42:43]
	ds_read_b128 v[160:163], v222 offset:32768
	ds_read_b128 v[164:167], v222 offset:33792
	ds_read_b128 v[168:171], v222 offset:34816
	ds_read_b128 v[172:175], v222 offset:35840
	ds_read_b128 v[176:179], v222 offset:36864
	ds_read_b128 v[180:183], v222 offset:37888
	ds_read_b128 v[230:233], v222 offset:38912
	ds_read_b128 v[234:237], v222 offset:39936
	global_load_lds_dwordx4 v[242:243], off
	v_lshl_add_u64 v[242:243], v[240:241], 0, s[44:45]
	s_mov_b32 m0, s19
	s_nop 0
	global_load_lds_dwordx4 v[242:243], off
	s_waitcnt vmcnt(8)
	s_waitcnt lgkmcnt(0)
	s_barrier
	s_waitcnt lgkmcnt(0)
	v_mfma_f32_16x16x32_bf16 v[124:127], v[128:131], v[160:163], v[124:127]
	v_mfma_f32_16x16x32_bf16 v[120:123], v[136:139], v[160:163], v[120:123]
	v_mfma_f32_16x16x32_bf16 v[108:111], v[128:131], v[168:171], v[108:111]
	v_mfma_f32_16x16x32_bf16 v[104:107], v[136:139], v[168:171], v[104:107]
	v_mfma_f32_16x16x32_bf16 v[92:95], v[128:131], v[176:179], v[92:95]
	v_mfma_f32_16x16x32_bf16 v[88:91], v[136:139], v[176:179], v[88:91]
	v_mfma_f32_16x16x32_bf16 v[76:79], v[128:131], v[230:233], v[76:79]
	v_mfma_f32_16x16x32_bf16 v[72:75], v[136:139], v[230:233], v[72:75]
	v_mfma_f32_16x16x32_bf16 v[124:127], v[132:135], v[164:167], v[124:127]
	v_mfma_f32_16x16x32_bf16 v[120:123], v[140:143], v[164:167], v[120:123]
	v_mfma_f32_16x16x32_bf16 v[108:111], v[132:135], v[172:175], v[108:111]
	v_mfma_f32_16x16x32_bf16 v[104:107], v[140:143], v[172:175], v[104:107]
	v_mfma_f32_16x16x32_bf16 v[92:95], v[132:135], v[180:183], v[92:95]
	v_mfma_f32_16x16x32_bf16 v[88:91], v[140:143], v[180:183], v[88:91]
	v_mfma_f32_16x16x32_bf16 v[76:79], v[132:135], v[234:237], v[76:79]
	v_mfma_f32_16x16x32_bf16 v[72:75], v[140:143], v[234:237], v[72:75]
	v_mfma_f32_16x16x32_bf16 v[116:119], v[144:147], v[160:163], v[116:119]
	v_mfma_f32_16x16x32_bf16 v[112:115], v[152:155], v[160:163], v[112:115]
	v_mfma_f32_16x16x32_bf16 v[100:103], v[144:147], v[168:171], v[100:103]
	v_mfma_f32_16x16x32_bf16 v[96:99], v[152:155], v[168:171], v[96:99]
	v_mfma_f32_16x16x32_bf16 v[84:87], v[144:147], v[176:179], v[84:87]
	v_mfma_f32_16x16x32_bf16 v[80:83], v[152:155], v[176:179], v[80:83]
	v_mfma_f32_16x16x32_bf16 v[68:71], v[144:147], v[230:233], v[68:71]
	v_mfma_f32_16x16x32_bf16 v[64:67], v[152:155], v[230:233], v[64:67]
	v_mfma_f32_16x16x32_bf16 v[116:119], v[148:151], v[164:167], v[116:119]
	v_mfma_f32_16x16x32_bf16 v[112:115], v[156:159], v[164:167], v[112:115]
	v_mfma_f32_16x16x32_bf16 v[100:103], v[148:151], v[172:175], v[100:103]
	v_mfma_f32_16x16x32_bf16 v[96:99], v[156:159], v[172:175], v[96:99]
	v_mfma_f32_16x16x32_bf16 v[84:87], v[148:151], v[180:183], v[84:87]
	v_mfma_f32_16x16x32_bf16 v[80:83], v[156:159], v[180:183], v[80:83]
	v_mfma_f32_16x16x32_bf16 v[68:71], v[148:151], v[234:237], v[68:71]
	v_mfma_f32_16x16x32_bf16 v[64:67], v[156:159], v[234:237], v[64:67]
	s_barrier
	s_add_i32 s33, s88, s14
	v_lshl_add_u64 v[242:243], v[238:239], 0, s[46:47]
	s_mov_b32 m0, s33
	ds_read_b128 v[160:163], v222 offset:49152
	ds_read_b128 v[164:167], v222 offset:50176
	ds_read_b128 v[168:171], v222 offset:51200
	ds_read_b128 v[172:175], v222 offset:52224
	ds_read_b128 v[176:179], v222 offset:53248
	ds_read_b128 v[180:183], v222 offset:54272
	ds_read_b128 v[230:233], v222 offset:55296
	ds_read_b128 v[234:237], v222 offset:56320
	global_load_lds_dwordx4 v[242:243], off
	v_lshl_add_u64 v[242:243], v[238:239], 0, s[48:49]
	s_add_i32 m0, s33, 0x2000
	s_add_i32 s33, s89, s14
	global_load_lds_dwordx4 v[242:243], off
	v_lshl_add_u64 v[242:243], v[238:239], 0, s[52:53]
	s_mov_b32 m0, s33
	v_lshl_add_u64 v[238:239], v[238:239], 0, s[54:55]
	global_load_lds_dwordx4 v[242:243], off
	s_add_i32 m0, s33, 0x2000
	s_nop 0
	global_load_lds_dwordx4 v[238:239], off
	v_lshl_add_u64 v[238:239], v[240:241], 0, s[46:47]
	s_mov_b32 m0, s80
	s_nop 0
	global_load_lds_dwordx4 v[238:239], off
	v_lshl_add_u64 v[238:239], v[240:241], 0, s[48:49]
	s_mov_b32 m0, s81
	s_nop 0
	global_load_lds_dwordx4 v[238:239], off
	s_waitcnt vmcnt(8)
	s_waitcnt lgkmcnt(0)
	s_barrier
	s_waitcnt lgkmcnt(0)
	v_mfma_f32_16x16x32_bf16 v[60:63], v[128:131], v[160:163], v[60:63]
	v_mfma_f32_16x16x32_bf16 v[56:59], v[136:139], v[160:163], v[56:59]
	v_mfma_f32_16x16x32_bf16 v[44:47], v[128:131], v[168:171], v[44:47]
	v_mfma_f32_16x16x32_bf16 v[40:43], v[136:139], v[168:171], v[40:43]
	v_mfma_f32_16x16x32_bf16 v[28:31], v[128:131], v[176:179], v[28:31]
	v_mfma_f32_16x16x32_bf16 v[24:27], v[136:139], v[176:179], v[24:27]
	v_mfma_f32_16x16x32_bf16 v[12:15], v[128:131], v[230:233], v[12:15]
	v_mfma_f32_16x16x32_bf16 v[8:11], v[136:139], v[230:233], v[8:11]
	v_mfma_f32_16x16x32_bf16 v[60:63], v[132:135], v[164:167], v[60:63]
	v_mfma_f32_16x16x32_bf16 v[56:59], v[140:143], v[164:167], v[56:59]
	v_mfma_f32_16x16x32_bf16 v[44:47], v[132:135], v[172:175], v[44:47]
	v_mfma_f32_16x16x32_bf16 v[40:43], v[140:143], v[172:175], v[40:43]
	v_mfma_f32_16x16x32_bf16 v[28:31], v[132:135], v[180:183], v[28:31]
	v_mfma_f32_16x16x32_bf16 v[24:27], v[140:143], v[180:183], v[24:27]
	v_mfma_f32_16x16x32_bf16 v[12:15], v[132:135], v[234:237], v[12:15]
	v_mfma_f32_16x16x32_bf16 v[8:11], v[140:143], v[234:237], v[8:11]
	v_mfma_f32_16x16x32_bf16 v[52:55], v[144:147], v[160:163], v[52:55]
	v_mfma_f32_16x16x32_bf16 v[48:51], v[152:155], v[160:163], v[48:51]
	v_mfma_f32_16x16x32_bf16 v[36:39], v[144:147], v[168:171], v[36:39]
	v_mfma_f32_16x16x32_bf16 v[32:35], v[152:155], v[168:171], v[32:35]
	v_mfma_f32_16x16x32_bf16 v[20:23], v[144:147], v[176:179], v[20:23]
	v_mfma_f32_16x16x32_bf16 v[16:19], v[152:155], v[176:179], v[16:19]
	v_mfma_f32_16x16x32_bf16 v[4:7], v[144:147], v[230:233], v[4:7]
	v_mfma_f32_16x16x32_bf16 v[0:3], v[152:155], v[230:233], v[0:3]
	v_mfma_f32_16x16x32_bf16 v[52:55], v[148:151], v[164:167], v[52:55]
	v_mfma_f32_16x16x32_bf16 v[48:51], v[156:159], v[164:167], v[48:51]
	v_mfma_f32_16x16x32_bf16 v[36:39], v[148:151], v[172:175], v[36:39]
	v_mfma_f32_16x16x32_bf16 v[32:35], v[156:159], v[172:175], v[32:35]
	v_mfma_f32_16x16x32_bf16 v[20:23], v[148:151], v[180:183], v[20:23]
	v_mfma_f32_16x16x32_bf16 v[16:19], v[156:159], v[180:183], v[16:19]
	v_mfma_f32_16x16x32_bf16 v[4:7], v[148:151], v[234:237], v[4:7]
	v_mfma_f32_16x16x32_bf16 v[0:3], v[156:159], v[234:237], v[0:3]
	s_barrier
	s_add_i32 s73, s73, 2
	s_add_u32 s70, s70, 0x10000
	s_addc_u32 s71, s71, 0
	s_add_u32 s69, s69, 0x10000
	s_addc_u32 s72, s72, 0
	s_cmp_gt_u32 s73, 41
